# each MFMA block signals its trailing s_barrier 8 MFMAs early (s_setprio 2 on the tail) in all 8 K-loops
# baseline (speedup 1.0000x reference)
; #define PG8_STAGE(bufoff, gbase, voff) do { _Pragma("unroll") for (int _i = 0; _i < 2; ++_i) \
;         __builtin_amdgcn_global_load_lds((const unsigned*)((const char*)(gbase) + (voff)[_i]), (PG8_LAS unsigned*)(lds + (bufoff) + ldsw + _i * 8192), 16, 0, 0); } while (0)
; #define PG8_LDA(dst, b, h) do { _Pragma("unroll") for (int m = 0; m < 4; ++m) _Pragma("unroll") for (int k = 0; k < 2; ++k) dst[m][k] = *(const PG8_LAS bf16x8*)(lds + PG8_SA(b, h) + aoff + m * 2048 + k * 1024); } while (0)
; #define PG8_LDB(dst, b, h) do { _Pragma("unroll") for (int n = 0; n < 2; ++n) _Pragma("unroll") for (int k = 0; k < 2; ++k) dst[n][k] = *(const PG8_LAS bf16x8*)(lds + PG8_SB(b, h) + boff + n * 2048 + k * 1024); } while (0)
; #define PG8_MMA(ai, bj, At, Bt) do { __builtin_amdgcn_s_setprio(1); _Pragma("unroll") for (int m = 0; m < 4; ++m) _Pragma("unroll") for (int n = 0; n < 2; ++n) _Pragma("unroll") for (int k = 0; k < 2; ++k) \
;         acc[ai][bj][m][n] = __builtin_amdgcn_mfma_f32_16x16x32_bf16(Bt[n][k], At[m][k], acc[ai][bj][m][n], 0, 0, 0); __builtin_amdgcn_s_setprio(0); } while (0)
; #define PG8_WAIT_V(n) asm volatile("s_waitcnt vmcnt(" #n ")" ::: "memory")
; #define PG8_BAR __builtin_amdgcn_s_barrier()
; template <class Epi, class Sched, bool ALIGN_EPI = false, bool SP2 = false>
; __device__ __forceinline__ void gemm_phase(PG8_LAS unsigned char* lds, const Gemm g, const Sched& S, const Epi& E, int wv) {
;     ...
;         for (int t = 0; t < nt; t += 2) {
;             const bool last = (t == nt - 2);
;             const char* a1 = cA + (size_t)(t + 1) * kstep;
;             const char* a2 = last ? nA : cA + (size_t)(t + 2) * kstep; const char* b2 = last ? nB : cB + (size_t)(t + 2) * kstep;
;             const char* a3 = a2 + kstep; const char* b3 = b2 + kstep;
;             if (last && has_next) S.a_ready(nxt);
;             if constexpr (SP2) {
;             PG8_LDB(B0, 0, 0); PG8_LDB(B1, 0, 1); PG8_SCHED; PG8_LDA(At, 0, 0); PG8_STAGE(PG8_SA(1, 1), a1 + hstep, voffA);
;             PG8_WAIT_V(8); PG8_WAIT_L(0); PG8_BAR; PG8_MMA(0, 0, At, B0); PG8_MMA(0, 1, At, B1); PG8_BAR; PG8_SCHED;
;             PG8_LDA(At, 0, 1); PG8_STAGE(PG8_SB(0, 0), b2, voffB); PG8_STAGE(PG8_SB(0, 1), b2 + hstep, voffB); PG8_STAGE(PG8_SA(0, 0), a2, voffA);
;             PG8_WAIT_V(8); PG8_WAIT_L(0); PG8_BAR; PG8_MMA(1, 0, At, B0); PG8_MMA(1, 1, At, B1); PG8_BAR; PG8_SCHED;
.LBB0_773:
	s_add_u32 s21, s42, 0xfffc0080
	s_addc_u32 s26, s43, -1
	s_add_i32 s28, 0, 0x10000
	s_cmp_eq_u32 s67, 12
	s_cselect_b32 s49, s13, s26
	s_cselect_b32 s48, s63, s21
	v_add_u32_e32 v138, s28, v141
	s_cselect_b32 s45, s15, s66
	s_cselect_b32 s44, s64, s65
	s_add_i32 s21, 0, 0x14000
	ds_read_b128 v[144:147], v138
	ds_read_b128 v[148:151], v138 offset:1024
	ds_read_b128 v[152:155], v138 offset:2048
	ds_read_b128 v[156:159], v138 offset:3072
	v_add_u32_e32 v138, s21, v141
	ds_read_b128 v[162:165], v138
	ds_read_b128 v[166:169], v138 offset:1024
	ds_read_b128 v[170:173], v138 offset:2048
	ds_read_b128 v[174:177], v138 offset:3072
	v_lshl_add_u64 v[138:139], s[42:43], 0, v[134:135]
	s_add_i32 m0, s51, 0xc000
	ds_read_b128 v[178:181], v143
	ds_read_b128 v[204:207], v143 offset:1024
	ds_read_b128 v[208:211], v143 offset:2048
	ds_read_b128 v[212:215], v143 offset:3072
	ds_read_b128 v[216:219], v143 offset:4096
	ds_read_b128 v[220:223], v143 offset:5120
	ds_read_b128 v[224:227], v143 offset:6144
	ds_read_b128 v[228:231], v143 offset:7168
	global_load_lds_dwordx4 v[138:139], off
	v_lshl_add_u64 v[138:139], s[42:43], 0, v[136:137]
	s_add_i32 m0, s51, 0xe000
	s_nop 0
	global_load_lds_dwordx4 v[138:139], off
	s_waitcnt vmcnt(8)
	s_waitcnt lgkmcnt(0)
	s_barrier
	s_setprio 1
	s_waitcnt lgkmcnt(0)
	v_mfma_f32_16x16x32_bf16 v[124:127], v[144:147], v[178:181], v[124:127]
	v_mfma_f32_16x16x32_bf16 v[120:123], v[152:155], v[178:181], v[120:123]
	v_mfma_f32_16x16x32_bf16 v[108:111], v[144:147], v[208:211], v[108:111]
	v_mfma_f32_16x16x32_bf16 v[104:107], v[152:155], v[208:211], v[104:107]
	v_mfma_f32_16x16x32_bf16 v[92:95], v[144:147], v[216:219], v[92:95]
	v_mfma_f32_16x16x32_bf16 v[88:91], v[152:155], v[216:219], v[88:91]
	v_mfma_f32_16x16x32_bf16 v[76:79], v[144:147], v[224:227], v[76:79]
	v_mfma_f32_16x16x32_bf16 v[72:75], v[152:155], v[224:227], v[72:75]
	v_mfma_f32_16x16x32_bf16 v[124:127], v[148:151], v[204:207], v[124:127]
	v_mfma_f32_16x16x32_bf16 v[120:123], v[156:159], v[204:207], v[120:123]
	v_mfma_f32_16x16x32_bf16 v[108:111], v[148:151], v[212:215], v[108:111]
	v_mfma_f32_16x16x32_bf16 v[104:107], v[156:159], v[212:215], v[104:107]
	v_mfma_f32_16x16x32_bf16 v[92:95], v[148:151], v[220:223], v[92:95]
	v_mfma_f32_16x16x32_bf16 v[88:91], v[156:159], v[220:223], v[88:91]
	v_mfma_f32_16x16x32_bf16 v[76:79], v[148:151], v[228:231], v[76:79]
	v_mfma_f32_16x16x32_bf16 v[72:75], v[156:159], v[228:231], v[72:75]
	s_setprio 0
	s_setprio 1
	v_mfma_f32_16x16x32_bf16 v[116:119], v[162:165], v[178:181], v[116:119]
	v_mfma_f32_16x16x32_bf16 v[112:115], v[170:173], v[178:181], v[112:115]
	v_mfma_f32_16x16x32_bf16 v[100:103], v[162:165], v[208:211], v[100:103]
	v_mfma_f32_16x16x32_bf16 v[96:99], v[170:173], v[208:211], v[96:99]
	v_mfma_f32_16x16x32_bf16 v[84:87], v[162:165], v[216:219], v[84:87]
	v_mfma_f32_16x16x32_bf16 v[80:83], v[170:173], v[216:219], v[80:83]
	v_mfma_f32_16x16x32_bf16 v[68:71], v[162:165], v[224:227], v[68:71]
	v_mfma_f32_16x16x32_bf16 v[64:67], v[170:173], v[224:227], v[64:67]
	s_setprio 2
	s_barrier
	v_mfma_f32_16x16x32_bf16 v[116:119], v[166:169], v[204:207], v[116:119]
	v_mfma_f32_16x16x32_bf16 v[112:115], v[174:177], v[204:207], v[112:115]
	v_mfma_f32_16x16x32_bf16 v[100:103], v[166:169], v[212:215], v[100:103]
	v_mfma_f32_16x16x32_bf16 v[96:99], v[174:177], v[212:215], v[96:99]
	v_mfma_f32_16x16x32_bf16 v[84:87], v[166:169], v[220:223], v[84:87]
	v_mfma_f32_16x16x32_bf16 v[80:83], v[174:177], v[220:223], v[80:83]
	v_mfma_f32_16x16x32_bf16 v[68:71], v[166:169], v[228:231], v[68:71]
	v_mfma_f32_16x16x32_bf16 v[64:67], v[174:177], v[228:231], v[64:67]
	s_setprio 0
	s_add_i32 s26, s28, s50
	v_lshl_add_u64 v[138:139], s[44:45], 0, v[160:161]
	s_mov_b32 m0, s26
	ds_read_b128 v[178:181], v143 offset:16384
	ds_read_b128 v[204:207], v143 offset:17408
	ds_read_b128 v[208:211], v143 offset:18432
	ds_read_b128 v[212:215], v143 offset:19456
	ds_read_b128 v[216:219], v143 offset:20480
	ds_read_b128 v[220:223], v143 offset:21504
	ds_read_b128 v[224:227], v143 offset:22528
	ds_read_b128 v[228:231], v143 offset:23552
	global_load_lds_dwordx4 v[138:139], off
	s_add_i32 m0, s26, 0x2000
	s_add_u32 s76, s44, 0x40000
	v_lshl_add_u64 v[232:233], s[44:45], 0, v[128:129]
	s_addc_u32 s77, s45, 0
	s_add_i32 s21, s21, s50
	global_load_lds_dwordx4 v[232:233], off
	v_lshl_add_u64 v[234:235], s[76:77], 0, v[160:161]
	s_mov_b32 m0, s21
	v_lshl_add_u64 v[236:237], s[48:49], 0, v[130:131]
	global_load_lds_dwordx4 v[234:235], off
	v_lshl_add_u64 v[234:235], s[76:77], 0, v[128:129]
	s_add_i32 m0, s21, 0x2000
	s_nop 0
	global_load_lds_dwordx4 v[234:235], off
	v_lshl_add_u64 v[234:235], s[48:49], 0, v[132:133]
	s_mov_b32 m0, s51
	s_nop 0
	global_load_lds_dwordx4 v[234:235], off
	s_mov_b32 m0, s52
	s_nop 0
	global_load_lds_dwordx4 v[236:237], off
	s_waitcnt vmcnt(8)
	s_waitcnt lgkmcnt(0)
	s_barrier
; #define PG8_STAGE(bufoff, gbase, voff) do { _Pragma("unroll") for (int _i = 0; _i < 2; ++_i) \
;         __builtin_amdgcn_global_load_lds((const unsigned*)((const char*)(gbase) + (voff)[_i]), (PG8_LAS unsigned*)(lds + (bufoff) + ldsw + _i * 8192), 16, 0, 0); } while (0)
; #define PG8_LDA(dst, b, h) do { _Pragma("unroll") for (int m = 0; m < 4; ++m) _Pragma("unroll") for (int k = 0; k < 2; ++k) dst[m][k] = *(const PG8_LAS bf16x8*)(lds + PG8_SA(b, h) + aoff + m * 2048 + k * 1024); } while (0)
; #define PG8_LDB(dst, b, h) do { _Pragma("unroll") for (int n = 0; n < 2; ++n) _Pragma("unroll") for (int k = 0; k < 2; ++k) dst[n][k] = *(const PG8_LAS bf16x8*)(lds + PG8_SB(b, h) + boff + n * 2048 + k * 1024); } while (0)
; #define PG8_MMA(ai, bj, At, Bt) do { __builtin_amdgcn_s_setprio(1); _Pragma("unroll") for (int m = 0; m < 4; ++m) _Pragma("unroll") for (int n = 0; n < 2; ++n) _Pragma("unroll") for (int k = 0; k < 2; ++k) \
;         acc[ai][bj][m][n] = __builtin_amdgcn_mfma_f32_16x16x32_bf16(Bt[n][k], At[m][k], acc[ai][bj][m][n], 0, 0, 0); __builtin_amdgcn_s_setprio(0); } while (0)
; #define PG8_WAIT_V(n) asm volatile("s_waitcnt vmcnt(" #n ")" ::: "memory")
; #define PG8_WAIT_L(n) asm volatile("s_waitcnt lgkmcnt(" #n ")" ::: "memory")
; #define PG8_BAR __builtin_amdgcn_s_barrier()
; #define PG8_SCHED __builtin_amdgcn_sched_barrier(0)
; template <class Epi, class Sched, bool ALIGN_EPI = false, bool SP2 = false>
; __device__ __forceinline__ void gemm_phase(PG8_LAS unsigned char* lds, const Gemm g, const Sched& S, const Epi& E, int wv) {
;     ...
;             PG8_WAIT_V(8); PG8_WAIT_L(0); PG8_BAR; PG8_MMA(1, 0, At, B0); PG8_MMA(1, 1, At, B1); PG8_BAR; PG8_SCHED;
;             PG8_LDB(B0, 1, 0); PG8_LDB(B1, 1, 1); PG8_SCHED; PG8_LDA(At, 1, 0); PG8_STAGE(PG8_SA(0, 1), a2 + hstep, voffA);
;             PG8_WAIT_V(8); PG8_WAIT_L(0); PG8_BAR; PG8_MMA(0, 0, At, B0); PG8_MMA(0, 1, At, B1); PG8_BAR; PG8_SCHED;
;             PG8_LDA(At, 1, 1); PG8_STAGE(PG8_SB(1, 0), b3, voffB); PG8_STAGE(PG8_SB(1, 1), b3 + hstep, voffB); PG8_STAGE(PG8_SA(1, 0), a3, voffA);
;             PG8_WAIT_V(8); PG8_WAIT_L(0); PG8_BAR; PG8_MMA(1, 0, At, B0); PG8_MMA(1, 1, At, B1); PG8_BAR; PG8_SCHED;
	s_setprio 1
	s_waitcnt lgkmcnt(0)
	v_mfma_f32_16x16x32_bf16 v[60:63], v[144:147], v[178:181], v[60:63]
	v_mfma_f32_16x16x32_bf16 v[56:59], v[152:155], v[178:181], v[56:59]
	v_mfma_f32_16x16x32_bf16 v[44:47], v[144:147], v[208:211], v[44:47]
	v_mfma_f32_16x16x32_bf16 v[40:43], v[152:155], v[208:211], v[40:43]
	v_mfma_f32_16x16x32_bf16 v[28:31], v[144:147], v[216:219], v[28:31]
	v_mfma_f32_16x16x32_bf16 v[24:27], v[152:155], v[216:219], v[24:27]
	v_mfma_f32_16x16x32_bf16 v[12:15], v[144:147], v[224:227], v[12:15]
	v_mfma_f32_16x16x32_bf16 v[8:11], v[152:155], v[224:227], v[8:11]
	v_mfma_f32_16x16x32_bf16 v[60:63], v[148:151], v[204:207], v[60:63]
	v_mfma_f32_16x16x32_bf16 v[56:59], v[156:159], v[204:207], v[56:59]
	v_mfma_f32_16x16x32_bf16 v[44:47], v[148:151], v[212:215], v[44:47]
	v_mfma_f32_16x16x32_bf16 v[40:43], v[156:159], v[212:215], v[40:43]
	v_mfma_f32_16x16x32_bf16 v[28:31], v[148:151], v[220:223], v[28:31]
	v_mfma_f32_16x16x32_bf16 v[24:27], v[156:159], v[220:223], v[24:27]
	v_mfma_f32_16x16x32_bf16 v[12:15], v[148:151], v[228:231], v[12:15]
	v_mfma_f32_16x16x32_bf16 v[8:11], v[156:159], v[228:231], v[8:11]
	s_setprio 0
	s_setprio 1
	v_mfma_f32_16x16x32_bf16 v[52:55], v[162:165], v[178:181], v[52:55]
	v_mfma_f32_16x16x32_bf16 v[48:51], v[170:173], v[178:181], v[48:51]
	v_mfma_f32_16x16x32_bf16 v[36:39], v[162:165], v[208:211], v[36:39]
	v_mfma_f32_16x16x32_bf16 v[32:35], v[170:173], v[208:211], v[32:35]
	v_mfma_f32_16x16x32_bf16 v[20:23], v[162:165], v[216:219], v[20:23]
	v_mfma_f32_16x16x32_bf16 v[16:19], v[170:173], v[216:219], v[16:19]
	v_mfma_f32_16x16x32_bf16 v[4:7], v[162:165], v[224:227], v[4:7]
	v_mfma_f32_16x16x32_bf16 v[0:3], v[170:173], v[224:227], v[0:3]
	s_setprio 2
	s_barrier
	v_mfma_f32_16x16x32_bf16 v[52:55], v[166:169], v[204:207], v[52:55]
	v_mfma_f32_16x16x32_bf16 v[48:51], v[174:177], v[204:207], v[48:51]
	v_mfma_f32_16x16x32_bf16 v[36:39], v[166:169], v[212:215], v[36:39]
	v_mfma_f32_16x16x32_bf16 v[32:35], v[174:177], v[212:215], v[32:35]
	v_mfma_f32_16x16x32_bf16 v[20:23], v[166:169], v[220:223], v[20:23]
	v_mfma_f32_16x16x32_bf16 v[16:19], v[174:177], v[220:223], v[16:19]
	v_mfma_f32_16x16x32_bf16 v[4:7], v[166:169], v[228:231], v[4:7]
	v_mfma_f32_16x16x32_bf16 v[0:3], v[174:177], v[228:231], v[0:3]
	s_setprio 0
	s_add_i32 s21, 0, 0x18000
	v_add_u32_e32 v140, s21, v141
	s_add_i32 s26, 0, 0x1c000
	ds_read_b128 v[144:147], v140
	ds_read_b128 v[148:151], v140 offset:1024
	ds_read_b128 v[152:155], v140 offset:2048
	ds_read_b128 v[156:159], v140 offset:3072
	v_add_u32_e32 v140, s26, v141
	ds_read_b128 v[162:165], v140
	ds_read_b128 v[166:169], v140 offset:1024
	ds_read_b128 v[170:173], v140 offset:2048
	ds_read_b128 v[174:177], v140 offset:3072
	s_add_u32 s48, s48, 0x40000
	s_addc_u32 s49, s49, 0
	s_mov_b32 m0, s53
	v_lshl_add_u64 v[238:239], s[48:49], 0, v[132:133]
	ds_read_b128 v[178:181], v143 offset:32768
	ds_read_b128 v[204:207], v143 offset:33792
	ds_read_b128 v[208:211], v143 offset:34816
	ds_read_b128 v[212:215], v143 offset:35840
	ds_read_b128 v[216:219], v143 offset:36864
	ds_read_b128 v[220:223], v143 offset:37888
	ds_read_b128 v[224:227], v143 offset:38912
	ds_read_b128 v[228:231], v143 offset:39936
	global_load_lds_dwordx4 v[238:239], off
	v_lshl_add_u64 v[238:239], s[48:49], 0, v[130:131]
	s_mov_b32 m0, s54
	s_nop 0
	global_load_lds_dwordx4 v[238:239], off
	s_waitcnt vmcnt(8)
	s_waitcnt lgkmcnt(0)
	s_barrier
	s_setprio 1
	s_waitcnt lgkmcnt(0)
	v_mfma_f32_16x16x32_bf16 v[124:127], v[144:147], v[178:181], v[124:127]
	v_mfma_f32_16x16x32_bf16 v[120:123], v[152:155], v[178:181], v[120:123]
	v_mfma_f32_16x16x32_bf16 v[108:111], v[144:147], v[208:211], v[108:111]
	v_mfma_f32_16x16x32_bf16 v[104:107], v[152:155], v[208:211], v[104:107]
	v_mfma_f32_16x16x32_bf16 v[92:95], v[144:147], v[216:219], v[92:95]
	v_mfma_f32_16x16x32_bf16 v[88:91], v[152:155], v[216:219], v[88:91]
	v_mfma_f32_16x16x32_bf16 v[76:79], v[144:147], v[224:227], v[76:79]
	v_mfma_f32_16x16x32_bf16 v[72:75], v[152:155], v[224:227], v[72:75]
	v_mfma_f32_16x16x32_bf16 v[124:127], v[148:151], v[204:207], v[124:127]
	v_mfma_f32_16x16x32_bf16 v[120:123], v[156:159], v[204:207], v[120:123]
	v_mfma_f32_16x16x32_bf16 v[108:111], v[148:151], v[212:215], v[108:111]
	v_mfma_f32_16x16x32_bf16 v[104:107], v[156:159], v[212:215], v[104:107]
	v_mfma_f32_16x16x32_bf16 v[92:95], v[148:151], v[220:223], v[92:95]
	v_mfma_f32_16x16x32_bf16 v[88:91], v[156:159], v[220:223], v[88:91]
	v_mfma_f32_16x16x32_bf16 v[76:79], v[148:151], v[228:231], v[76:79]
	v_mfma_f32_16x16x32_bf16 v[72:75], v[156:159], v[228:231], v[72:75]
	s_setprio 0
	s_setprio 1
	v_mfma_f32_16x16x32_bf16 v[116:119], v[162:165], v[178:181], v[116:119]
	v_mfma_f32_16x16x32_bf16 v[112:115], v[170:173], v[178:181], v[112:115]
	v_mfma_f32_16x16x32_bf16 v[100:103], v[162:165], v[208:211], v[100:103]
	v_mfma_f32_16x16x32_bf16 v[96:99], v[170:173], v[208:211], v[96:99]
	v_mfma_f32_16x16x32_bf16 v[84:87], v[162:165], v[216:219], v[84:87]
	v_mfma_f32_16x16x32_bf16 v[80:83], v[170:173], v[216:219], v[80:83]
	v_mfma_f32_16x16x32_bf16 v[68:71], v[162:165], v[224:227], v[68:71]
	v_mfma_f32_16x16x32_bf16 v[64:67], v[170:173], v[224:227], v[64:67]
	s_setprio 2
	s_barrier
; #define PG8_STAGE(bufoff, gbase, voff) do { _Pragma("unroll") for (int _i = 0; _i < 2; ++_i) \
;         __builtin_amdgcn_global_load_lds((const unsigned*)((const char*)(gbase) + (voff)[_i]), (PG8_LAS unsigned*)(lds + (bufoff) + ldsw + _i * 8192), 16, 0, 0); } while (0)
; #define PG8_LDA(dst, b, h) do { _Pragma("unroll") for (int m = 0; m < 4; ++m) _Pragma("unroll") for (int k = 0; k < 2; ++k) dst[m][k] = *(const PG8_LAS bf16x8*)(lds + PG8_SA(b, h) + aoff + m * 2048 + k * 1024); } while (0)
; #define PG8_MMA(ai, bj, At, Bt) do { __builtin_amdgcn_s_setprio(1); _Pragma("unroll") for (int m = 0; m < 4; ++m) _Pragma("unroll") for (int n = 0; n < 2; ++n) _Pragma("unroll") for (int k = 0; k < 2; ++k) \
;         acc[ai][bj][m][n] = __builtin_amdgcn_mfma_f32_16x16x32_bf16(Bt[n][k], At[m][k], acc[ai][bj][m][n], 0, 0, 0); __builtin_amdgcn_s_setprio(0); } while (0)
; #define PG8_WAIT_V(n) asm volatile("s_waitcnt vmcnt(" #n ")" ::: "memory")
; #define PG8_WAIT_L(n) asm volatile("s_waitcnt lgkmcnt(" #n ")" ::: "memory")
; #define PG8_BAR __builtin_amdgcn_s_barrier()
; #define PG8_SCHED __builtin_amdgcn_sched_barrier(0)
; template <class Epi, class Sched, bool ALIGN_EPI = false, bool SP2 = false>
; __device__ __forceinline__ void gemm_phase(PG8_LAS unsigned char* lds, const Gemm g, const Sched& S, const Epi& E, int wv) {
;     ...
;         for (int t = 0; t < nt; t += 2) {
;     ...
;             PG8_WAIT_V(8); PG8_WAIT_L(0); PG8_BAR; PG8_MMA(0, 0, At, B0); PG8_MMA(0, 1, At, B1); PG8_BAR; PG8_SCHED;
;             PG8_LDA(At, 1, 1); PG8_STAGE(PG8_SB(1, 0), b3, voffB); PG8_STAGE(PG8_SB(1, 1), b3 + hstep, voffB); PG8_STAGE(PG8_SA(1, 0), a3, voffA);
;             PG8_WAIT_V(8); PG8_WAIT_L(0); PG8_BAR; PG8_MMA(1, 0, At, B0); PG8_MMA(1, 1, At, B1); PG8_BAR; PG8_SCHED;
	v_mfma_f32_16x16x32_bf16 v[116:119], v[166:169], v[204:207], v[116:119]
	v_mfma_f32_16x16x32_bf16 v[112:115], v[174:177], v[204:207], v[112:115]
	v_mfma_f32_16x16x32_bf16 v[100:103], v[166:169], v[212:215], v[100:103]
	v_mfma_f32_16x16x32_bf16 v[96:99], v[174:177], v[212:215], v[96:99]
	v_mfma_f32_16x16x32_bf16 v[84:87], v[166:169], v[220:223], v[84:87]
	v_mfma_f32_16x16x32_bf16 v[80:83], v[174:177], v[220:223], v[80:83]
	v_mfma_f32_16x16x32_bf16 v[68:71], v[166:169], v[228:231], v[68:71]
	v_mfma_f32_16x16x32_bf16 v[64:67], v[174:177], v[228:231], v[64:67]
	s_setprio 0
	s_add_i32 s21, s21, s50
	v_lshl_add_u64 v[138:139], v[138:139], 0, s[74:75]
	s_mov_b32 m0, s21
	ds_read_b128 v[178:181], v143 offset:49152
	ds_read_b128 v[204:207], v143 offset:50176
	ds_read_b128 v[208:211], v143 offset:51200
	ds_read_b128 v[212:215], v143 offset:52224
	ds_read_b128 v[216:219], v143 offset:53248
	ds_read_b128 v[220:223], v143 offset:54272
	ds_read_b128 v[224:227], v143 offset:55296
	ds_read_b128 v[228:231], v143 offset:56320
	global_load_lds_dwordx4 v[138:139], off
	s_add_i32 m0, s21, 0x2000
	s_add_u32 s44, s44, 0x40080
	v_lshl_add_u64 v[138:139], v[232:233], 0, s[74:75]
	s_addc_u32 s45, s45, 0
	s_add_i32 s21, s26, s50
	global_load_lds_dwordx4 v[138:139], off
	v_lshl_add_u64 v[138:139], s[44:45], 0, v[160:161]
	s_mov_b32 m0, s21
	s_nop 0
	global_load_lds_dwordx4 v[138:139], off
	v_lshl_add_u64 v[138:139], s[44:45], 0, v[128:129]
	s_add_i32 m0, s21, 0x2000
	s_nop 0
	global_load_lds_dwordx4 v[138:139], off
	v_lshl_add_u64 v[138:139], v[234:235], 0, s[74:75]
	s_mov_b32 m0, s60
	s_nop 0
	global_load_lds_dwordx4 v[138:139], off
	v_lshl_add_u64 v[138:139], v[236:237], 0, s[74:75]
	s_mov_b32 m0, s61
	s_nop 0
	global_load_lds_dwordx4 v[138:139], off
	s_waitcnt vmcnt(8)
	s_waitcnt lgkmcnt(0)
	s_barrier
	s_setprio 1
	s_waitcnt lgkmcnt(0)
	v_mfma_f32_16x16x32_bf16 v[60:63], v[144:147], v[178:181], v[60:63]
	v_mfma_f32_16x16x32_bf16 v[56:59], v[152:155], v[178:181], v[56:59]
	v_mfma_f32_16x16x32_bf16 v[44:47], v[144:147], v[208:211], v[44:47]
	v_mfma_f32_16x16x32_bf16 v[40:43], v[152:155], v[208:211], v[40:43]
	v_mfma_f32_16x16x32_bf16 v[28:31], v[144:147], v[216:219], v[28:31]
	v_mfma_f32_16x16x32_bf16 v[24:27], v[152:155], v[216:219], v[24:27]
	v_mfma_f32_16x16x32_bf16 v[12:15], v[144:147], v[224:227], v[12:15]
	v_mfma_f32_16x16x32_bf16 v[8:11], v[152:155], v[224:227], v[8:11]
	v_mfma_f32_16x16x32_bf16 v[60:63], v[148:151], v[204:207], v[60:63]
	v_mfma_f32_16x16x32_bf16 v[56:59], v[156:159], v[204:207], v[56:59]
	v_mfma_f32_16x16x32_bf16 v[44:47], v[148:151], v[212:215], v[44:47]
	v_mfma_f32_16x16x32_bf16 v[40:43], v[156:159], v[212:215], v[40:43]
	v_mfma_f32_16x16x32_bf16 v[28:31], v[148:151], v[220:223], v[28:31]
	v_mfma_f32_16x16x32_bf16 v[24:27], v[156:159], v[220:223], v[24:27]
	v_mfma_f32_16x16x32_bf16 v[12:15], v[148:151], v[228:231], v[12:15]
	v_mfma_f32_16x16x32_bf16 v[8:11], v[156:159], v[228:231], v[8:11]
	s_setprio 0
	s_setprio 1
	v_mfma_f32_16x16x32_bf16 v[52:55], v[162:165], v[178:181], v[52:55]
	v_mfma_f32_16x16x32_bf16 v[48:51], v[170:173], v[178:181], v[48:51]
	v_mfma_f32_16x16x32_bf16 v[36:39], v[162:165], v[208:211], v[36:39]
	v_mfma_f32_16x16x32_bf16 v[32:35], v[170:173], v[208:211], v[32:35]
	v_mfma_f32_16x16x32_bf16 v[20:23], v[162:165], v[216:219], v[20:23]
	v_mfma_f32_16x16x32_bf16 v[16:19], v[170:173], v[216:219], v[16:19]
	v_mfma_f32_16x16x32_bf16 v[4:7], v[162:165], v[224:227], v[4:7]
	v_mfma_f32_16x16x32_bf16 v[0:3], v[170:173], v[224:227], v[0:3]
	s_setprio 2
	s_barrier
	v_mfma_f32_16x16x32_bf16 v[52:55], v[166:169], v[204:207], v[52:55]
	v_mfma_f32_16x16x32_bf16 v[48:51], v[174:177], v[204:207], v[48:51]
	v_mfma_f32_16x16x32_bf16 v[36:39], v[166:169], v[212:215], v[36:39]
	v_mfma_f32_16x16x32_bf16 v[32:35], v[174:177], v[212:215], v[32:35]
	v_mfma_f32_16x16x32_bf16 v[20:23], v[166:169], v[220:223], v[20:23]
	v_mfma_f32_16x16x32_bf16 v[16:19], v[174:177], v[220:223], v[16:19]
	v_mfma_f32_16x16x32_bf16 v[4:7], v[166:169], v[228:231], v[4:7]
	v_mfma_f32_16x16x32_bf16 v[0:3], v[174:177], v[228:231], v[0:3]
	s_setprio 0
	s_add_i32 s67, s67, 2
	s_add_u32 s42, s42, 0x100
	s_addc_u32 s43, s43, 0
	s_add_u32 s65, s65, 0x100
	s_addc_u32 s66, s66, 0
	s_cmp_gt_u32 s67, 13
	s_cbranch_scc0 .LBB0_773
	s_and_b64 vcc, exec, s[10:11]
	s_cbranch_vccz .LBB0_776
	s_barrier

; #define PG8_STAGE(bufoff, gbase, voff) do { _Pragma("unroll") for (int _i = 0; _i < 2; ++_i) \
;         __builtin_amdgcn_global_load_lds((const unsigned*)((const char*)(gbase) + (voff)[_i]), (PG8_LAS unsigned*)(lds + (bufoff) + ldsw + _i * 8192), 16, 0, 0); } while (0)
; #define PG8_LDA(dst, b, h) do { _Pragma("unroll") for (int m = 0; m < 4; ++m) _Pragma("unroll") for (int k = 0; k < 2; ++k) dst[m][k] = *(const PG8_LAS bf16x8*)(lds + PG8_SA(b, h) + aoff + m * 2048 + k * 1024); } while (0)
; #define PG8_LDB(dst, b, h) do { _Pragma("unroll") for (int n = 0; n < 2; ++n) _Pragma("unroll") for (int k = 0; k < 2; ++k) dst[n][k] = *(const PG8_LAS bf16x8*)(lds + PG8_SB(b, h) + boff + n * 2048 + k * 1024); } while (0)
; #define PG8_MMA(ai, bj, At, Bt) do { __builtin_amdgcn_s_setprio(1); _Pragma("unroll") for (int m = 0; m < 4; ++m) _Pragma("unroll") for (int n = 0; n < 2; ++n) _Pragma("unroll") for (int k = 0; k < 2; ++k) \
;         acc[ai][bj][m][n] = __builtin_amdgcn_mfma_f32_16x16x32_bf16(Bt[n][k], At[m][k], acc[ai][bj][m][n], 0, 0, 0); __builtin_amdgcn_s_setprio(0); } while (0)
; #define PG8_WAIT_V(n) asm volatile("s_waitcnt vmcnt(" #n ")" ::: "memory")
; #define PG8_WAIT_L(n) asm volatile("s_waitcnt lgkmcnt(" #n ")" ::: "memory")
; #define PG8_BAR __builtin_amdgcn_s_barrier()
; #define PG8_SCHED __builtin_amdgcn_sched_barrier(0)
; template <class Epi, class Sched, bool ALIGN_EPI = false, bool SP2 = false>
; __device__ __forceinline__ void gemm_phase(PG8_LAS unsigned char* lds, const Gemm g, const Sched& S, const Epi& E, int wv) {
;     ...
;             PG8_LDB(B0, 0, 0); PG8_LDB(B1, 0, 1); PG8_SCHED; PG8_LDA(At, 0, 0); PG8_STAGE(PG8_SA(1, 1), a1 + hstep, voffA);
;             PG8_WAIT_V(8); PG8_WAIT_L(0); PG8_BAR; PG8_MMA(0, 0, At, B0); PG8_MMA(0, 1, At, B1); PG8_BAR; PG8_SCHED;
;             PG8_LDA(At, 0, 1); PG8_STAGE(PG8_SB(0, 0), b2, voffB); PG8_STAGE(PG8_SB(0, 1), b2 + hstep, voffB); PG8_STAGE(PG8_SA(0, 0), a2, voffA);
;             PG8_WAIT_V(8); PG8_WAIT_L(0); PG8_BAR; PG8_MMA(1, 0, At, B0); PG8_MMA(1, 1, At, B1); PG8_BAR; PG8_SCHED;
.LBB0_845:
	s_add_u32 s44, s6, 0x100
	s_addc_u32 s45, s7, 0
	s_add_i32 s21, 0, 0x10000
	s_cmp_eq_u32 s67, 40
	s_cselect_b32 s51, s41, s45
	s_cselect_b32 s50, s40, s44
	s_cselect_b32 s49, s43, s25
	s_cselect_b32 s48, s42, s24
	s_add_i32 s26, 0, 0x14000
	v_add_u32_e32 v140, s21, v170
	v_add_u32_e32 v168, s26, v170
	ds_read_b128 v[128:131], v140
	ds_read_b128 v[132:135], v140 offset:1024
	ds_read_b128 v[136:139], v140 offset:2048
	ds_read_b128 v[140:143], v140 offset:3072
	ds_read_b128 v[144:147], v168
	ds_read_b128 v[148:151], v168 offset:1024
	ds_read_b128 v[164:167], v168 offset:2048
	ds_read_b128 v[172:175], v168 offset:3072
	v_lshl_add_u64 v[168:169], s[6:7], 0, v[158:159]
	s_add_i32 m0, s31, 0xc000
	ds_read_b128 v[176:179], v171
	ds_read_b128 v[204:207], v171 offset:1024
	ds_read_b128 v[208:211], v171 offset:2048
	ds_read_b128 v[212:215], v171 offset:3072
	ds_read_b128 v[216:219], v171 offset:4096
	ds_read_b128 v[220:223], v171 offset:5120
	ds_read_b128 v[224:227], v171 offset:6144
	ds_read_b128 v[228:231], v171 offset:7168
	global_load_lds_dwordx4 v[168:169], off
	v_lshl_add_u64 v[168:169], s[6:7], 0, v[162:163]
	s_add_i32 m0, s31, 0xe000
	s_nop 0
	global_load_lds_dwordx4 v[168:169], off
	s_waitcnt vmcnt(8)
	s_waitcnt lgkmcnt(0)
	s_barrier
	s_setprio 1
	s_waitcnt lgkmcnt(0)
	v_mfma_f32_16x16x32_bf16 v[124:127], v[128:131], v[176:179], v[124:127]
	v_mfma_f32_16x16x32_bf16 v[120:123], v[136:139], v[176:179], v[120:123]
	v_mfma_f32_16x16x32_bf16 v[108:111], v[128:131], v[208:211], v[108:111]
	v_mfma_f32_16x16x32_bf16 v[104:107], v[136:139], v[208:211], v[104:107]
	v_mfma_f32_16x16x32_bf16 v[92:95], v[128:131], v[216:219], v[92:95]
	v_mfma_f32_16x16x32_bf16 v[88:91], v[136:139], v[216:219], v[88:91]
	v_mfma_f32_16x16x32_bf16 v[76:79], v[128:131], v[224:227], v[76:79]
	v_mfma_f32_16x16x32_bf16 v[72:75], v[136:139], v[224:227], v[72:75]
	v_mfma_f32_16x16x32_bf16 v[124:127], v[132:135], v[204:207], v[124:127]
	v_mfma_f32_16x16x32_bf16 v[120:123], v[140:143], v[204:207], v[120:123]
	v_mfma_f32_16x16x32_bf16 v[108:111], v[132:135], v[212:215], v[108:111]
	v_mfma_f32_16x16x32_bf16 v[104:107], v[140:143], v[212:215], v[104:107]
	v_mfma_f32_16x16x32_bf16 v[92:95], v[132:135], v[220:223], v[92:95]
	v_mfma_f32_16x16x32_bf16 v[88:91], v[140:143], v[220:223], v[88:91]
	v_mfma_f32_16x16x32_bf16 v[76:79], v[132:135], v[228:231], v[76:79]
	v_mfma_f32_16x16x32_bf16 v[72:75], v[140:143], v[228:231], v[72:75]
	s_setprio 0
	s_setprio 1
	v_mfma_f32_16x16x32_bf16 v[116:119], v[144:147], v[176:179], v[116:119]
	v_mfma_f32_16x16x32_bf16 v[112:115], v[164:167], v[176:179], v[112:115]
	v_mfma_f32_16x16x32_bf16 v[100:103], v[144:147], v[208:211], v[100:103]
	v_mfma_f32_16x16x32_bf16 v[96:99], v[164:167], v[208:211], v[96:99]
	v_mfma_f32_16x16x32_bf16 v[84:87], v[144:147], v[216:219], v[84:87]
	v_mfma_f32_16x16x32_bf16 v[80:83], v[164:167], v[216:219], v[80:83]
	v_mfma_f32_16x16x32_bf16 v[68:71], v[144:147], v[224:227], v[68:71]
	v_mfma_f32_16x16x32_bf16 v[64:67], v[164:167], v[224:227], v[64:67]
	s_setprio 2
	s_barrier
	v_mfma_f32_16x16x32_bf16 v[116:119], v[148:151], v[204:207], v[116:119]
	v_mfma_f32_16x16x32_bf16 v[112:115], v[172:175], v[204:207], v[112:115]
	v_mfma_f32_16x16x32_bf16 v[100:103], v[148:151], v[212:215], v[100:103]
	v_mfma_f32_16x16x32_bf16 v[96:99], v[172:175], v[212:215], v[96:99]
	v_mfma_f32_16x16x32_bf16 v[84:87], v[148:151], v[220:223], v[84:87]
	v_mfma_f32_16x16x32_bf16 v[80:83], v[172:175], v[220:223], v[80:83]
	v_mfma_f32_16x16x32_bf16 v[68:71], v[148:151], v[228:231], v[68:71]
	v_mfma_f32_16x16x32_bf16 v[64:67], v[172:175], v[228:231], v[64:67]
	s_setprio 0
	s_add_i32 s6, s21, s30
	v_lshl_add_u64 v[168:169], s[48:49], 0, v[160:161]
	s_mov_b32 m0, s6
	ds_read_b128 v[176:179], v171 offset:16384
	ds_read_b128 v[204:207], v171 offset:17408
	ds_read_b128 v[208:211], v171 offset:18432
	ds_read_b128 v[212:215], v171 offset:19456
	ds_read_b128 v[216:219], v171 offset:20480
	ds_read_b128 v[220:223], v171 offset:21504
	ds_read_b128 v[224:227], v171 offset:22528
	ds_read_b128 v[228:231], v171 offset:23552
	global_load_lds_dwordx4 v[168:169], off
	s_add_i32 m0, s6, 0x2000
	s_add_u32 s6, s48, 0xb0000
	v_lshl_add_u64 v[180:181], s[48:49], 0, v[152:153]
	s_addc_u32 s7, s49, 0
	s_add_i32 s21, s26, s30
	global_load_lds_dwordx4 v[180:181], off
	v_lshl_add_u64 v[232:233], s[6:7], 0, v[160:161]
	s_mov_b32 m0, s21
	v_lshl_add_u64 v[234:235], s[50:51], 0, v[154:155]
	global_load_lds_dwordx4 v[232:233], off
	v_lshl_add_u64 v[232:233], s[6:7], 0, v[152:153]
	s_add_i32 m0, s21, 0x2000
	s_nop 0
	global_load_lds_dwordx4 v[232:233], off
	v_lshl_add_u64 v[232:233], s[50:51], 0, v[156:157]
	s_mov_b32 m0, s31
	s_nop 0
	global_load_lds_dwordx4 v[232:233], off
	s_mov_b32 m0, s52
	s_nop 0
	global_load_lds_dwordx4 v[234:235], off
	s_waitcnt vmcnt(8)
	s_waitcnt lgkmcnt(0)
	s_barrier
; #define PG8_STAGE(bufoff, gbase, voff) do { _Pragma("unroll") for (int _i = 0; _i < 2; ++_i) \
;         __builtin_amdgcn_global_load_lds((const unsigned*)((const char*)(gbase) + (voff)[_i]), (PG8_LAS unsigned*)(lds + (bufoff) + ldsw + _i * 8192), 16, 0, 0); } while (0)
; #define PG8_LDA(dst, b, h) do { _Pragma("unroll") for (int m = 0; m < 4; ++m) _Pragma("unroll") for (int k = 0; k < 2; ++k) dst[m][k] = *(const PG8_LAS bf16x8*)(lds + PG8_SA(b, h) + aoff + m * 2048 + k * 1024); } while (0)
; #define PG8_LDB(dst, b, h) do { _Pragma("unroll") for (int n = 0; n < 2; ++n) _Pragma("unroll") for (int k = 0; k < 2; ++k) dst[n][k] = *(const PG8_LAS bf16x8*)(lds + PG8_SB(b, h) + boff + n * 2048 + k * 1024); } while (0)
; #define PG8_MMA(ai, bj, At, Bt) do { __builtin_amdgcn_s_setprio(1); _Pragma("unroll") for (int m = 0; m < 4; ++m) _Pragma("unroll") for (int n = 0; n < 2; ++n) _Pragma("unroll") for (int k = 0; k < 2; ++k) \
;         acc[ai][bj][m][n] = __builtin_amdgcn_mfma_f32_16x16x32_bf16(Bt[n][k], At[m][k], acc[ai][bj][m][n], 0, 0, 0); __builtin_amdgcn_s_setprio(0); } while (0)
; #define PG8_WAIT_V(n) asm volatile("s_waitcnt vmcnt(" #n ")" ::: "memory")
; #define PG8_WAIT_L(n) asm volatile("s_waitcnt lgkmcnt(" #n ")" ::: "memory")
; #define PG8_BAR __builtin_amdgcn_s_barrier()
; #define PG8_SCHED __builtin_amdgcn_sched_barrier(0)
; template <class Epi, class Sched, bool ALIGN_EPI = false, bool SP2 = false>
; __device__ __forceinline__ void gemm_phase(PG8_LAS unsigned char* lds, const Gemm g, const Sched& S, const Epi& E, int wv) {
;     ...
;             PG8_WAIT_V(8); PG8_WAIT_L(0); PG8_BAR; PG8_MMA(1, 0, At, B0); PG8_MMA(1, 1, At, B1); PG8_BAR; PG8_SCHED;
;             PG8_LDB(B0, 1, 0); PG8_LDB(B1, 1, 1); PG8_SCHED; PG8_LDA(At, 1, 0); PG8_STAGE(PG8_SA(0, 1), a2 + hstep, voffA);
;             PG8_WAIT_V(8); PG8_WAIT_L(0); PG8_BAR; PG8_MMA(0, 0, At, B0); PG8_MMA(0, 1, At, B1); PG8_BAR; PG8_SCHED;
	s_setprio 1
	s_waitcnt lgkmcnt(0)
	v_mfma_f32_16x16x32_bf16 v[60:63], v[128:131], v[176:179], v[60:63]
	v_mfma_f32_16x16x32_bf16 v[56:59], v[136:139], v[176:179], v[56:59]
	v_mfma_f32_16x16x32_bf16 v[44:47], v[128:131], v[208:211], v[44:47]
	v_mfma_f32_16x16x32_bf16 v[40:43], v[136:139], v[208:211], v[40:43]
	v_mfma_f32_16x16x32_bf16 v[28:31], v[128:131], v[216:219], v[28:31]
	v_mfma_f32_16x16x32_bf16 v[24:27], v[136:139], v[216:219], v[24:27]
	v_mfma_f32_16x16x32_bf16 v[12:15], v[128:131], v[224:227], v[12:15]
	v_mfma_f32_16x16x32_bf16 v[8:11], v[136:139], v[224:227], v[8:11]
	v_mfma_f32_16x16x32_bf16 v[60:63], v[132:135], v[204:207], v[60:63]
	v_mfma_f32_16x16x32_bf16 v[56:59], v[140:143], v[204:207], v[56:59]
	v_mfma_f32_16x16x32_bf16 v[44:47], v[132:135], v[212:215], v[44:47]
	v_mfma_f32_16x16x32_bf16 v[40:43], v[140:143], v[212:215], v[40:43]
	v_mfma_f32_16x16x32_bf16 v[28:31], v[132:135], v[220:223], v[28:31]
	v_mfma_f32_16x16x32_bf16 v[24:27], v[140:143], v[220:223], v[24:27]
	v_mfma_f32_16x16x32_bf16 v[12:15], v[132:135], v[228:231], v[12:15]
	v_mfma_f32_16x16x32_bf16 v[8:11], v[140:143], v[228:231], v[8:11]
	s_setprio 0
	s_setprio 1
	v_mfma_f32_16x16x32_bf16 v[52:55], v[144:147], v[176:179], v[52:55]
	v_mfma_f32_16x16x32_bf16 v[48:51], v[164:167], v[176:179], v[48:51]
	v_mfma_f32_16x16x32_bf16 v[36:39], v[144:147], v[208:211], v[36:39]
	v_mfma_f32_16x16x32_bf16 v[32:35], v[164:167], v[208:211], v[32:35]
	v_mfma_f32_16x16x32_bf16 v[20:23], v[144:147], v[216:219], v[20:23]
	v_mfma_f32_16x16x32_bf16 v[16:19], v[164:167], v[216:219], v[16:19]
	v_mfma_f32_16x16x32_bf16 v[4:7], v[144:147], v[224:227], v[4:7]
	v_mfma_f32_16x16x32_bf16 v[0:3], v[164:167], v[224:227], v[0:3]
	s_setprio 2
	s_barrier
	v_mfma_f32_16x16x32_bf16 v[52:55], v[148:151], v[204:207], v[52:55]
	v_mfma_f32_16x16x32_bf16 v[48:51], v[172:175], v[204:207], v[48:51]
	v_mfma_f32_16x16x32_bf16 v[36:39], v[148:151], v[212:215], v[36:39]
	v_mfma_f32_16x16x32_bf16 v[32:35], v[172:175], v[212:215], v[32:35]
	v_mfma_f32_16x16x32_bf16 v[20:23], v[148:151], v[220:223], v[20:23]
	v_mfma_f32_16x16x32_bf16 v[16:19], v[172:175], v[220:223], v[16:19]
	v_mfma_f32_16x16x32_bf16 v[4:7], v[148:151], v[228:231], v[4:7]
	v_mfma_f32_16x16x32_bf16 v[0:3], v[172:175], v[228:231], v[0:3]
	s_setprio 0
	s_add_i32 s21, 0, 0x18000
	s_add_i32 s26, 0, 0x1c000
	v_add_u32_e32 v140, s21, v170
	v_add_u32_e32 v172, s26, v170
	ds_read_b128 v[128:131], v140
	ds_read_b128 v[132:135], v140 offset:1024
	ds_read_b128 v[136:139], v140 offset:2048
	ds_read_b128 v[140:143], v140 offset:3072
	ds_read_b128 v[144:147], v172
	ds_read_b128 v[148:151], v172 offset:1024
	ds_read_b128 v[164:167], v172 offset:2048
	ds_read_b128 v[172:175], v172 offset:3072
	s_add_u32 s6, s50, 0xb0000
	s_addc_u32 s7, s51, 0
	s_mov_b32 m0, s53
	v_lshl_add_u64 v[236:237], s[6:7], 0, v[156:157]
	ds_read_b128 v[176:179], v171 offset:32768
	ds_read_b128 v[204:207], v171 offset:33792
	ds_read_b128 v[208:211], v171 offset:34816
	ds_read_b128 v[212:215], v171 offset:35840
	ds_read_b128 v[216:219], v171 offset:36864
	ds_read_b128 v[220:223], v171 offset:37888
	ds_read_b128 v[224:227], v171 offset:38912
	ds_read_b128 v[228:231], v171 offset:39936
	global_load_lds_dwordx4 v[236:237], off
	v_lshl_add_u64 v[236:237], s[6:7], 0, v[154:155]
	s_mov_b32 m0, s54
	s_nop 0
	global_load_lds_dwordx4 v[236:237], off
	s_waitcnt vmcnt(8)
	s_waitcnt lgkmcnt(0)
	s_barrier
	s_setprio 1
	s_waitcnt lgkmcnt(0)
	v_mfma_f32_16x16x32_bf16 v[124:127], v[128:131], v[176:179], v[124:127]
	v_mfma_f32_16x16x32_bf16 v[120:123], v[136:139], v[176:179], v[120:123]
	v_mfma_f32_16x16x32_bf16 v[108:111], v[128:131], v[208:211], v[108:111]
	v_mfma_f32_16x16x32_bf16 v[104:107], v[136:139], v[208:211], v[104:107]
	v_mfma_f32_16x16x32_bf16 v[92:95], v[128:131], v[216:219], v[92:95]
	v_mfma_f32_16x16x32_bf16 v[88:91], v[136:139], v[216:219], v[88:91]
	v_mfma_f32_16x16x32_bf16 v[76:79], v[128:131], v[224:227], v[76:79]
	v_mfma_f32_16x16x32_bf16 v[72:75], v[136:139], v[224:227], v[72:75]
	v_mfma_f32_16x16x32_bf16 v[124:127], v[132:135], v[204:207], v[124:127]
	v_mfma_f32_16x16x32_bf16 v[120:123], v[140:143], v[204:207], v[120:123]
	v_mfma_f32_16x16x32_bf16 v[108:111], v[132:135], v[212:215], v[108:111]
	v_mfma_f32_16x16x32_bf16 v[104:107], v[140:143], v[212:215], v[104:107]
	v_mfma_f32_16x16x32_bf16 v[92:95], v[132:135], v[220:223], v[92:95]
	v_mfma_f32_16x16x32_bf16 v[88:91], v[140:143], v[220:223], v[88:91]
	v_mfma_f32_16x16x32_bf16 v[76:79], v[132:135], v[228:231], v[76:79]
	v_mfma_f32_16x16x32_bf16 v[72:75], v[140:143], v[228:231], v[72:75]
	s_setprio 0
	s_setprio 1
	v_mfma_f32_16x16x32_bf16 v[116:119], v[144:147], v[176:179], v[116:119]
	v_mfma_f32_16x16x32_bf16 v[112:115], v[164:167], v[176:179], v[112:115]
	v_mfma_f32_16x16x32_bf16 v[100:103], v[144:147], v[208:211], v[100:103]
	v_mfma_f32_16x16x32_bf16 v[96:99], v[164:167], v[208:211], v[96:99]
	v_mfma_f32_16x16x32_bf16 v[84:87], v[144:147], v[216:219], v[84:87]
	v_mfma_f32_16x16x32_bf16 v[80:83], v[164:167], v[216:219], v[80:83]
	v_mfma_f32_16x16x32_bf16 v[68:71], v[144:147], v[224:227], v[68:71]
	v_mfma_f32_16x16x32_bf16 v[64:67], v[164:167], v[224:227], v[64:67]
	s_setprio 2
	s_barrier
; #define PG8_STAGE(bufoff, gbase, voff) do { _Pragma("unroll") for (int _i = 0; _i < 2; ++_i) \
;         __builtin_amdgcn_global_load_lds((const unsigned*)((const char*)(gbase) + (voff)[_i]), (PG8_LAS unsigned*)(lds + (bufoff) + ldsw + _i * 8192), 16, 0, 0); } while (0)
; #define PG8_LDA(dst, b, h) do { _Pragma("unroll") for (int m = 0; m < 4; ++m) _Pragma("unroll") for (int k = 0; k < 2; ++k) dst[m][k] = *(const PG8_LAS bf16x8*)(lds + PG8_SA(b, h) + aoff + m * 2048 + k * 1024); } while (0)
; #define PG8_MMA(ai, bj, At, Bt) do { __builtin_amdgcn_s_setprio(1); _Pragma("unroll") for (int m = 0; m < 4; ++m) _Pragma("unroll") for (int n = 0; n < 2; ++n) _Pragma("unroll") for (int k = 0; k < 2; ++k) \
;         acc[ai][bj][m][n] = __builtin_amdgcn_mfma_f32_16x16x32_bf16(Bt[n][k], At[m][k], acc[ai][bj][m][n], 0, 0, 0); __builtin_amdgcn_s_setprio(0); } while (0)
; #define PG8_WAIT_V(n) asm volatile("s_waitcnt vmcnt(" #n ")" ::: "memory")
; #define PG8_WAIT_L(n) asm volatile("s_waitcnt lgkmcnt(" #n ")" ::: "memory")
; #define PG8_BAR __builtin_amdgcn_s_barrier()
; #define PG8_SCHED __builtin_amdgcn_sched_barrier(0)
; template <class Epi, class Sched, bool ALIGN_EPI = false, bool SP2 = false>
; __device__ __forceinline__ void gemm_phase(PG8_LAS unsigned char* lds, const Gemm g, const Sched& S, const Epi& E, int wv) {
;     ...
;         for (int t = 0; t < nt; t += 2) {
;     ...
;             PG8_WAIT_V(8); PG8_WAIT_L(0); PG8_BAR; PG8_MMA(0, 0, At, B0); PG8_MMA(0, 1, At, B1); PG8_BAR; PG8_SCHED;
;             PG8_LDA(At, 1, 1); PG8_STAGE(PG8_SB(1, 0), b3, voffB); PG8_STAGE(PG8_SB(1, 1), b3 + hstep, voffB); PG8_STAGE(PG8_SA(1, 0), a3, voffA);
;             PG8_WAIT_V(8); PG8_WAIT_L(0); PG8_BAR; PG8_MMA(1, 0, At, B0); PG8_MMA(1, 1, At, B1); PG8_BAR; PG8_SCHED;
	v_mfma_f32_16x16x32_bf16 v[116:119], v[148:151], v[204:207], v[116:119]
	v_mfma_f32_16x16x32_bf16 v[112:115], v[172:175], v[204:207], v[112:115]
	v_mfma_f32_16x16x32_bf16 v[100:103], v[148:151], v[212:215], v[100:103]
	v_mfma_f32_16x16x32_bf16 v[96:99], v[172:175], v[212:215], v[96:99]
	v_mfma_f32_16x16x32_bf16 v[84:87], v[148:151], v[220:223], v[84:87]
	v_mfma_f32_16x16x32_bf16 v[80:83], v[172:175], v[220:223], v[80:83]
	v_mfma_f32_16x16x32_bf16 v[68:71], v[148:151], v[228:231], v[68:71]
	v_mfma_f32_16x16x32_bf16 v[64:67], v[172:175], v[228:231], v[64:67]
	s_setprio 0
	s_add_i32 s6, s21, s30
	v_lshl_add_u64 v[168:169], v[168:169], 0, s[74:75]
	s_mov_b32 m0, s6
	ds_read_b128 v[176:179], v171 offset:49152
	ds_read_b128 v[204:207], v171 offset:50176
	ds_read_b128 v[208:211], v171 offset:51200
	ds_read_b128 v[212:215], v171 offset:52224
	ds_read_b128 v[216:219], v171 offset:53248
	ds_read_b128 v[220:223], v171 offset:54272
	ds_read_b128 v[224:227], v171 offset:55296
	ds_read_b128 v[228:231], v171 offset:56320
	global_load_lds_dwordx4 v[168:169], off
	s_add_i32 m0, s6, 0x2000
	s_add_u32 s6, s48, 0xb0080
	v_lshl_add_u64 v[168:169], v[180:181], 0, s[74:75]
	s_addc_u32 s7, s49, 0
	s_add_i32 s21, s26, s30
	global_load_lds_dwordx4 v[168:169], off
	v_lshl_add_u64 v[168:169], s[6:7], 0, v[160:161]
	s_mov_b32 m0, s21
	s_nop 0
	global_load_lds_dwordx4 v[168:169], off
	v_lshl_add_u64 v[168:169], s[6:7], 0, v[152:153]
	s_add_i32 m0, s21, 0x2000
	s_nop 0
	global_load_lds_dwordx4 v[168:169], off
	v_lshl_add_u64 v[168:169], v[232:233], 0, s[74:75]
	s_mov_b32 m0, s61
	s_nop 0
	global_load_lds_dwordx4 v[168:169], off
	v_lshl_add_u64 v[168:169], v[234:235], 0, s[74:75]
	s_mov_b32 m0, s62
	s_nop 0
	global_load_lds_dwordx4 v[168:169], off
	s_waitcnt vmcnt(8)
	s_waitcnt lgkmcnt(0)
	s_barrier
	s_setprio 1
	s_waitcnt lgkmcnt(0)
	v_mfma_f32_16x16x32_bf16 v[60:63], v[128:131], v[176:179], v[60:63]
	v_mfma_f32_16x16x32_bf16 v[56:59], v[136:139], v[176:179], v[56:59]
	v_mfma_f32_16x16x32_bf16 v[44:47], v[128:131], v[208:211], v[44:47]
	v_mfma_f32_16x16x32_bf16 v[40:43], v[136:139], v[208:211], v[40:43]
	v_mfma_f32_16x16x32_bf16 v[28:31], v[128:131], v[216:219], v[28:31]
	v_mfma_f32_16x16x32_bf16 v[24:27], v[136:139], v[216:219], v[24:27]
	v_mfma_f32_16x16x32_bf16 v[12:15], v[128:131], v[224:227], v[12:15]
	v_mfma_f32_16x16x32_bf16 v[8:11], v[136:139], v[224:227], v[8:11]
	v_mfma_f32_16x16x32_bf16 v[60:63], v[132:135], v[204:207], v[60:63]
	v_mfma_f32_16x16x32_bf16 v[56:59], v[140:143], v[204:207], v[56:59]
	v_mfma_f32_16x16x32_bf16 v[44:47], v[132:135], v[212:215], v[44:47]
	v_mfma_f32_16x16x32_bf16 v[40:43], v[140:143], v[212:215], v[40:43]
	v_mfma_f32_16x16x32_bf16 v[28:31], v[132:135], v[220:223], v[28:31]
	v_mfma_f32_16x16x32_bf16 v[24:27], v[140:143], v[220:223], v[24:27]
	v_mfma_f32_16x16x32_bf16 v[12:15], v[132:135], v[228:231], v[12:15]
	v_mfma_f32_16x16x32_bf16 v[8:11], v[140:143], v[228:231], v[8:11]
	s_setprio 0
	s_setprio 1
	v_mfma_f32_16x16x32_bf16 v[52:55], v[144:147], v[176:179], v[52:55]
	v_mfma_f32_16x16x32_bf16 v[48:51], v[164:167], v[176:179], v[48:51]
	v_mfma_f32_16x16x32_bf16 v[36:39], v[144:147], v[208:211], v[36:39]
	v_mfma_f32_16x16x32_bf16 v[32:35], v[164:167], v[208:211], v[32:35]
	v_mfma_f32_16x16x32_bf16 v[20:23], v[144:147], v[216:219], v[20:23]
	v_mfma_f32_16x16x32_bf16 v[16:19], v[164:167], v[216:219], v[16:19]
	v_mfma_f32_16x16x32_bf16 v[4:7], v[144:147], v[224:227], v[4:7]
	v_mfma_f32_16x16x32_bf16 v[0:3], v[164:167], v[224:227], v[0:3]
	s_setprio 2
	s_barrier
	v_mfma_f32_16x16x32_bf16 v[52:55], v[148:151], v[204:207], v[52:55]
	v_mfma_f32_16x16x32_bf16 v[48:51], v[172:175], v[204:207], v[48:51]
	v_mfma_f32_16x16x32_bf16 v[36:39], v[148:151], v[212:215], v[36:39]
	v_mfma_f32_16x16x32_bf16 v[32:35], v[172:175], v[212:215], v[32:35]
	v_mfma_f32_16x16x32_bf16 v[20:23], v[148:151], v[220:223], v[20:23]
	v_mfma_f32_16x16x32_bf16 v[16:19], v[172:175], v[220:223], v[16:19]
	v_mfma_f32_16x16x32_bf16 v[4:7], v[148:151], v[228:231], v[4:7]
	v_mfma_f32_16x16x32_bf16 v[0:3], v[172:175], v[228:231], v[0:3]
	s_setprio 0
	s_add_i32 s67, s67, 2
	s_add_u32 s24, s24, 0x100
	s_addc_u32 s25, s25, 0
	s_cmp_gt_u32 s67, 41
	s_mov_b64 s[6:7], s[44:45]
	s_cbranch_scc0 .LBB0_845
	s_and_b64 vcc, exec, s[34:35]
	s_cbranch_vccz .LBB0_848
	s_barrier

; #define PG8_STAGE(bufoff, gbase, voff) do { _Pragma("unroll") for (int _i = 0; _i < 2; ++_i) \
;         __builtin_amdgcn_global_load_lds((const unsigned*)((const char*)(gbase) + (voff)[_i]), (PG8_LAS unsigned*)(lds + (bufoff) + ldsw + _i * 8192), 16, 0, 0); } while (0)
; #define PG8_LDA(dst, b, h) do { _Pragma("unroll") for (int m = 0; m < 4; ++m) _Pragma("unroll") for (int k = 0; k < 2; ++k) dst[m][k] = *(const PG8_LAS bf16x8*)(lds + PG8_SA(b, h) + aoff + m * 2048 + k * 1024); } while (0)
; #define PG8_LDB(dst, b, h) do { _Pragma("unroll") for (int n = 0; n < 2; ++n) _Pragma("unroll") for (int k = 0; k < 2; ++k) dst[n][k] = *(const PG8_LAS bf16x8*)(lds + PG8_SB(b, h) + boff + n * 2048 + k * 1024); } while (0)
; #define PG8_MMA(ai, bj, At, Bt) do { __builtin_amdgcn_s_setprio(1); _Pragma("unroll") for (int m = 0; m < 4; ++m) _Pragma("unroll") for (int n = 0; n < 2; ++n) _Pragma("unroll") for (int k = 0; k < 2; ++k) \
;         acc[ai][bj][m][n] = __builtin_amdgcn_mfma_f32_16x16x32_bf16(Bt[n][k], At[m][k], acc[ai][bj][m][n], 0, 0, 0); __builtin_amdgcn_s_setprio(0); } while (0)
; #define PG8_WAIT_V(n) asm volatile("s_waitcnt vmcnt(" #n ")" ::: "memory")
; #define PG8_WAIT_L(n) asm volatile("s_waitcnt lgkmcnt(" #n ")" ::: "memory")
; #define PG8_BAR __builtin_amdgcn_s_barrier()
; #define PG8_SCHED __builtin_amdgcn_sched_barrier(0)
; template <class Epi, class Sched, bool ALIGN_EPI = false, bool SP2 = false>
; __device__ __forceinline__ void gemm_phase(PG8_LAS unsigned char* lds, const Gemm g, const Sched& S, const Epi& E, int wv) {
;     ...
;             const bool last = (t == nt - 2);
;             const char* a1 = cA + (size_t)(t + 1) * kstep;
;             const char* a2 = last ? nA : cA + (size_t)(t + 2) * kstep; const char* b2 = last ? nB : cB + (size_t)(t + 2) * kstep;
;             const char* a3 = a2 + kstep; const char* b3 = b2 + kstep;
;             if (last && has_next) S.a_ready(nxt);
;             if constexpr (SP2) {
;             PG8_LDB(B0, 0, 0); PG8_LDB(B1, 0, 1); PG8_SCHED; PG8_LDA(At, 0, 0); PG8_STAGE(PG8_SA(1, 1), a1 + hstep, voffA);
;             PG8_WAIT_V(8); PG8_WAIT_L(0); PG8_BAR; PG8_MMA(0, 0, At, B0); PG8_MMA(0, 1, At, B1); PG8_BAR; PG8_SCHED;
;             PG8_LDA(At, 0, 1); PG8_STAGE(PG8_SB(0, 0), b2, voffB); PG8_STAGE(PG8_SB(0, 1), b2 + hstep, voffB); PG8_STAGE(PG8_SA(0, 0), a2, voffA);
.LBB0_1188:
	s_add_u32 s21, s44, 0xfffc0080
	s_addc_u32 s26, s45, -1
	s_add_i32 s28, 0, 0x10000
	s_cmp_eq_u32 s67, 12
	s_cselect_b32 s51, s13, s26
	s_cselect_b32 s50, s63, s21
	v_add_u32_e32 v138, s28, v139
	s_cselect_b32 s49, s19, s66
	s_cselect_b32 s48, s64, s65
	s_add_i32 s21, 0, 0x14000
	ds_read_b128 v[142:145], v138
	ds_read_b128 v[146:149], v138 offset:1024
	ds_read_b128 v[150:153], v138 offset:2048
	ds_read_b128 v[154:157], v138 offset:3072
	v_add_u32_e32 v138, s21, v139
	ds_read_b128 v[162:165], v138
	ds_read_b128 v[166:169], v138 offset:1024
	ds_read_b128 v[170:173], v138 offset:2048
	ds_read_b128 v[174:177], v138 offset:3072
	v_lshl_add_u64 v[158:159], s[44:45], 0, v[134:135]
	s_add_i32 m0, s31, 0xc000
	ds_read_b128 v[178:181], v141
	ds_read_b128 v[204:207], v141 offset:1024
	ds_read_b128 v[208:211], v141 offset:2048
	ds_read_b128 v[212:215], v141 offset:3072
	ds_read_b128 v[216:219], v141 offset:4096
	ds_read_b128 v[220:223], v141 offset:5120
	ds_read_b128 v[224:227], v141 offset:6144
	ds_read_b128 v[228:231], v141 offset:7168
	global_load_lds_dwordx4 v[158:159], off
	v_lshl_add_u64 v[158:159], s[44:45], 0, v[136:137]
	s_add_i32 m0, s31, 0xe000
	s_nop 0
	global_load_lds_dwordx4 v[158:159], off
	s_waitcnt vmcnt(8)
	s_waitcnt lgkmcnt(0)
	s_barrier
	s_setprio 1
	s_waitcnt lgkmcnt(0)
	v_mfma_f32_16x16x32_bf16 v[124:127], v[142:145], v[178:181], v[124:127]
	v_mfma_f32_16x16x32_bf16 v[120:123], v[150:153], v[178:181], v[120:123]
	v_mfma_f32_16x16x32_bf16 v[116:119], v[142:145], v[208:211], v[116:119]
	v_mfma_f32_16x16x32_bf16 v[112:115], v[150:153], v[208:211], v[112:115]
	v_mfma_f32_16x16x32_bf16 v[100:103], v[142:145], v[216:219], v[100:103]
	v_mfma_f32_16x16x32_bf16 v[96:99], v[150:153], v[216:219], v[96:99]
	v_mfma_f32_16x16x32_bf16 v[84:87], v[142:145], v[224:227], v[84:87]
	v_mfma_f32_16x16x32_bf16 v[76:79], v[150:153], v[224:227], v[76:79]
	v_mfma_f32_16x16x32_bf16 v[124:127], v[146:149], v[204:207], v[124:127]
	v_mfma_f32_16x16x32_bf16 v[120:123], v[154:157], v[204:207], v[120:123]
	v_mfma_f32_16x16x32_bf16 v[116:119], v[146:149], v[212:215], v[116:119]
	v_mfma_f32_16x16x32_bf16 v[112:115], v[154:157], v[212:215], v[112:115]
	v_mfma_f32_16x16x32_bf16 v[100:103], v[146:149], v[220:223], v[100:103]
	v_mfma_f32_16x16x32_bf16 v[96:99], v[154:157], v[220:223], v[96:99]
	v_mfma_f32_16x16x32_bf16 v[84:87], v[146:149], v[228:231], v[84:87]
	v_mfma_f32_16x16x32_bf16 v[76:79], v[154:157], v[228:231], v[76:79]
	s_setprio 0
	s_setprio 1
	v_mfma_f32_16x16x32_bf16 v[108:111], v[162:165], v[178:181], v[108:111]
	v_mfma_f32_16x16x32_bf16 v[104:107], v[170:173], v[178:181], v[104:107]
	v_mfma_f32_16x16x32_bf16 v[92:95], v[162:165], v[208:211], v[92:95]
	v_mfma_f32_16x16x32_bf16 v[88:91], v[170:173], v[208:211], v[88:91]
	v_mfma_f32_16x16x32_bf16 v[80:83], v[162:165], v[216:219], v[80:83]
	v_mfma_f32_16x16x32_bf16 v[72:75], v[170:173], v[216:219], v[72:75]
	v_mfma_f32_16x16x32_bf16 v[68:71], v[162:165], v[224:227], v[68:71]
	v_mfma_f32_16x16x32_bf16 v[64:67], v[170:173], v[224:227], v[64:67]
	s_setprio 2
	s_barrier
	v_mfma_f32_16x16x32_bf16 v[108:111], v[166:169], v[204:207], v[108:111]
	v_mfma_f32_16x16x32_bf16 v[104:107], v[174:177], v[204:207], v[104:107]
	v_mfma_f32_16x16x32_bf16 v[92:95], v[166:169], v[212:215], v[92:95]
	v_mfma_f32_16x16x32_bf16 v[88:91], v[174:177], v[212:215], v[88:91]
	v_mfma_f32_16x16x32_bf16 v[80:83], v[166:169], v[220:223], v[80:83]
	v_mfma_f32_16x16x32_bf16 v[72:75], v[174:177], v[220:223], v[72:75]
	v_mfma_f32_16x16x32_bf16 v[68:71], v[166:169], v[228:231], v[68:71]
	v_mfma_f32_16x16x32_bf16 v[64:67], v[174:177], v[228:231], v[64:67]
	s_setprio 0
	s_add_i32 s26, s28, s30
	v_lshl_add_u64 v[158:159], s[48:49], 0, v[160:161]
	s_mov_b32 m0, s26
	ds_read_b128 v[178:181], v141 offset:16384
	ds_read_b128 v[204:207], v141 offset:17408
	ds_read_b128 v[208:211], v141 offset:18432
	ds_read_b128 v[212:215], v141 offset:19456
	ds_read_b128 v[216:219], v141 offset:20480
	ds_read_b128 v[220:223], v141 offset:21504
	ds_read_b128 v[224:227], v141 offset:22528
	ds_read_b128 v[228:231], v141 offset:23552
	global_load_lds_dwordx4 v[158:159], off
	s_add_i32 m0, s26, 0x2000
	s_add_u32 s76, s48, 0x40000
	v_lshl_add_u64 v[232:233], s[48:49], 0, v[128:129]
	s_addc_u32 s77, s49, 0
	s_add_i32 s21, s21, s30
	global_load_lds_dwordx4 v[232:233], off
	v_lshl_add_u64 v[234:235], s[76:77], 0, v[160:161]
	s_mov_b32 m0, s21
	v_lshl_add_u64 v[236:237], s[50:51], 0, v[130:131]
	global_load_lds_dwordx4 v[234:235], off
	v_lshl_add_u64 v[234:235], s[76:77], 0, v[128:129]
	s_add_i32 m0, s21, 0x2000
	s_nop 0
	global_load_lds_dwordx4 v[234:235], off
	v_lshl_add_u64 v[234:235], s[50:51], 0, v[132:133]
	s_mov_b32 m0, s31
	s_nop 0
	global_load_lds_dwordx4 v[234:235], off
	s_mov_b32 m0, s52
	s_nop 0
	global_load_lds_dwordx4 v[236:237], off
	s_waitcnt vmcnt(8)
	s_waitcnt lgkmcnt(0)
	s_barrier
; #define PG8_STAGE(bufoff, gbase, voff) do { _Pragma("unroll") for (int _i = 0; _i < 2; ++_i) \
;         __builtin_amdgcn_global_load_lds((const unsigned*)((const char*)(gbase) + (voff)[_i]), (PG8_LAS unsigned*)(lds + (bufoff) + ldsw + _i * 8192), 16, 0, 0); } while (0)
; #define PG8_LDA(dst, b, h) do { _Pragma("unroll") for (int m = 0; m < 4; ++m) _Pragma("unroll") for (int k = 0; k < 2; ++k) dst[m][k] = *(const PG8_LAS bf16x8*)(lds + PG8_SA(b, h) + aoff + m * 2048 + k * 1024); } while (0)
; #define PG8_LDB(dst, b, h) do { _Pragma("unroll") for (int n = 0; n < 2; ++n) _Pragma("unroll") for (int k = 0; k < 2; ++k) dst[n][k] = *(const PG8_LAS bf16x8*)(lds + PG8_SB(b, h) + boff + n * 2048 + k * 1024); } while (0)
; #define PG8_MMA(ai, bj, At, Bt) do { __builtin_amdgcn_s_setprio(1); _Pragma("unroll") for (int m = 0; m < 4; ++m) _Pragma("unroll") for (int n = 0; n < 2; ++n) _Pragma("unroll") for (int k = 0; k < 2; ++k) \
;         acc[ai][bj][m][n] = __builtin_amdgcn_mfma_f32_16x16x32_bf16(Bt[n][k], At[m][k], acc[ai][bj][m][n], 0, 0, 0); __builtin_amdgcn_s_setprio(0); } while (0)
; #define PG8_WAIT_V(n) asm volatile("s_waitcnt vmcnt(" #n ")" ::: "memory")
; #define PG8_WAIT_L(n) asm volatile("s_waitcnt lgkmcnt(" #n ")" ::: "memory")
; #define PG8_BAR __builtin_amdgcn_s_barrier()
; #define PG8_SCHED __builtin_amdgcn_sched_barrier(0)
; template <class Epi, class Sched, bool ALIGN_EPI = false, bool SP2 = false>
; __device__ __forceinline__ void gemm_phase(PG8_LAS unsigned char* lds, const Gemm g, const Sched& S, const Epi& E, int wv) {
;     ...
;             PG8_WAIT_V(8); PG8_WAIT_L(0); PG8_BAR; PG8_MMA(1, 0, At, B0); PG8_MMA(1, 1, At, B1); PG8_BAR; PG8_SCHED;
;             PG8_LDB(B0, 1, 0); PG8_LDB(B1, 1, 1); PG8_SCHED; PG8_LDA(At, 1, 0); PG8_STAGE(PG8_SA(0, 1), a2 + hstep, voffA);
;             PG8_WAIT_V(8); PG8_WAIT_L(0); PG8_BAR; PG8_MMA(0, 0, At, B0); PG8_MMA(0, 1, At, B1); PG8_BAR; PG8_SCHED;
	s_setprio 1
	s_waitcnt lgkmcnt(0)
	v_mfma_f32_16x16x32_bf16 v[60:63], v[142:145], v[178:181], v[60:63]
	v_mfma_f32_16x16x32_bf16 v[56:59], v[150:153], v[178:181], v[56:59]
	v_mfma_f32_16x16x32_bf16 v[52:55], v[142:145], v[208:211], v[52:55]
	v_mfma_f32_16x16x32_bf16 v[44:47], v[150:153], v[208:211], v[44:47]
	v_mfma_f32_16x16x32_bf16 v[36:39], v[142:145], v[216:219], v[36:39]
	v_mfma_f32_16x16x32_bf16 v[28:31], v[150:153], v[216:219], v[28:31]
	v_mfma_f32_16x16x32_bf16 v[20:23], v[142:145], v[224:227], v[20:23]
	v_mfma_f32_16x16x32_bf16 v[12:15], v[150:153], v[224:227], v[12:15]
	v_mfma_f32_16x16x32_bf16 v[60:63], v[146:149], v[204:207], v[60:63]
	v_mfma_f32_16x16x32_bf16 v[56:59], v[154:157], v[204:207], v[56:59]
	v_mfma_f32_16x16x32_bf16 v[52:55], v[146:149], v[212:215], v[52:55]
	v_mfma_f32_16x16x32_bf16 v[44:47], v[154:157], v[212:215], v[44:47]
	v_mfma_f32_16x16x32_bf16 v[36:39], v[146:149], v[220:223], v[36:39]
	v_mfma_f32_16x16x32_bf16 v[28:31], v[154:157], v[220:223], v[28:31]
	v_mfma_f32_16x16x32_bf16 v[20:23], v[146:149], v[228:231], v[20:23]
	v_mfma_f32_16x16x32_bf16 v[12:15], v[154:157], v[228:231], v[12:15]
	s_setprio 0
	s_setprio 1
	v_mfma_f32_16x16x32_bf16 v[48:51], v[162:165], v[178:181], v[48:51]
	v_mfma_f32_16x16x32_bf16 v[40:43], v[170:173], v[178:181], v[40:43]
	v_mfma_f32_16x16x32_bf16 v[32:35], v[162:165], v[208:211], v[32:35]
	v_mfma_f32_16x16x32_bf16 v[24:27], v[170:173], v[208:211], v[24:27]
	v_mfma_f32_16x16x32_bf16 v[16:19], v[162:165], v[216:219], v[16:19]
	v_mfma_f32_16x16x32_bf16 v[8:11], v[170:173], v[216:219], v[8:11]
	v_mfma_f32_16x16x32_bf16 v[4:7], v[162:165], v[224:227], v[4:7]
	v_mfma_f32_16x16x32_bf16 v[0:3], v[170:173], v[224:227], v[0:3]
	s_setprio 2
	s_barrier
	v_mfma_f32_16x16x32_bf16 v[48:51], v[166:169], v[204:207], v[48:51]
	v_mfma_f32_16x16x32_bf16 v[40:43], v[174:177], v[204:207], v[40:43]
	v_mfma_f32_16x16x32_bf16 v[32:35], v[166:169], v[212:215], v[32:35]
	v_mfma_f32_16x16x32_bf16 v[24:27], v[174:177], v[212:215], v[24:27]
	v_mfma_f32_16x16x32_bf16 v[16:19], v[166:169], v[220:223], v[16:19]
	v_mfma_f32_16x16x32_bf16 v[8:11], v[174:177], v[220:223], v[8:11]
	v_mfma_f32_16x16x32_bf16 v[4:7], v[166:169], v[228:231], v[4:7]
	v_mfma_f32_16x16x32_bf16 v[0:3], v[174:177], v[228:231], v[0:3]
	s_setprio 0
	s_add_i32 s21, 0, 0x18000
	v_add_u32_e32 v138, s21, v139
	s_add_i32 s26, 0, 0x1c000
	ds_read_b128 v[142:145], v138
	ds_read_b128 v[146:149], v138 offset:1024
	ds_read_b128 v[150:153], v138 offset:2048
	ds_read_b128 v[154:157], v138 offset:3072
	v_add_u32_e32 v138, s26, v139
	ds_read_b128 v[162:165], v138
	ds_read_b128 v[166:169], v138 offset:1024
	ds_read_b128 v[170:173], v138 offset:2048
	ds_read_b128 v[174:177], v138 offset:3072
	s_add_u32 s50, s50, 0x40000
	s_addc_u32 s51, s51, 0
	s_mov_b32 m0, s53
	v_lshl_add_u64 v[238:239], s[50:51], 0, v[132:133]
	ds_read_b128 v[178:181], v141 offset:32768
	ds_read_b128 v[204:207], v141 offset:33792
	ds_read_b128 v[208:211], v141 offset:34816
	ds_read_b128 v[212:215], v141 offset:35840
	ds_read_b128 v[216:219], v141 offset:36864
	ds_read_b128 v[220:223], v141 offset:37888
	ds_read_b128 v[224:227], v141 offset:38912
	ds_read_b128 v[228:231], v141 offset:39936
	global_load_lds_dwordx4 v[238:239], off
	v_lshl_add_u64 v[238:239], s[50:51], 0, v[130:131]
	s_mov_b32 m0, s54
	s_nop 0
	global_load_lds_dwordx4 v[238:239], off
	s_waitcnt vmcnt(8)
	s_waitcnt lgkmcnt(0)
	s_barrier
	s_setprio 1
	s_waitcnt lgkmcnt(0)
	v_mfma_f32_16x16x32_bf16 v[124:127], v[142:145], v[178:181], v[124:127]
	v_mfma_f32_16x16x32_bf16 v[120:123], v[150:153], v[178:181], v[120:123]
	v_mfma_f32_16x16x32_bf16 v[116:119], v[142:145], v[208:211], v[116:119]
	v_mfma_f32_16x16x32_bf16 v[112:115], v[150:153], v[208:211], v[112:115]
	v_mfma_f32_16x16x32_bf16 v[100:103], v[142:145], v[216:219], v[100:103]
	v_mfma_f32_16x16x32_bf16 v[96:99], v[150:153], v[216:219], v[96:99]
	v_mfma_f32_16x16x32_bf16 v[84:87], v[142:145], v[224:227], v[84:87]
	v_mfma_f32_16x16x32_bf16 v[76:79], v[150:153], v[224:227], v[76:79]
	v_mfma_f32_16x16x32_bf16 v[124:127], v[146:149], v[204:207], v[124:127]
	v_mfma_f32_16x16x32_bf16 v[120:123], v[154:157], v[204:207], v[120:123]
	v_mfma_f32_16x16x32_bf16 v[116:119], v[146:149], v[212:215], v[116:119]
	v_mfma_f32_16x16x32_bf16 v[112:115], v[154:157], v[212:215], v[112:115]
	v_mfma_f32_16x16x32_bf16 v[100:103], v[146:149], v[220:223], v[100:103]
	v_mfma_f32_16x16x32_bf16 v[96:99], v[154:157], v[220:223], v[96:99]
	v_mfma_f32_16x16x32_bf16 v[84:87], v[146:149], v[228:231], v[84:87]
	v_mfma_f32_16x16x32_bf16 v[76:79], v[154:157], v[228:231], v[76:79]
	s_setprio 0
	s_setprio 1
	v_mfma_f32_16x16x32_bf16 v[108:111], v[162:165], v[178:181], v[108:111]
	v_mfma_f32_16x16x32_bf16 v[104:107], v[170:173], v[178:181], v[104:107]
	v_mfma_f32_16x16x32_bf16 v[92:95], v[162:165], v[208:211], v[92:95]
	v_mfma_f32_16x16x32_bf16 v[88:91], v[170:173], v[208:211], v[88:91]
	v_mfma_f32_16x16x32_bf16 v[80:83], v[162:165], v[216:219], v[80:83]
	v_mfma_f32_16x16x32_bf16 v[72:75], v[170:173], v[216:219], v[72:75]
	v_mfma_f32_16x16x32_bf16 v[68:71], v[162:165], v[224:227], v[68:71]
	v_mfma_f32_16x16x32_bf16 v[64:67], v[170:173], v[224:227], v[64:67]
	s_setprio 2
	s_barrier
; #define PG8_STAGE(bufoff, gbase, voff) do { _Pragma("unroll") for (int _i = 0; _i < 2; ++_i) \
;         __builtin_amdgcn_global_load_lds((const unsigned*)((const char*)(gbase) + (voff)[_i]), (PG8_LAS unsigned*)(lds + (bufoff) + ldsw + _i * 8192), 16, 0, 0); } while (0)
; #define PG8_LDA(dst, b, h) do { _Pragma("unroll") for (int m = 0; m < 4; ++m) _Pragma("unroll") for (int k = 0; k < 2; ++k) dst[m][k] = *(const PG8_LAS bf16x8*)(lds + PG8_SA(b, h) + aoff + m * 2048 + k * 1024); } while (0)
; #define PG8_MMA(ai, bj, At, Bt) do { __builtin_amdgcn_s_setprio(1); _Pragma("unroll") for (int m = 0; m < 4; ++m) _Pragma("unroll") for (int n = 0; n < 2; ++n) _Pragma("unroll") for (int k = 0; k < 2; ++k) \
;         acc[ai][bj][m][n] = __builtin_amdgcn_mfma_f32_16x16x32_bf16(Bt[n][k], At[m][k], acc[ai][bj][m][n], 0, 0, 0); __builtin_amdgcn_s_setprio(0); } while (0)
; #define PG8_WAIT_V(n) asm volatile("s_waitcnt vmcnt(" #n ")" ::: "memory")
; #define PG8_WAIT_L(n) asm volatile("s_waitcnt lgkmcnt(" #n ")" ::: "memory")
; #define PG8_BAR __builtin_amdgcn_s_barrier()
; #define PG8_SCHED __builtin_amdgcn_sched_barrier(0)
; template <class Epi, class Sched, bool ALIGN_EPI = false, bool SP2 = false>
; __device__ __forceinline__ void gemm_phase(PG8_LAS unsigned char* lds, const Gemm g, const Sched& S, const Epi& E, int wv) {
;     ...
;         for (int t = 0; t < nt; t += 2) {
;     ...
;             PG8_WAIT_V(8); PG8_WAIT_L(0); PG8_BAR; PG8_MMA(0, 0, At, B0); PG8_MMA(0, 1, At, B1); PG8_BAR; PG8_SCHED;
;             PG8_LDA(At, 1, 1); PG8_STAGE(PG8_SB(1, 0), b3, voffB); PG8_STAGE(PG8_SB(1, 1), b3 + hstep, voffB); PG8_STAGE(PG8_SA(1, 0), a3, voffA);
;             PG8_WAIT_V(8); PG8_WAIT_L(0); PG8_BAR; PG8_MMA(1, 0, At, B0); PG8_MMA(1, 1, At, B1); PG8_BAR; PG8_SCHED;
	v_mfma_f32_16x16x32_bf16 v[108:111], v[166:169], v[204:207], v[108:111]
	v_mfma_f32_16x16x32_bf16 v[104:107], v[174:177], v[204:207], v[104:107]
	v_mfma_f32_16x16x32_bf16 v[92:95], v[166:169], v[212:215], v[92:95]
	v_mfma_f32_16x16x32_bf16 v[88:91], v[174:177], v[212:215], v[88:91]
	v_mfma_f32_16x16x32_bf16 v[80:83], v[166:169], v[220:223], v[80:83]
	v_mfma_f32_16x16x32_bf16 v[72:75], v[174:177], v[220:223], v[72:75]
	v_mfma_f32_16x16x32_bf16 v[68:71], v[166:169], v[228:231], v[68:71]
	v_mfma_f32_16x16x32_bf16 v[64:67], v[174:177], v[228:231], v[64:67]
	s_setprio 0
	s_add_i32 s21, s21, s30
	v_lshl_add_u64 v[158:159], v[158:159], 0, s[74:75]
	s_mov_b32 m0, s21
	ds_read_b128 v[178:181], v141 offset:49152
	ds_read_b128 v[204:207], v141 offset:50176
	ds_read_b128 v[208:211], v141 offset:51200
	ds_read_b128 v[212:215], v141 offset:52224
	ds_read_b128 v[216:219], v141 offset:53248
	ds_read_b128 v[220:223], v141 offset:54272
	ds_read_b128 v[224:227], v141 offset:55296
	ds_read_b128 v[228:231], v141 offset:56320
	global_load_lds_dwordx4 v[158:159], off
	s_add_i32 m0, s21, 0x2000
	s_add_u32 s48, s48, 0x40080
	v_lshl_add_u64 v[158:159], v[232:233], 0, s[74:75]
	s_addc_u32 s49, s49, 0
	s_add_i32 s21, s26, s30
	global_load_lds_dwordx4 v[158:159], off
	v_lshl_add_u64 v[158:159], s[48:49], 0, v[160:161]
	s_mov_b32 m0, s21
	s_nop 0
	global_load_lds_dwordx4 v[158:159], off
	v_lshl_add_u64 v[158:159], s[48:49], 0, v[128:129]
	s_add_i32 m0, s21, 0x2000
	s_nop 0
	global_load_lds_dwordx4 v[158:159], off
	v_lshl_add_u64 v[158:159], v[234:235], 0, s[74:75]
	s_mov_b32 m0, s60
	s_nop 0
	global_load_lds_dwordx4 v[158:159], off
	v_lshl_add_u64 v[158:159], v[236:237], 0, s[74:75]
	s_mov_b32 m0, s61
	s_nop 0
	global_load_lds_dwordx4 v[158:159], off
	s_waitcnt vmcnt(8)
	s_waitcnt lgkmcnt(0)
	s_barrier
	s_setprio 1
	s_waitcnt lgkmcnt(0)
	v_mfma_f32_16x16x32_bf16 v[60:63], v[142:145], v[178:181], v[60:63]
	v_mfma_f32_16x16x32_bf16 v[56:59], v[150:153], v[178:181], v[56:59]
	v_mfma_f32_16x16x32_bf16 v[52:55], v[142:145], v[208:211], v[52:55]
	v_mfma_f32_16x16x32_bf16 v[44:47], v[150:153], v[208:211], v[44:47]
	v_mfma_f32_16x16x32_bf16 v[36:39], v[142:145], v[216:219], v[36:39]
	v_mfma_f32_16x16x32_bf16 v[28:31], v[150:153], v[216:219], v[28:31]
	v_mfma_f32_16x16x32_bf16 v[20:23], v[142:145], v[224:227], v[20:23]
	v_mfma_f32_16x16x32_bf16 v[12:15], v[150:153], v[224:227], v[12:15]
	v_mfma_f32_16x16x32_bf16 v[60:63], v[146:149], v[204:207], v[60:63]
	v_mfma_f32_16x16x32_bf16 v[56:59], v[154:157], v[204:207], v[56:59]
	v_mfma_f32_16x16x32_bf16 v[52:55], v[146:149], v[212:215], v[52:55]
	v_mfma_f32_16x16x32_bf16 v[44:47], v[154:157], v[212:215], v[44:47]
	v_mfma_f32_16x16x32_bf16 v[36:39], v[146:149], v[220:223], v[36:39]
	v_mfma_f32_16x16x32_bf16 v[28:31], v[154:157], v[220:223], v[28:31]
	v_mfma_f32_16x16x32_bf16 v[20:23], v[146:149], v[228:231], v[20:23]
	v_mfma_f32_16x16x32_bf16 v[12:15], v[154:157], v[228:231], v[12:15]
	s_setprio 0
	s_setprio 1
	v_mfma_f32_16x16x32_bf16 v[48:51], v[162:165], v[178:181], v[48:51]
	v_mfma_f32_16x16x32_bf16 v[40:43], v[170:173], v[178:181], v[40:43]
	v_mfma_f32_16x16x32_bf16 v[32:35], v[162:165], v[208:211], v[32:35]
	v_mfma_f32_16x16x32_bf16 v[24:27], v[170:173], v[208:211], v[24:27]
	v_mfma_f32_16x16x32_bf16 v[16:19], v[162:165], v[216:219], v[16:19]
	v_mfma_f32_16x16x32_bf16 v[8:11], v[170:173], v[216:219], v[8:11]
	v_mfma_f32_16x16x32_bf16 v[4:7], v[162:165], v[224:227], v[4:7]
	v_mfma_f32_16x16x32_bf16 v[0:3], v[170:173], v[224:227], v[0:3]
	s_setprio 2
	s_barrier
	v_mfma_f32_16x16x32_bf16 v[48:51], v[166:169], v[204:207], v[48:51]
	v_mfma_f32_16x16x32_bf16 v[40:43], v[174:177], v[204:207], v[40:43]
	v_mfma_f32_16x16x32_bf16 v[32:35], v[166:169], v[212:215], v[32:35]
	v_mfma_f32_16x16x32_bf16 v[24:27], v[174:177], v[212:215], v[24:27]
	v_mfma_f32_16x16x32_bf16 v[16:19], v[166:169], v[220:223], v[16:19]
	v_mfma_f32_16x16x32_bf16 v[8:11], v[174:177], v[220:223], v[8:11]
	v_mfma_f32_16x16x32_bf16 v[4:7], v[166:169], v[228:231], v[4:7]
	v_mfma_f32_16x16x32_bf16 v[0:3], v[174:177], v[228:231], v[0:3]
	s_setprio 0
	s_add_i32 s67, s67, 2
	s_add_u32 s44, s44, 0x100
	s_addc_u32 s45, s45, 0
	s_add_u32 s65, s65, 0x100
	s_addc_u32 s66, s66, 0
	s_cmp_gt_u32 s67, 13
	s_cbranch_scc0 .LBB0_1188
	s_and_b64 vcc, exec, s[10:11]
	s_cbranch_vccz .LBB0_1191
	s_barrier

; #define PG8_STAGE(bufoff, gbase, voff) do { _Pragma("unroll") for (int _i = 0; _i < 2; ++_i) \
;         __builtin_amdgcn_global_load_lds((const unsigned*)((const char*)(gbase) + (voff)[_i]), (PG8_LAS unsigned*)(lds + (bufoff) + ldsw + _i * 8192), 16, 0, 0); } while (0)
; #define PG8_LDA(dst, b, h) do { _Pragma("unroll") for (int m = 0; m < 4; ++m) _Pragma("unroll") for (int k = 0; k < 2; ++k) dst[m][k] = *(const PG8_LAS bf16x8*)(lds + PG8_SA(b, h) + aoff + m * 2048 + k * 1024); } while (0)
; #define PG8_LDB(dst, b, h) do { _Pragma("unroll") for (int n = 0; n < 2; ++n) _Pragma("unroll") for (int k = 0; k < 2; ++k) dst[n][k] = *(const PG8_LAS bf16x8*)(lds + PG8_SB(b, h) + boff + n * 2048 + k * 1024); } while (0)
; #define PG8_MMA(ai, bj, At, Bt) do { __builtin_amdgcn_s_setprio(1); _Pragma("unroll") for (int m = 0; m < 4; ++m) _Pragma("unroll") for (int n = 0; n < 2; ++n) _Pragma("unroll") for (int k = 0; k < 2; ++k) \
;         acc[ai][bj][m][n] = __builtin_amdgcn_mfma_f32_16x16x32_bf16(Bt[n][k], At[m][k], acc[ai][bj][m][n], 0, 0, 0); __builtin_amdgcn_s_setprio(0); } while (0)
; #define PG8_WAIT_V(n) asm volatile("s_waitcnt vmcnt(" #n ")" ::: "memory")
; #define PG8_WAIT_L(n) asm volatile("s_waitcnt lgkmcnt(" #n ")" ::: "memory")
; #define PG8_BAR __builtin_amdgcn_s_barrier()
; #define PG8_SCHED __builtin_amdgcn_sched_barrier(0)
; template <class Epi, class Sched, bool ALIGN_EPI = false, bool SP2 = false>
; __device__ __forceinline__ void gemm_phase(PG8_LAS unsigned char* lds, const Gemm g, const Sched& S, const Epi& E, int wv) {
;     ...
;             const bool last = (t == nt - 2);
;             const char* a1 = cA + (size_t)(t + 1) * kstep;
;             const char* a2 = last ? nA : cA + (size_t)(t + 2) * kstep; const char* b2 = last ? nB : cB + (size_t)(t + 2) * kstep;
;             const char* a3 = a2 + kstep; const char* b3 = b2 + kstep;
;             if (last && has_next) S.a_ready(nxt);
;             if constexpr (SP2) {
;             PG8_LDB(B0, 0, 0); PG8_LDB(B1, 0, 1); PG8_SCHED; PG8_LDA(At, 0, 0); PG8_STAGE(PG8_SA(1, 1), a1 + hstep, voffA);
;             PG8_WAIT_V(8); PG8_WAIT_L(0); PG8_BAR; PG8_MMA(0, 0, At, B0); PG8_MMA(0, 1, At, B1); PG8_BAR; PG8_SCHED;
;             PG8_LDA(At, 0, 1); PG8_STAGE(PG8_SB(0, 0), b2, voffB); PG8_STAGE(PG8_SB(0, 1), b2 + hstep, voffB); PG8_STAGE(PG8_SA(0, 0), a2, voffA);
.LBB0_1956:
	s_add_u32 s21, s4, 0xfffc0080
	s_addc_u32 s26, s5, -1
	s_add_i32 s28, 0, 0x10000
	s_cmp_eq_u32 s67, 12
	s_cselect_b32 s51, s19, s26
	s_cselect_b32 s50, s63, s21
	s_cselect_b32 s49, s35, s66
	s_cselect_b32 s48, s64, s65
	s_add_i32 s21, 0, 0x14000
	v_add_u32_e32 v140, s28, v168
	v_add_u32_e32 v170, s21, v168
	ds_read_b128 v[128:131], v140
	ds_read_b128 v[132:135], v140 offset:1024
	ds_read_b128 v[136:139], v140 offset:2048
	ds_read_b128 v[140:143], v140 offset:3072
	ds_read_b128 v[144:147], v170
	ds_read_b128 v[148:151], v170 offset:1024
	ds_read_b128 v[164:167], v170 offset:2048
	ds_read_b128 v[170:173], v170 offset:3072
	v_lshl_add_u64 v[228:229], s[4:5], 0, v[158:159]
	s_add_i32 m0, s31, 0xc000
	ds_read_b128 v[174:177], v169
	ds_read_b128 v[178:181], v169 offset:1024
	ds_read_b128 v[204:207], v169 offset:2048
	ds_read_b128 v[208:211], v169 offset:3072
	ds_read_b128 v[212:215], v169 offset:4096
	ds_read_b128 v[216:219], v169 offset:5120
	ds_read_b128 v[220:223], v169 offset:6144
	ds_read_b128 v[224:227], v169 offset:7168
	global_load_lds_dwordx4 v[228:229], off
	v_lshl_add_u64 v[228:229], s[4:5], 0, v[162:163]
	s_add_i32 m0, s31, 0xe000
	s_nop 0
	global_load_lds_dwordx4 v[228:229], off
	s_waitcnt vmcnt(8)
	s_waitcnt lgkmcnt(0)
	s_barrier
	s_setprio 1
	s_waitcnt lgkmcnt(0)
	v_mfma_f32_16x16x32_bf16 v[124:127], v[128:131], v[174:177], v[124:127]
	v_mfma_f32_16x16x32_bf16 v[120:123], v[136:139], v[174:177], v[120:123]
	v_mfma_f32_16x16x32_bf16 v[108:111], v[128:131], v[204:207], v[108:111]
	v_mfma_f32_16x16x32_bf16 v[104:107], v[136:139], v[204:207], v[104:107]
	v_mfma_f32_16x16x32_bf16 v[92:95], v[128:131], v[212:215], v[92:95]
	v_mfma_f32_16x16x32_bf16 v[88:91], v[136:139], v[212:215], v[88:91]
	v_mfma_f32_16x16x32_bf16 v[76:79], v[128:131], v[220:223], v[76:79]
	v_mfma_f32_16x16x32_bf16 v[72:75], v[136:139], v[220:223], v[72:75]
	v_mfma_f32_16x16x32_bf16 v[124:127], v[132:135], v[178:181], v[124:127]
	v_mfma_f32_16x16x32_bf16 v[120:123], v[140:143], v[178:181], v[120:123]
	v_mfma_f32_16x16x32_bf16 v[108:111], v[132:135], v[208:211], v[108:111]
	v_mfma_f32_16x16x32_bf16 v[104:107], v[140:143], v[208:211], v[104:107]
	v_mfma_f32_16x16x32_bf16 v[92:95], v[132:135], v[216:219], v[92:95]
	v_mfma_f32_16x16x32_bf16 v[88:91], v[140:143], v[216:219], v[88:91]
	v_mfma_f32_16x16x32_bf16 v[76:79], v[132:135], v[224:227], v[76:79]
	v_mfma_f32_16x16x32_bf16 v[72:75], v[140:143], v[224:227], v[72:75]
	s_setprio 0
	s_setprio 1
	v_mfma_f32_16x16x32_bf16 v[116:119], v[144:147], v[174:177], v[116:119]
	v_mfma_f32_16x16x32_bf16 v[112:115], v[164:167], v[174:177], v[112:115]
	v_mfma_f32_16x16x32_bf16 v[100:103], v[144:147], v[204:207], v[100:103]
	v_mfma_f32_16x16x32_bf16 v[96:99], v[164:167], v[204:207], v[96:99]
	v_mfma_f32_16x16x32_bf16 v[84:87], v[144:147], v[212:215], v[84:87]
	v_mfma_f32_16x16x32_bf16 v[80:83], v[164:167], v[212:215], v[80:83]
	v_mfma_f32_16x16x32_bf16 v[68:71], v[144:147], v[220:223], v[68:71]
	v_mfma_f32_16x16x32_bf16 v[64:67], v[164:167], v[220:223], v[64:67]
	s_setprio 2
	s_barrier
	v_mfma_f32_16x16x32_bf16 v[116:119], v[148:151], v[178:181], v[116:119]
	v_mfma_f32_16x16x32_bf16 v[112:115], v[170:173], v[178:181], v[112:115]
	v_mfma_f32_16x16x32_bf16 v[100:103], v[148:151], v[208:211], v[100:103]
	v_mfma_f32_16x16x32_bf16 v[96:99], v[170:173], v[208:211], v[96:99]
	v_mfma_f32_16x16x32_bf16 v[84:87], v[148:151], v[216:219], v[84:87]
	v_mfma_f32_16x16x32_bf16 v[80:83], v[170:173], v[216:219], v[80:83]
	v_mfma_f32_16x16x32_bf16 v[68:71], v[148:151], v[224:227], v[68:71]
	v_mfma_f32_16x16x32_bf16 v[64:67], v[170:173], v[224:227], v[64:67]
	s_setprio 0
	s_add_i32 s26, s28, s30
	v_lshl_add_u64 v[228:229], s[48:49], 0, v[160:161]
	s_mov_b32 m0, s26
	ds_read_b128 v[174:177], v169 offset:16384
	ds_read_b128 v[178:181], v169 offset:17408
	ds_read_b128 v[204:207], v169 offset:18432
	ds_read_b128 v[208:211], v169 offset:19456
	ds_read_b128 v[212:215], v169 offset:20480
	ds_read_b128 v[216:219], v169 offset:21504
	ds_read_b128 v[220:223], v169 offset:22528
	ds_read_b128 v[224:227], v169 offset:23552
	global_load_lds_dwordx4 v[228:229], off
	s_add_i32 m0, s26, 0x2000
	s_add_u32 s76, s48, 0x40000
	v_lshl_add_u64 v[230:231], s[48:49], 0, v[152:153]
	s_addc_u32 s77, s49, 0
	s_add_i32 s21, s21, s30
	global_load_lds_dwordx4 v[230:231], off
	v_lshl_add_u64 v[232:233], s[76:77], 0, v[160:161]
	s_mov_b32 m0, s21
	v_lshl_add_u64 v[234:235], s[50:51], 0, v[154:155]
	global_load_lds_dwordx4 v[232:233], off
	v_lshl_add_u64 v[232:233], s[76:77], 0, v[152:153]
	s_add_i32 m0, s21, 0x2000
	s_nop 0
	global_load_lds_dwordx4 v[232:233], off
	v_lshl_add_u64 v[232:233], s[50:51], 0, v[156:157]
	s_mov_b32 m0, s31
	s_nop 0
	global_load_lds_dwordx4 v[232:233], off
	s_mov_b32 m0, s52
	s_nop 0
	global_load_lds_dwordx4 v[234:235], off
	s_waitcnt vmcnt(8)
	s_waitcnt lgkmcnt(0)
	s_barrier
; #define PG8_STAGE(bufoff, gbase, voff) do { _Pragma("unroll") for (int _i = 0; _i < 2; ++_i) \
;         __builtin_amdgcn_global_load_lds((const unsigned*)((const char*)(gbase) + (voff)[_i]), (PG8_LAS unsigned*)(lds + (bufoff) + ldsw + _i * 8192), 16, 0, 0); } while (0)
; #define PG8_LDA(dst, b, h) do { _Pragma("unroll") for (int m = 0; m < 4; ++m) _Pragma("unroll") for (int k = 0; k < 2; ++k) dst[m][k] = *(const PG8_LAS bf16x8*)(lds + PG8_SA(b, h) + aoff + m * 2048 + k * 1024); } while (0)
; #define PG8_LDB(dst, b, h) do { _Pragma("unroll") for (int n = 0; n < 2; ++n) _Pragma("unroll") for (int k = 0; k < 2; ++k) dst[n][k] = *(const PG8_LAS bf16x8*)(lds + PG8_SB(b, h) + boff + n * 2048 + k * 1024); } while (0)
; #define PG8_MMA(ai, bj, At, Bt) do { __builtin_amdgcn_s_setprio(1); _Pragma("unroll") for (int m = 0; m < 4; ++m) _Pragma("unroll") for (int n = 0; n < 2; ++n) _Pragma("unroll") for (int k = 0; k < 2; ++k) \
;         acc[ai][bj][m][n] = __builtin_amdgcn_mfma_f32_16x16x32_bf16(Bt[n][k], At[m][k], acc[ai][bj][m][n], 0, 0, 0); __builtin_amdgcn_s_setprio(0); } while (0)
; #define PG8_WAIT_V(n) asm volatile("s_waitcnt vmcnt(" #n ")" ::: "memory")
; #define PG8_WAIT_L(n) asm volatile("s_waitcnt lgkmcnt(" #n ")" ::: "memory")
; #define PG8_BAR __builtin_amdgcn_s_barrier()
; #define PG8_SCHED __builtin_amdgcn_sched_barrier(0)
; template <class Epi, class Sched, bool ALIGN_EPI = false, bool SP2 = false>
; __device__ __forceinline__ void gemm_phase(PG8_LAS unsigned char* lds, const Gemm g, const Sched& S, const Epi& E, int wv) {
;     ...
;             PG8_WAIT_V(8); PG8_WAIT_L(0); PG8_BAR; PG8_MMA(1, 0, At, B0); PG8_MMA(1, 1, At, B1); PG8_BAR; PG8_SCHED;
;             PG8_LDB(B0, 1, 0); PG8_LDB(B1, 1, 1); PG8_SCHED; PG8_LDA(At, 1, 0); PG8_STAGE(PG8_SA(0, 1), a2 + hstep, voffA);
;             PG8_WAIT_V(8); PG8_WAIT_L(0); PG8_BAR; PG8_MMA(0, 0, At, B0); PG8_MMA(0, 1, At, B1); PG8_BAR; PG8_SCHED;
	s_setprio 1
	s_waitcnt lgkmcnt(0)
	v_mfma_f32_16x16x32_bf16 v[60:63], v[128:131], v[174:177], v[60:63]
	v_mfma_f32_16x16x32_bf16 v[56:59], v[136:139], v[174:177], v[56:59]
	v_mfma_f32_16x16x32_bf16 v[44:47], v[128:131], v[204:207], v[44:47]
	v_mfma_f32_16x16x32_bf16 v[40:43], v[136:139], v[204:207], v[40:43]
	v_mfma_f32_16x16x32_bf16 v[28:31], v[128:131], v[212:215], v[28:31]
	v_mfma_f32_16x16x32_bf16 v[24:27], v[136:139], v[212:215], v[24:27]
	v_mfma_f32_16x16x32_bf16 v[12:15], v[128:131], v[220:223], v[12:15]
	v_mfma_f32_16x16x32_bf16 v[8:11], v[136:139], v[220:223], v[8:11]
	v_mfma_f32_16x16x32_bf16 v[60:63], v[132:135], v[178:181], v[60:63]
	v_mfma_f32_16x16x32_bf16 v[56:59], v[140:143], v[178:181], v[56:59]
	v_mfma_f32_16x16x32_bf16 v[44:47], v[132:135], v[208:211], v[44:47]
	v_mfma_f32_16x16x32_bf16 v[40:43], v[140:143], v[208:211], v[40:43]
	v_mfma_f32_16x16x32_bf16 v[28:31], v[132:135], v[216:219], v[28:31]
	v_mfma_f32_16x16x32_bf16 v[24:27], v[140:143], v[216:219], v[24:27]
	v_mfma_f32_16x16x32_bf16 v[12:15], v[132:135], v[224:227], v[12:15]
	v_mfma_f32_16x16x32_bf16 v[8:11], v[140:143], v[224:227], v[8:11]
	s_setprio 0
	s_setprio 1
	v_mfma_f32_16x16x32_bf16 v[52:55], v[144:147], v[174:177], v[52:55]
	v_mfma_f32_16x16x32_bf16 v[48:51], v[164:167], v[174:177], v[48:51]
	v_mfma_f32_16x16x32_bf16 v[36:39], v[144:147], v[204:207], v[36:39]
	v_mfma_f32_16x16x32_bf16 v[32:35], v[164:167], v[204:207], v[32:35]
	v_mfma_f32_16x16x32_bf16 v[20:23], v[144:147], v[212:215], v[20:23]
	v_mfma_f32_16x16x32_bf16 v[16:19], v[164:167], v[212:215], v[16:19]
	v_mfma_f32_16x16x32_bf16 v[4:7], v[144:147], v[220:223], v[4:7]
	v_mfma_f32_16x16x32_bf16 v[0:3], v[164:167], v[220:223], v[0:3]
	s_setprio 2
	s_barrier
	v_mfma_f32_16x16x32_bf16 v[52:55], v[148:151], v[178:181], v[52:55]
	v_mfma_f32_16x16x32_bf16 v[48:51], v[170:173], v[178:181], v[48:51]
	v_mfma_f32_16x16x32_bf16 v[36:39], v[148:151], v[208:211], v[36:39]
	v_mfma_f32_16x16x32_bf16 v[32:35], v[170:173], v[208:211], v[32:35]
	v_mfma_f32_16x16x32_bf16 v[20:23], v[148:151], v[216:219], v[20:23]
	v_mfma_f32_16x16x32_bf16 v[16:19], v[170:173], v[216:219], v[16:19]
	v_mfma_f32_16x16x32_bf16 v[4:7], v[148:151], v[224:227], v[4:7]
	v_mfma_f32_16x16x32_bf16 v[0:3], v[170:173], v[224:227], v[0:3]
	s_setprio 0
	s_add_i32 s21, 0, 0x18000
	s_add_i32 s26, 0, 0x1c000
	v_add_u32_e32 v140, s21, v168
	v_add_u32_e32 v170, s26, v168
	ds_read_b128 v[128:131], v140
	ds_read_b128 v[132:135], v140 offset:1024
	ds_read_b128 v[136:139], v140 offset:2048
	ds_read_b128 v[140:143], v140 offset:3072
	ds_read_b128 v[144:147], v170
	ds_read_b128 v[148:151], v170 offset:1024
	ds_read_b128 v[164:167], v170 offset:2048
	ds_read_b128 v[170:173], v170 offset:3072
	s_add_u32 s50, s50, 0x40000
	s_addc_u32 s51, s51, 0
	s_mov_b32 m0, s53
	v_lshl_add_u64 v[236:237], s[50:51], 0, v[156:157]
	ds_read_b128 v[174:177], v169 offset:32768
	ds_read_b128 v[178:181], v169 offset:33792
	ds_read_b128 v[204:207], v169 offset:34816
	ds_read_b128 v[208:211], v169 offset:35840
	ds_read_b128 v[212:215], v169 offset:36864
	ds_read_b128 v[216:219], v169 offset:37888
	ds_read_b128 v[220:223], v169 offset:38912
	ds_read_b128 v[224:227], v169 offset:39936
	global_load_lds_dwordx4 v[236:237], off
	v_lshl_add_u64 v[236:237], s[50:51], 0, v[154:155]
	s_mov_b32 m0, s54
	s_nop 0
	global_load_lds_dwordx4 v[236:237], off
	s_waitcnt vmcnt(8)
	s_waitcnt lgkmcnt(0)
	s_barrier
	s_setprio 1
	s_waitcnt lgkmcnt(0)
	v_mfma_f32_16x16x32_bf16 v[124:127], v[128:131], v[174:177], v[124:127]
	v_mfma_f32_16x16x32_bf16 v[120:123], v[136:139], v[174:177], v[120:123]
	v_mfma_f32_16x16x32_bf16 v[108:111], v[128:131], v[204:207], v[108:111]
	v_mfma_f32_16x16x32_bf16 v[104:107], v[136:139], v[204:207], v[104:107]
	v_mfma_f32_16x16x32_bf16 v[92:95], v[128:131], v[212:215], v[92:95]
	v_mfma_f32_16x16x32_bf16 v[88:91], v[136:139], v[212:215], v[88:91]
	v_mfma_f32_16x16x32_bf16 v[76:79], v[128:131], v[220:223], v[76:79]
	v_mfma_f32_16x16x32_bf16 v[72:75], v[136:139], v[220:223], v[72:75]
	v_mfma_f32_16x16x32_bf16 v[124:127], v[132:135], v[178:181], v[124:127]
	v_mfma_f32_16x16x32_bf16 v[120:123], v[140:143], v[178:181], v[120:123]
	v_mfma_f32_16x16x32_bf16 v[108:111], v[132:135], v[208:211], v[108:111]
	v_mfma_f32_16x16x32_bf16 v[104:107], v[140:143], v[208:211], v[104:107]
	v_mfma_f32_16x16x32_bf16 v[92:95], v[132:135], v[216:219], v[92:95]
	v_mfma_f32_16x16x32_bf16 v[88:91], v[140:143], v[216:219], v[88:91]
	v_mfma_f32_16x16x32_bf16 v[76:79], v[132:135], v[224:227], v[76:79]
	v_mfma_f32_16x16x32_bf16 v[72:75], v[140:143], v[224:227], v[72:75]
	s_setprio 0
	s_setprio 1
	v_mfma_f32_16x16x32_bf16 v[116:119], v[144:147], v[174:177], v[116:119]
	v_mfma_f32_16x16x32_bf16 v[112:115], v[164:167], v[174:177], v[112:115]
	v_mfma_f32_16x16x32_bf16 v[100:103], v[144:147], v[204:207], v[100:103]
	v_mfma_f32_16x16x32_bf16 v[96:99], v[164:167], v[204:207], v[96:99]
	v_mfma_f32_16x16x32_bf16 v[84:87], v[144:147], v[212:215], v[84:87]
	v_mfma_f32_16x16x32_bf16 v[80:83], v[164:167], v[212:215], v[80:83]
	v_mfma_f32_16x16x32_bf16 v[68:71], v[144:147], v[220:223], v[68:71]
	v_mfma_f32_16x16x32_bf16 v[64:67], v[164:167], v[220:223], v[64:67]
	s_setprio 2
	s_barrier
; #define PG8_STAGE(bufoff, gbase, voff) do { _Pragma("unroll") for (int _i = 0; _i < 2; ++_i) \
;         __builtin_amdgcn_global_load_lds((const unsigned*)((const char*)(gbase) + (voff)[_i]), (PG8_LAS unsigned*)(lds + (bufoff) + ldsw + _i * 8192), 16, 0, 0); } while (0)
; #define PG8_LDA(dst, b, h) do { _Pragma("unroll") for (int m = 0; m < 4; ++m) _Pragma("unroll") for (int k = 0; k < 2; ++k) dst[m][k] = *(const PG8_LAS bf16x8*)(lds + PG8_SA(b, h) + aoff + m * 2048 + k * 1024); } while (0)
; #define PG8_MMA(ai, bj, At, Bt) do { __builtin_amdgcn_s_setprio(1); _Pragma("unroll") for (int m = 0; m < 4; ++m) _Pragma("unroll") for (int n = 0; n < 2; ++n) _Pragma("unroll") for (int k = 0; k < 2; ++k) \
;         acc[ai][bj][m][n] = __builtin_amdgcn_mfma_f32_16x16x32_bf16(Bt[n][k], At[m][k], acc[ai][bj][m][n], 0, 0, 0); __builtin_amdgcn_s_setprio(0); } while (0)
; #define PG8_WAIT_V(n) asm volatile("s_waitcnt vmcnt(" #n ")" ::: "memory")
; #define PG8_WAIT_L(n) asm volatile("s_waitcnt lgkmcnt(" #n ")" ::: "memory")
; #define PG8_BAR __builtin_amdgcn_s_barrier()
; #define PG8_SCHED __builtin_amdgcn_sched_barrier(0)
; template <class Epi, class Sched, bool ALIGN_EPI = false, bool SP2 = false>
; __device__ __forceinline__ void gemm_phase(PG8_LAS unsigned char* lds, const Gemm g, const Sched& S, const Epi& E, int wv) {
;     ...
;         for (int t = 0; t < nt; t += 2) {
;     ...
;             PG8_WAIT_V(8); PG8_WAIT_L(0); PG8_BAR; PG8_MMA(0, 0, At, B0); PG8_MMA(0, 1, At, B1); PG8_BAR; PG8_SCHED;
;             PG8_LDA(At, 1, 1); PG8_STAGE(PG8_SB(1, 0), b3, voffB); PG8_STAGE(PG8_SB(1, 1), b3 + hstep, voffB); PG8_STAGE(PG8_SA(1, 0), a3, voffA);
;             PG8_WAIT_V(8); PG8_WAIT_L(0); PG8_BAR; PG8_MMA(1, 0, At, B0); PG8_MMA(1, 1, At, B1); PG8_BAR; PG8_SCHED;
	v_mfma_f32_16x16x32_bf16 v[116:119], v[148:151], v[178:181], v[116:119]
	v_mfma_f32_16x16x32_bf16 v[112:115], v[170:173], v[178:181], v[112:115]
	v_mfma_f32_16x16x32_bf16 v[100:103], v[148:151], v[208:211], v[100:103]
	v_mfma_f32_16x16x32_bf16 v[96:99], v[170:173], v[208:211], v[96:99]
	v_mfma_f32_16x16x32_bf16 v[84:87], v[148:151], v[216:219], v[84:87]
	v_mfma_f32_16x16x32_bf16 v[80:83], v[170:173], v[216:219], v[80:83]
	v_mfma_f32_16x16x32_bf16 v[68:71], v[148:151], v[224:227], v[68:71]
	v_mfma_f32_16x16x32_bf16 v[64:67], v[170:173], v[224:227], v[64:67]
	s_setprio 0
	s_add_i32 s21, s21, s30
	v_lshl_add_u64 v[228:229], v[228:229], 0, s[74:75]
	s_mov_b32 m0, s21
	ds_read_b128 v[174:177], v169 offset:49152
	ds_read_b128 v[178:181], v169 offset:50176
	ds_read_b128 v[204:207], v169 offset:51200
	ds_read_b128 v[208:211], v169 offset:52224
	ds_read_b128 v[212:215], v169 offset:53248
	ds_read_b128 v[216:219], v169 offset:54272
	ds_read_b128 v[220:223], v169 offset:55296
	ds_read_b128 v[224:227], v169 offset:56320
	global_load_lds_dwordx4 v[228:229], off
	s_add_i32 m0, s21, 0x2000
	s_add_u32 s48, s48, 0x40080
	v_lshl_add_u64 v[228:229], v[230:231], 0, s[74:75]
	s_addc_u32 s49, s49, 0
	s_add_i32 s21, s26, s30
	global_load_lds_dwordx4 v[228:229], off
	v_lshl_add_u64 v[228:229], s[48:49], 0, v[160:161]
	s_mov_b32 m0, s21
	s_nop 0
	global_load_lds_dwordx4 v[228:229], off
	v_lshl_add_u64 v[228:229], s[48:49], 0, v[152:153]
	s_add_i32 m0, s21, 0x2000
	s_nop 0
	global_load_lds_dwordx4 v[228:229], off
	v_lshl_add_u64 v[228:229], v[232:233], 0, s[74:75]
	s_mov_b32 m0, s60
	s_nop 0
	global_load_lds_dwordx4 v[228:229], off
	v_lshl_add_u64 v[228:229], v[234:235], 0, s[74:75]
	s_mov_b32 m0, s61
	s_nop 0
	global_load_lds_dwordx4 v[228:229], off
	s_waitcnt vmcnt(8)
	s_waitcnt lgkmcnt(0)
	s_barrier
	s_setprio 1
	s_waitcnt lgkmcnt(0)
	v_mfma_f32_16x16x32_bf16 v[60:63], v[128:131], v[174:177], v[60:63]
	v_mfma_f32_16x16x32_bf16 v[56:59], v[136:139], v[174:177], v[56:59]
	v_mfma_f32_16x16x32_bf16 v[44:47], v[128:131], v[204:207], v[44:47]
	v_mfma_f32_16x16x32_bf16 v[40:43], v[136:139], v[204:207], v[40:43]
	v_mfma_f32_16x16x32_bf16 v[28:31], v[128:131], v[212:215], v[28:31]
	v_mfma_f32_16x16x32_bf16 v[24:27], v[136:139], v[212:215], v[24:27]
	v_mfma_f32_16x16x32_bf16 v[12:15], v[128:131], v[220:223], v[12:15]
	v_mfma_f32_16x16x32_bf16 v[8:11], v[136:139], v[220:223], v[8:11]
	v_mfma_f32_16x16x32_bf16 v[60:63], v[132:135], v[178:181], v[60:63]
	v_mfma_f32_16x16x32_bf16 v[56:59], v[140:143], v[178:181], v[56:59]
	v_mfma_f32_16x16x32_bf16 v[44:47], v[132:135], v[208:211], v[44:47]
	v_mfma_f32_16x16x32_bf16 v[40:43], v[140:143], v[208:211], v[40:43]
	v_mfma_f32_16x16x32_bf16 v[28:31], v[132:135], v[216:219], v[28:31]
	v_mfma_f32_16x16x32_bf16 v[24:27], v[140:143], v[216:219], v[24:27]
	v_mfma_f32_16x16x32_bf16 v[12:15], v[132:135], v[224:227], v[12:15]
	v_mfma_f32_16x16x32_bf16 v[8:11], v[140:143], v[224:227], v[8:11]
	s_setprio 0
	s_setprio 1
	v_mfma_f32_16x16x32_bf16 v[52:55], v[144:147], v[174:177], v[52:55]
	v_mfma_f32_16x16x32_bf16 v[48:51], v[164:167], v[174:177], v[48:51]
	v_mfma_f32_16x16x32_bf16 v[36:39], v[144:147], v[204:207], v[36:39]
	v_mfma_f32_16x16x32_bf16 v[32:35], v[164:167], v[204:207], v[32:35]
	v_mfma_f32_16x16x32_bf16 v[20:23], v[144:147], v[212:215], v[20:23]
	v_mfma_f32_16x16x32_bf16 v[16:19], v[164:167], v[212:215], v[16:19]
	v_mfma_f32_16x16x32_bf16 v[4:7], v[144:147], v[220:223], v[4:7]
	v_mfma_f32_16x16x32_bf16 v[0:3], v[164:167], v[220:223], v[0:3]
	s_setprio 2
	s_barrier
	v_mfma_f32_16x16x32_bf16 v[52:55], v[148:151], v[178:181], v[52:55]
	v_mfma_f32_16x16x32_bf16 v[48:51], v[170:173], v[178:181], v[48:51]
	v_mfma_f32_16x16x32_bf16 v[36:39], v[148:151], v[208:211], v[36:39]
	v_mfma_f32_16x16x32_bf16 v[32:35], v[170:173], v[208:211], v[32:35]
	v_mfma_f32_16x16x32_bf16 v[20:23], v[148:151], v[216:219], v[20:23]
	v_mfma_f32_16x16x32_bf16 v[16:19], v[170:173], v[216:219], v[16:19]
	v_mfma_f32_16x16x32_bf16 v[4:7], v[148:151], v[224:227], v[4:7]
	v_mfma_f32_16x16x32_bf16 v[0:3], v[170:173], v[224:227], v[0:3]
	s_setprio 0
	s_add_i32 s67, s67, 2
	s_add_u32 s4, s4, 0x100
	s_addc_u32 s5, s5, 0
	s_add_u32 s65, s65, 0x100
	s_addc_u32 s66, s66, 0
	s_cmp_gt_u32 s67, 13
	s_cbranch_scc0 .LBB0_1956
	s_and_b64 vcc, exec, s[12:13]
	s_cbranch_vccz .LBB0_1959
	s_barrier

; #define PG8_STAGE(bufoff, gbase, voff) do { _Pragma("unroll") for (int _i = 0; _i < 2; ++_i) \
;         __builtin_amdgcn_global_load_lds((const unsigned*)((const char*)(gbase) + (voff)[_i]), (PG8_LAS unsigned*)(lds + (bufoff) + ldsw + _i * 8192), 16, 0, 0); } while (0)
; #define PG8_LDA(dst, b, h) do { _Pragma("unroll") for (int m = 0; m < 4; ++m) _Pragma("unroll") for (int k = 0; k < 2; ++k) dst[m][k] = *(const PG8_LAS bf16x8*)(lds + PG8_SA(b, h) + aoff + m * 2048 + k * 1024); } while (0)
; #define PG8_LDB(dst, b, h) do { _Pragma("unroll") for (int n = 0; n < 2; ++n) _Pragma("unroll") for (int k = 0; k < 2; ++k) dst[n][k] = *(const PG8_LAS bf16x8*)(lds + PG8_SB(b, h) + boff + n * 2048 + k * 1024); } while (0)
; #define PG8_MMA(ai, bj, At, Bt) do { __builtin_amdgcn_s_setprio(1); _Pragma("unroll") for (int m = 0; m < 4; ++m) _Pragma("unroll") for (int n = 0; n < 2; ++n) _Pragma("unroll") for (int k = 0; k < 2; ++k) \
;         acc[ai][bj][m][n] = __builtin_amdgcn_mfma_f32_16x16x32_bf16(Bt[n][k], At[m][k], acc[ai][bj][m][n], 0, 0, 0); __builtin_amdgcn_s_setprio(0); } while (0)
; #define PG8_WAIT_V(n) asm volatile("s_waitcnt vmcnt(" #n ")" ::: "memory")
; #define PG8_WAIT_L(n) asm volatile("s_waitcnt lgkmcnt(" #n ")" ::: "memory")
; #define PG8_BAR __builtin_amdgcn_s_barrier()
; #define PG8_SCHED __builtin_amdgcn_sched_barrier(0)
; template <class Epi, class Sched, bool ALIGN_EPI = false, bool SP2 = false>
; __device__ __forceinline__ void gemm_phase(PG8_LAS unsigned char* lds, const Gemm g, const Sched& S, const Epi& E, int wv) {
;     ...
;             const bool last = (t == nt - 2);
;             const char* a1 = cA + (size_t)(t + 1) * kstep;
;             const char* a2 = last ? nA : cA + (size_t)(t + 2) * kstep; const char* b2 = last ? nB : cB + (size_t)(t + 2) * kstep;
;             const char* a3 = a2 + kstep; const char* b3 = b2 + kstep;
;             if (last && has_next) S.a_ready(nxt);
;             if constexpr (SP2) {
;             PG8_LDB(B0, 0, 0); PG8_LDB(B1, 0, 1); PG8_SCHED; PG8_LDA(At, 0, 0); PG8_STAGE(PG8_SA(1, 1), a1 + hstep, voffA);
;             PG8_WAIT_V(8); PG8_WAIT_L(0); PG8_BAR; PG8_MMA(0, 0, At, B0); PG8_MMA(0, 1, At, B1); PG8_BAR; PG8_SCHED;
;             PG8_LDA(At, 0, 1); PG8_STAGE(PG8_SB(0, 0), b2, voffB); PG8_STAGE(PG8_SB(0, 1), b2 + hstep, voffB); PG8_STAGE(PG8_SA(0, 0), a2, voffA);
.LBB0_2108:
	s_add_u32 s21, s44, 0xfffc0080
	s_addc_u32 s26, s45, -1
	s_add_i32 s28, 0, 0x10000
	s_cmp_eq_u32 s67, 12
	s_cselect_b32 s51, s13, s26
	s_cselect_b32 s50, s63, s21
	v_add_u32_e32 v138, s28, v141
	s_cselect_b32 s49, s19, s66
	s_cselect_b32 s48, s64, s65
	s_add_i32 s21, 0, 0x14000
	ds_read_b128 v[144:147], v138
	ds_read_b128 v[148:151], v138 offset:1024
	ds_read_b128 v[152:155], v138 offset:2048
	ds_read_b128 v[156:159], v138 offset:3072
	v_add_u32_e32 v138, s21, v141
	ds_read_b128 v[162:165], v138
	ds_read_b128 v[166:169], v138 offset:1024
	ds_read_b128 v[170:173], v138 offset:2048
	ds_read_b128 v[174:177], v138 offset:3072
	v_lshl_add_u64 v[138:139], s[44:45], 0, v[134:135]
	s_add_i32 m0, s31, 0xc000
	ds_read_b128 v[178:181], v143
	ds_read_b128 v[204:207], v143 offset:1024
	ds_read_b128 v[208:211], v143 offset:2048
	ds_read_b128 v[212:215], v143 offset:3072
	ds_read_b128 v[216:219], v143 offset:4096
	ds_read_b128 v[220:223], v143 offset:5120
	ds_read_b128 v[224:227], v143 offset:6144
	ds_read_b128 v[228:231], v143 offset:7168
	global_load_lds_dwordx4 v[138:139], off
	v_lshl_add_u64 v[138:139], s[44:45], 0, v[136:137]
	s_add_i32 m0, s31, 0xe000
	s_nop 0
	global_load_lds_dwordx4 v[138:139], off
	s_waitcnt vmcnt(8)
	s_waitcnt lgkmcnt(0)
	s_barrier
	s_setprio 1
	s_waitcnt lgkmcnt(0)
	v_mfma_f32_16x16x32_bf16 v[124:127], v[144:147], v[178:181], v[124:127]
	v_mfma_f32_16x16x32_bf16 v[120:123], v[152:155], v[178:181], v[120:123]
	v_mfma_f32_16x16x32_bf16 v[108:111], v[144:147], v[208:211], v[108:111]
	v_mfma_f32_16x16x32_bf16 v[104:107], v[152:155], v[208:211], v[104:107]
	v_mfma_f32_16x16x32_bf16 v[92:95], v[144:147], v[216:219], v[92:95]
	v_mfma_f32_16x16x32_bf16 v[88:91], v[152:155], v[216:219], v[88:91]
	v_mfma_f32_16x16x32_bf16 v[76:79], v[144:147], v[224:227], v[76:79]
	v_mfma_f32_16x16x32_bf16 v[72:75], v[152:155], v[224:227], v[72:75]
	v_mfma_f32_16x16x32_bf16 v[124:127], v[148:151], v[204:207], v[124:127]
	v_mfma_f32_16x16x32_bf16 v[120:123], v[156:159], v[204:207], v[120:123]
	v_mfma_f32_16x16x32_bf16 v[108:111], v[148:151], v[212:215], v[108:111]
	v_mfma_f32_16x16x32_bf16 v[104:107], v[156:159], v[212:215], v[104:107]
	v_mfma_f32_16x16x32_bf16 v[92:95], v[148:151], v[220:223], v[92:95]
	v_mfma_f32_16x16x32_bf16 v[88:91], v[156:159], v[220:223], v[88:91]
	v_mfma_f32_16x16x32_bf16 v[76:79], v[148:151], v[228:231], v[76:79]
	v_mfma_f32_16x16x32_bf16 v[72:75], v[156:159], v[228:231], v[72:75]
	s_setprio 0
	s_setprio 1
	v_mfma_f32_16x16x32_bf16 v[116:119], v[162:165], v[178:181], v[116:119]
	v_mfma_f32_16x16x32_bf16 v[112:115], v[170:173], v[178:181], v[112:115]
	v_mfma_f32_16x16x32_bf16 v[100:103], v[162:165], v[208:211], v[100:103]
	v_mfma_f32_16x16x32_bf16 v[96:99], v[170:173], v[208:211], v[96:99]
	v_mfma_f32_16x16x32_bf16 v[84:87], v[162:165], v[216:219], v[84:87]
	v_mfma_f32_16x16x32_bf16 v[80:83], v[170:173], v[216:219], v[80:83]
	v_mfma_f32_16x16x32_bf16 v[68:71], v[162:165], v[224:227], v[68:71]
	v_mfma_f32_16x16x32_bf16 v[64:67], v[170:173], v[224:227], v[64:67]
	s_setprio 2
	s_barrier
	v_mfma_f32_16x16x32_bf16 v[116:119], v[166:169], v[204:207], v[116:119]
	v_mfma_f32_16x16x32_bf16 v[112:115], v[174:177], v[204:207], v[112:115]
	v_mfma_f32_16x16x32_bf16 v[100:103], v[166:169], v[212:215], v[100:103]
	v_mfma_f32_16x16x32_bf16 v[96:99], v[174:177], v[212:215], v[96:99]
	v_mfma_f32_16x16x32_bf16 v[84:87], v[166:169], v[220:223], v[84:87]
	v_mfma_f32_16x16x32_bf16 v[80:83], v[174:177], v[220:223], v[80:83]
	v_mfma_f32_16x16x32_bf16 v[68:71], v[166:169], v[228:231], v[68:71]
	v_mfma_f32_16x16x32_bf16 v[64:67], v[174:177], v[228:231], v[64:67]
	s_setprio 0
	s_add_i32 s26, s28, s30
	v_lshl_add_u64 v[138:139], s[48:49], 0, v[160:161]
	s_mov_b32 m0, s26
	ds_read_b128 v[178:181], v143 offset:16384
	ds_read_b128 v[204:207], v143 offset:17408
	ds_read_b128 v[208:211], v143 offset:18432
	ds_read_b128 v[212:215], v143 offset:19456
	ds_read_b128 v[216:219], v143 offset:20480
	ds_read_b128 v[220:223], v143 offset:21504
	ds_read_b128 v[224:227], v143 offset:22528
	ds_read_b128 v[228:231], v143 offset:23552
	global_load_lds_dwordx4 v[138:139], off
	s_add_i32 m0, s26, 0x2000
	s_add_u32 s76, s48, 0x40000
	v_lshl_add_u64 v[232:233], s[48:49], 0, v[128:129]
	s_addc_u32 s77, s49, 0
	s_add_i32 s21, s21, s30
	global_load_lds_dwordx4 v[232:233], off
	v_lshl_add_u64 v[234:235], s[76:77], 0, v[160:161]
	s_mov_b32 m0, s21
	v_lshl_add_u64 v[236:237], s[50:51], 0, v[130:131]
	global_load_lds_dwordx4 v[234:235], off
	v_lshl_add_u64 v[234:235], s[76:77], 0, v[128:129]
	s_add_i32 m0, s21, 0x2000
	s_nop 0
	global_load_lds_dwordx4 v[234:235], off
	v_lshl_add_u64 v[234:235], s[50:51], 0, v[132:133]
	s_mov_b32 m0, s31
	s_nop 0
	global_load_lds_dwordx4 v[234:235], off
	s_mov_b32 m0, s52
	s_nop 0
	global_load_lds_dwordx4 v[236:237], off
	s_waitcnt vmcnt(8)
	s_waitcnt lgkmcnt(0)
	s_barrier
; #define PG8_STAGE(bufoff, gbase, voff) do { _Pragma("unroll") for (int _i = 0; _i < 2; ++_i) \
;         __builtin_amdgcn_global_load_lds((const unsigned*)((const char*)(gbase) + (voff)[_i]), (PG8_LAS unsigned*)(lds + (bufoff) + ldsw + _i * 8192), 16, 0, 0); } while (0)
; #define PG8_LDA(dst, b, h) do { _Pragma("unroll") for (int m = 0; m < 4; ++m) _Pragma("unroll") for (int k = 0; k < 2; ++k) dst[m][k] = *(const PG8_LAS bf16x8*)(lds + PG8_SA(b, h) + aoff + m * 2048 + k * 1024); } while (0)
; #define PG8_LDB(dst, b, h) do { _Pragma("unroll") for (int n = 0; n < 2; ++n) _Pragma("unroll") for (int k = 0; k < 2; ++k) dst[n][k] = *(const PG8_LAS bf16x8*)(lds + PG8_SB(b, h) + boff + n * 2048 + k * 1024); } while (0)
; #define PG8_MMA(ai, bj, At, Bt) do { __builtin_amdgcn_s_setprio(1); _Pragma("unroll") for (int m = 0; m < 4; ++m) _Pragma("unroll") for (int n = 0; n < 2; ++n) _Pragma("unroll") for (int k = 0; k < 2; ++k) \
;         acc[ai][bj][m][n] = __builtin_amdgcn_mfma_f32_16x16x32_bf16(Bt[n][k], At[m][k], acc[ai][bj][m][n], 0, 0, 0); __builtin_amdgcn_s_setprio(0); } while (0)
; #define PG8_WAIT_V(n) asm volatile("s_waitcnt vmcnt(" #n ")" ::: "memory")
; #define PG8_WAIT_L(n) asm volatile("s_waitcnt lgkmcnt(" #n ")" ::: "memory")
; #define PG8_BAR __builtin_amdgcn_s_barrier()
; #define PG8_SCHED __builtin_amdgcn_sched_barrier(0)
; template <class Epi, class Sched, bool ALIGN_EPI = false, bool SP2 = false>
; __device__ __forceinline__ void gemm_phase(PG8_LAS unsigned char* lds, const Gemm g, const Sched& S, const Epi& E, int wv) {
;     ...
;             PG8_WAIT_V(8); PG8_WAIT_L(0); PG8_BAR; PG8_MMA(1, 0, At, B0); PG8_MMA(1, 1, At, B1); PG8_BAR; PG8_SCHED;
;             PG8_LDB(B0, 1, 0); PG8_LDB(B1, 1, 1); PG8_SCHED; PG8_LDA(At, 1, 0); PG8_STAGE(PG8_SA(0, 1), a2 + hstep, voffA);
;             PG8_WAIT_V(8); PG8_WAIT_L(0); PG8_BAR; PG8_MMA(0, 0, At, B0); PG8_MMA(0, 1, At, B1); PG8_BAR; PG8_SCHED;
	s_setprio 1
	s_waitcnt lgkmcnt(0)
	v_mfma_f32_16x16x32_bf16 v[60:63], v[144:147], v[178:181], v[60:63]
	v_mfma_f32_16x16x32_bf16 v[56:59], v[152:155], v[178:181], v[56:59]
	v_mfma_f32_16x16x32_bf16 v[44:47], v[144:147], v[208:211], v[44:47]
	v_mfma_f32_16x16x32_bf16 v[40:43], v[152:155], v[208:211], v[40:43]
	v_mfma_f32_16x16x32_bf16 v[28:31], v[144:147], v[216:219], v[28:31]
	v_mfma_f32_16x16x32_bf16 v[24:27], v[152:155], v[216:219], v[24:27]
	v_mfma_f32_16x16x32_bf16 v[12:15], v[144:147], v[224:227], v[12:15]
	v_mfma_f32_16x16x32_bf16 v[8:11], v[152:155], v[224:227], v[8:11]
	v_mfma_f32_16x16x32_bf16 v[60:63], v[148:151], v[204:207], v[60:63]
	v_mfma_f32_16x16x32_bf16 v[56:59], v[156:159], v[204:207], v[56:59]
	v_mfma_f32_16x16x32_bf16 v[44:47], v[148:151], v[212:215], v[44:47]
	v_mfma_f32_16x16x32_bf16 v[40:43], v[156:159], v[212:215], v[40:43]
	v_mfma_f32_16x16x32_bf16 v[28:31], v[148:151], v[220:223], v[28:31]
	v_mfma_f32_16x16x32_bf16 v[24:27], v[156:159], v[220:223], v[24:27]
	v_mfma_f32_16x16x32_bf16 v[12:15], v[148:151], v[228:231], v[12:15]
	v_mfma_f32_16x16x32_bf16 v[8:11], v[156:159], v[228:231], v[8:11]
	s_setprio 0
	s_setprio 1
	v_mfma_f32_16x16x32_bf16 v[52:55], v[162:165], v[178:181], v[52:55]
	v_mfma_f32_16x16x32_bf16 v[48:51], v[170:173], v[178:181], v[48:51]
	v_mfma_f32_16x16x32_bf16 v[36:39], v[162:165], v[208:211], v[36:39]
	v_mfma_f32_16x16x32_bf16 v[32:35], v[170:173], v[208:211], v[32:35]
	v_mfma_f32_16x16x32_bf16 v[20:23], v[162:165], v[216:219], v[20:23]
	v_mfma_f32_16x16x32_bf16 v[16:19], v[170:173], v[216:219], v[16:19]
	v_mfma_f32_16x16x32_bf16 v[4:7], v[162:165], v[224:227], v[4:7]
	v_mfma_f32_16x16x32_bf16 v[0:3], v[170:173], v[224:227], v[0:3]
	s_setprio 2
	s_barrier
	v_mfma_f32_16x16x32_bf16 v[52:55], v[166:169], v[204:207], v[52:55]
	v_mfma_f32_16x16x32_bf16 v[48:51], v[174:177], v[204:207], v[48:51]
	v_mfma_f32_16x16x32_bf16 v[36:39], v[166:169], v[212:215], v[36:39]
	v_mfma_f32_16x16x32_bf16 v[32:35], v[174:177], v[212:215], v[32:35]
	v_mfma_f32_16x16x32_bf16 v[20:23], v[166:169], v[220:223], v[20:23]
	v_mfma_f32_16x16x32_bf16 v[16:19], v[174:177], v[220:223], v[16:19]
	v_mfma_f32_16x16x32_bf16 v[4:7], v[166:169], v[228:231], v[4:7]
	v_mfma_f32_16x16x32_bf16 v[0:3], v[174:177], v[228:231], v[0:3]
	s_setprio 0
	s_add_i32 s21, 0, 0x18000
	v_add_u32_e32 v140, s21, v141
	s_add_i32 s26, 0, 0x1c000
	ds_read_b128 v[144:147], v140
	ds_read_b128 v[148:151], v140 offset:1024
	ds_read_b128 v[152:155], v140 offset:2048
	ds_read_b128 v[156:159], v140 offset:3072
	v_add_u32_e32 v140, s26, v141
	ds_read_b128 v[162:165], v140
	ds_read_b128 v[166:169], v140 offset:1024
	ds_read_b128 v[170:173], v140 offset:2048
	ds_read_b128 v[174:177], v140 offset:3072
	s_add_u32 s50, s50, 0x40000
	s_addc_u32 s51, s51, 0
	s_mov_b32 m0, s53
	v_lshl_add_u64 v[238:239], s[50:51], 0, v[132:133]
	ds_read_b128 v[178:181], v143 offset:32768
	ds_read_b128 v[204:207], v143 offset:33792
	ds_read_b128 v[208:211], v143 offset:34816
	ds_read_b128 v[212:215], v143 offset:35840
	ds_read_b128 v[216:219], v143 offset:36864
	ds_read_b128 v[220:223], v143 offset:37888
	ds_read_b128 v[224:227], v143 offset:38912
	ds_read_b128 v[228:231], v143 offset:39936
	global_load_lds_dwordx4 v[238:239], off
	v_lshl_add_u64 v[238:239], s[50:51], 0, v[130:131]
	s_mov_b32 m0, s54
	s_nop 0
	global_load_lds_dwordx4 v[238:239], off
	s_waitcnt vmcnt(8)
	s_waitcnt lgkmcnt(0)
	s_barrier
	s_setprio 1
	s_waitcnt lgkmcnt(0)
	v_mfma_f32_16x16x32_bf16 v[124:127], v[144:147], v[178:181], v[124:127]
	v_mfma_f32_16x16x32_bf16 v[120:123], v[152:155], v[178:181], v[120:123]
	v_mfma_f32_16x16x32_bf16 v[108:111], v[144:147], v[208:211], v[108:111]
	v_mfma_f32_16x16x32_bf16 v[104:107], v[152:155], v[208:211], v[104:107]
	v_mfma_f32_16x16x32_bf16 v[92:95], v[144:147], v[216:219], v[92:95]
	v_mfma_f32_16x16x32_bf16 v[88:91], v[152:155], v[216:219], v[88:91]
	v_mfma_f32_16x16x32_bf16 v[76:79], v[144:147], v[224:227], v[76:79]
	v_mfma_f32_16x16x32_bf16 v[72:75], v[152:155], v[224:227], v[72:75]
	v_mfma_f32_16x16x32_bf16 v[124:127], v[148:151], v[204:207], v[124:127]
	v_mfma_f32_16x16x32_bf16 v[120:123], v[156:159], v[204:207], v[120:123]
	v_mfma_f32_16x16x32_bf16 v[108:111], v[148:151], v[212:215], v[108:111]
	v_mfma_f32_16x16x32_bf16 v[104:107], v[156:159], v[212:215], v[104:107]
	v_mfma_f32_16x16x32_bf16 v[92:95], v[148:151], v[220:223], v[92:95]
	v_mfma_f32_16x16x32_bf16 v[88:91], v[156:159], v[220:223], v[88:91]
	v_mfma_f32_16x16x32_bf16 v[76:79], v[148:151], v[228:231], v[76:79]
	v_mfma_f32_16x16x32_bf16 v[72:75], v[156:159], v[228:231], v[72:75]
	s_setprio 0
	s_setprio 1
	v_mfma_f32_16x16x32_bf16 v[116:119], v[162:165], v[178:181], v[116:119]
	v_mfma_f32_16x16x32_bf16 v[112:115], v[170:173], v[178:181], v[112:115]
	v_mfma_f32_16x16x32_bf16 v[100:103], v[162:165], v[208:211], v[100:103]
	v_mfma_f32_16x16x32_bf16 v[96:99], v[170:173], v[208:211], v[96:99]
	v_mfma_f32_16x16x32_bf16 v[84:87], v[162:165], v[216:219], v[84:87]
	v_mfma_f32_16x16x32_bf16 v[80:83], v[170:173], v[216:219], v[80:83]
	v_mfma_f32_16x16x32_bf16 v[68:71], v[162:165], v[224:227], v[68:71]
	v_mfma_f32_16x16x32_bf16 v[64:67], v[170:173], v[224:227], v[64:67]
	s_setprio 2
	s_barrier
; #define PG8_STAGE(bufoff, gbase, voff) do { _Pragma("unroll") for (int _i = 0; _i < 2; ++_i) \
;         __builtin_amdgcn_global_load_lds((const unsigned*)((const char*)(gbase) + (voff)[_i]), (PG8_LAS unsigned*)(lds + (bufoff) + ldsw + _i * 8192), 16, 0, 0); } while (0)
; #define PG8_LDA(dst, b, h) do { _Pragma("unroll") for (int m = 0; m < 4; ++m) _Pragma("unroll") for (int k = 0; k < 2; ++k) dst[m][k] = *(const PG8_LAS bf16x8*)(lds + PG8_SA(b, h) + aoff + m * 2048 + k * 1024); } while (0)
; #define PG8_MMA(ai, bj, At, Bt) do { __builtin_amdgcn_s_setprio(1); _Pragma("unroll") for (int m = 0; m < 4; ++m) _Pragma("unroll") for (int n = 0; n < 2; ++n) _Pragma("unroll") for (int k = 0; k < 2; ++k) \
;         acc[ai][bj][m][n] = __builtin_amdgcn_mfma_f32_16x16x32_bf16(Bt[n][k], At[m][k], acc[ai][bj][m][n], 0, 0, 0); __builtin_amdgcn_s_setprio(0); } while (0)
; #define PG8_WAIT_V(n) asm volatile("s_waitcnt vmcnt(" #n ")" ::: "memory")
; #define PG8_WAIT_L(n) asm volatile("s_waitcnt lgkmcnt(" #n ")" ::: "memory")
; #define PG8_BAR __builtin_amdgcn_s_barrier()
; #define PG8_SCHED __builtin_amdgcn_sched_barrier(0)
; template <class Epi, class Sched, bool ALIGN_EPI = false, bool SP2 = false>
; __device__ __forceinline__ void gemm_phase(PG8_LAS unsigned char* lds, const Gemm g, const Sched& S, const Epi& E, int wv) {
;     ...
;         for (int t = 0; t < nt; t += 2) {
;     ...
;             PG8_WAIT_V(8); PG8_WAIT_L(0); PG8_BAR; PG8_MMA(0, 0, At, B0); PG8_MMA(0, 1, At, B1); PG8_BAR; PG8_SCHED;
;             PG8_LDA(At, 1, 1); PG8_STAGE(PG8_SB(1, 0), b3, voffB); PG8_STAGE(PG8_SB(1, 1), b3 + hstep, voffB); PG8_STAGE(PG8_SA(1, 0), a3, voffA);
;             PG8_WAIT_V(8); PG8_WAIT_L(0); PG8_BAR; PG8_MMA(1, 0, At, B0); PG8_MMA(1, 1, At, B1); PG8_BAR; PG8_SCHED;
	v_mfma_f32_16x16x32_bf16 v[116:119], v[166:169], v[204:207], v[116:119]
	v_mfma_f32_16x16x32_bf16 v[112:115], v[174:177], v[204:207], v[112:115]
	v_mfma_f32_16x16x32_bf16 v[100:103], v[166:169], v[212:215], v[100:103]
	v_mfma_f32_16x16x32_bf16 v[96:99], v[174:177], v[212:215], v[96:99]
	v_mfma_f32_16x16x32_bf16 v[84:87], v[166:169], v[220:223], v[84:87]
	v_mfma_f32_16x16x32_bf16 v[80:83], v[174:177], v[220:223], v[80:83]
	v_mfma_f32_16x16x32_bf16 v[68:71], v[166:169], v[228:231], v[68:71]
	v_mfma_f32_16x16x32_bf16 v[64:67], v[174:177], v[228:231], v[64:67]
	s_setprio 0
	s_add_i32 s21, s21, s30
	v_lshl_add_u64 v[138:139], v[138:139], 0, s[74:75]
	s_mov_b32 m0, s21
	ds_read_b128 v[178:181], v143 offset:49152
	ds_read_b128 v[204:207], v143 offset:50176
	ds_read_b128 v[208:211], v143 offset:51200
	ds_read_b128 v[212:215], v143 offset:52224
	ds_read_b128 v[216:219], v143 offset:53248
	ds_read_b128 v[220:223], v143 offset:54272
	ds_read_b128 v[224:227], v143 offset:55296
	ds_read_b128 v[228:231], v143 offset:56320
	global_load_lds_dwordx4 v[138:139], off
	s_add_i32 m0, s21, 0x2000
	s_add_u32 s48, s48, 0x40080
	v_lshl_add_u64 v[138:139], v[232:233], 0, s[74:75]
	s_addc_u32 s49, s49, 0
	s_add_i32 s21, s26, s30
	global_load_lds_dwordx4 v[138:139], off
	v_lshl_add_u64 v[138:139], s[48:49], 0, v[160:161]
	s_mov_b32 m0, s21
	s_nop 0
	global_load_lds_dwordx4 v[138:139], off
	v_lshl_add_u64 v[138:139], s[48:49], 0, v[128:129]
	s_add_i32 m0, s21, 0x2000
	s_nop 0
	global_load_lds_dwordx4 v[138:139], off
	v_lshl_add_u64 v[138:139], v[234:235], 0, s[74:75]
	s_mov_b32 m0, s60
	s_nop 0
	global_load_lds_dwordx4 v[138:139], off
	v_lshl_add_u64 v[138:139], v[236:237], 0, s[74:75]
	s_mov_b32 m0, s61
	s_nop 0
	global_load_lds_dwordx4 v[138:139], off
	s_waitcnt vmcnt(8)
	s_waitcnt lgkmcnt(0)
	s_barrier
	s_setprio 1
	s_waitcnt lgkmcnt(0)
	v_mfma_f32_16x16x32_bf16 v[60:63], v[144:147], v[178:181], v[60:63]
	v_mfma_f32_16x16x32_bf16 v[56:59], v[152:155], v[178:181], v[56:59]
	v_mfma_f32_16x16x32_bf16 v[44:47], v[144:147], v[208:211], v[44:47]
	v_mfma_f32_16x16x32_bf16 v[40:43], v[152:155], v[208:211], v[40:43]
	v_mfma_f32_16x16x32_bf16 v[28:31], v[144:147], v[216:219], v[28:31]
	v_mfma_f32_16x16x32_bf16 v[24:27], v[152:155], v[216:219], v[24:27]
	v_mfma_f32_16x16x32_bf16 v[12:15], v[144:147], v[224:227], v[12:15]
	v_mfma_f32_16x16x32_bf16 v[8:11], v[152:155], v[224:227], v[8:11]
	v_mfma_f32_16x16x32_bf16 v[60:63], v[148:151], v[204:207], v[60:63]
	v_mfma_f32_16x16x32_bf16 v[56:59], v[156:159], v[204:207], v[56:59]
	v_mfma_f32_16x16x32_bf16 v[44:47], v[148:151], v[212:215], v[44:47]
	v_mfma_f32_16x16x32_bf16 v[40:43], v[156:159], v[212:215], v[40:43]
	v_mfma_f32_16x16x32_bf16 v[28:31], v[148:151], v[220:223], v[28:31]
	v_mfma_f32_16x16x32_bf16 v[24:27], v[156:159], v[220:223], v[24:27]
	v_mfma_f32_16x16x32_bf16 v[12:15], v[148:151], v[228:231], v[12:15]
	v_mfma_f32_16x16x32_bf16 v[8:11], v[156:159], v[228:231], v[8:11]
	s_setprio 0
	s_setprio 1
	v_mfma_f32_16x16x32_bf16 v[52:55], v[162:165], v[178:181], v[52:55]
	v_mfma_f32_16x16x32_bf16 v[48:51], v[170:173], v[178:181], v[48:51]
	v_mfma_f32_16x16x32_bf16 v[36:39], v[162:165], v[208:211], v[36:39]
	v_mfma_f32_16x16x32_bf16 v[32:35], v[170:173], v[208:211], v[32:35]
	v_mfma_f32_16x16x32_bf16 v[20:23], v[162:165], v[216:219], v[20:23]
	v_mfma_f32_16x16x32_bf16 v[16:19], v[170:173], v[216:219], v[16:19]
	v_mfma_f32_16x16x32_bf16 v[4:7], v[162:165], v[224:227], v[4:7]
	v_mfma_f32_16x16x32_bf16 v[0:3], v[170:173], v[224:227], v[0:3]
	s_setprio 2
	s_barrier
	v_mfma_f32_16x16x32_bf16 v[52:55], v[166:169], v[204:207], v[52:55]
	v_mfma_f32_16x16x32_bf16 v[48:51], v[174:177], v[204:207], v[48:51]
	v_mfma_f32_16x16x32_bf16 v[36:39], v[166:169], v[212:215], v[36:39]
	v_mfma_f32_16x16x32_bf16 v[32:35], v[174:177], v[212:215], v[32:35]
	v_mfma_f32_16x16x32_bf16 v[20:23], v[166:169], v[220:223], v[20:23]
	v_mfma_f32_16x16x32_bf16 v[16:19], v[174:177], v[220:223], v[16:19]
	v_mfma_f32_16x16x32_bf16 v[4:7], v[166:169], v[228:231], v[4:7]
	v_mfma_f32_16x16x32_bf16 v[0:3], v[174:177], v[228:231], v[0:3]
	s_setprio 0
	s_add_i32 s67, s67, 2
	s_add_u32 s44, s44, 0x100
	s_addc_u32 s45, s45, 0
	s_add_u32 s65, s65, 0x100
	s_addc_u32 s66, s66, 0
	s_cmp_gt_u32 s67, 13
	s_cbranch_scc0 .LBB0_2108
	s_and_b64 vcc, exec, s[10:11]
	s_cbranch_vccz .LBB0_2111
	s_barrier

; #define PG8_STAGE(bufoff, gbase, voff) do { _Pragma("unroll") for (int _i = 0; _i < 2; ++_i) \
;         __builtin_amdgcn_global_load_lds((const unsigned*)((const char*)(gbase) + (voff)[_i]), (PG8_LAS unsigned*)(lds + (bufoff) + ldsw + _i * 8192), 16, 0, 0); } while (0)
; #define PG8_LDA(dst, b, h) do { _Pragma("unroll") for (int m = 0; m < 4; ++m) _Pragma("unroll") for (int k = 0; k < 2; ++k) dst[m][k] = *(const PG8_LAS bf16x8*)(lds + PG8_SA(b, h) + aoff + m * 2048 + k * 1024); } while (0)
; #define PG8_LDB(dst, b, h) do { _Pragma("unroll") for (int n = 0; n < 2; ++n) _Pragma("unroll") for (int k = 0; k < 2; ++k) dst[n][k] = *(const PG8_LAS bf16x8*)(lds + PG8_SB(b, h) + boff + n * 2048 + k * 1024); } while (0)
; #define PG8_MMA(ai, bj, At, Bt) do { __builtin_amdgcn_s_setprio(1); _Pragma("unroll") for (int m = 0; m < 4; ++m) _Pragma("unroll") for (int n = 0; n < 2; ++n) _Pragma("unroll") for (int k = 0; k < 2; ++k) \
;         acc[ai][bj][m][n] = __builtin_amdgcn_mfma_f32_16x16x32_bf16(Bt[n][k], At[m][k], acc[ai][bj][m][n], 0, 0, 0); __builtin_amdgcn_s_setprio(0); } while (0)
; #define PG8_WAIT_V(n) asm volatile("s_waitcnt vmcnt(" #n ")" ::: "memory")
; #define PG8_WAIT_L(n) asm volatile("s_waitcnt lgkmcnt(" #n ")" ::: "memory")
; #define PG8_BAR __builtin_amdgcn_s_barrier()
; #define PG8_SCHED __builtin_amdgcn_sched_barrier(0)
; template <class Epi, class Sched, bool ALIGN_EPI = false, bool SP2 = false>
; __device__ __forceinline__ void gemm_phase(PG8_LAS unsigned char* lds, const Gemm g, const Sched& S, const Epi& E, int wv) {
;     ...
;             const bool last = (t == nt - 2);
;             const char* a1 = cA + (size_t)(t + 1) * kstep;
;             const char* a2 = last ? nA : cA + (size_t)(t + 2) * kstep; const char* b2 = last ? nB : cB + (size_t)(t + 2) * kstep;
;             const char* a3 = a2 + kstep; const char* b3 = b2 + kstep;
;             if (last && has_next) S.a_ready(nxt);
;             if constexpr (SP2) {
;             PG8_LDB(B0, 0, 0); PG8_LDB(B1, 0, 1); PG8_SCHED; PG8_LDA(At, 0, 0); PG8_STAGE(PG8_SA(1, 1), a1 + hstep, voffA);
;             PG8_WAIT_V(8); PG8_WAIT_L(0); PG8_BAR; PG8_MMA(0, 0, At, B0); PG8_MMA(0, 1, At, B1); PG8_BAR; PG8_SCHED;
;             PG8_LDA(At, 0, 1); PG8_STAGE(PG8_SB(0, 0), b2, voffB); PG8_STAGE(PG8_SB(0, 1), b2 + hstep, voffB); PG8_STAGE(PG8_SA(0, 0), a2, voffA);
.LBB0_2180:
	s_add_u32 s42, s6, 0x100
	s_addc_u32 s43, s7, 0
	s_add_i32 s21, 0, 0x10000
	s_cmp_eq_u32 s65, 40
	s_cselect_b32 s49, s35, s43
	s_cselect_b32 s48, s34, s42
	s_cselect_b32 s45, s41, s25
	s_cselect_b32 s44, s40, s24
	s_add_i32 s26, 0, 0x14000
	v_add_u32_e32 v140, s21, v168
	v_add_u32_e32 v170, s26, v168
	ds_read_b128 v[128:131], v140
	ds_read_b128 v[132:135], v140 offset:1024
	ds_read_b128 v[136:139], v140 offset:2048
	ds_read_b128 v[140:143], v140 offset:3072
	ds_read_b128 v[144:147], v170
	ds_read_b128 v[148:151], v170 offset:1024
	ds_read_b128 v[164:167], v170 offset:2048
	ds_read_b128 v[170:173], v170 offset:3072
	v_lshl_add_u64 v[228:229], s[6:7], 0, v[158:159]
	s_add_i32 m0, s31, 0xc000
	ds_read_b128 v[174:177], v169
	ds_read_b128 v[178:181], v169 offset:1024
	ds_read_b128 v[204:207], v169 offset:2048
	ds_read_b128 v[208:211], v169 offset:3072
	ds_read_b128 v[212:215], v169 offset:4096
	ds_read_b128 v[216:219], v169 offset:5120
	ds_read_b128 v[220:223], v169 offset:6144
	ds_read_b128 v[224:227], v169 offset:7168
	global_load_lds_dwordx4 v[228:229], off
	v_lshl_add_u64 v[228:229], s[6:7], 0, v[162:163]
	s_add_i32 m0, s31, 0xe000
	s_nop 0
	global_load_lds_dwordx4 v[228:229], off
	s_waitcnt vmcnt(8)
	s_waitcnt lgkmcnt(0)
	s_barrier
	s_setprio 1
	s_waitcnt lgkmcnt(0)
	v_mfma_f32_16x16x32_bf16 v[124:127], v[128:131], v[174:177], v[124:127]
	v_mfma_f32_16x16x32_bf16 v[120:123], v[136:139], v[174:177], v[120:123]
	v_mfma_f32_16x16x32_bf16 v[108:111], v[128:131], v[204:207], v[108:111]
	v_mfma_f32_16x16x32_bf16 v[104:107], v[136:139], v[204:207], v[104:107]
	v_mfma_f32_16x16x32_bf16 v[92:95], v[128:131], v[212:215], v[92:95]
	v_mfma_f32_16x16x32_bf16 v[88:91], v[136:139], v[212:215], v[88:91]
	v_mfma_f32_16x16x32_bf16 v[76:79], v[128:131], v[220:223], v[76:79]
	v_mfma_f32_16x16x32_bf16 v[72:75], v[136:139], v[220:223], v[72:75]
	v_mfma_f32_16x16x32_bf16 v[124:127], v[132:135], v[178:181], v[124:127]
	v_mfma_f32_16x16x32_bf16 v[120:123], v[140:143], v[178:181], v[120:123]
	v_mfma_f32_16x16x32_bf16 v[108:111], v[132:135], v[208:211], v[108:111]
	v_mfma_f32_16x16x32_bf16 v[104:107], v[140:143], v[208:211], v[104:107]
	v_mfma_f32_16x16x32_bf16 v[92:95], v[132:135], v[216:219], v[92:95]
	v_mfma_f32_16x16x32_bf16 v[88:91], v[140:143], v[216:219], v[88:91]
	v_mfma_f32_16x16x32_bf16 v[76:79], v[132:135], v[224:227], v[76:79]
	v_mfma_f32_16x16x32_bf16 v[72:75], v[140:143], v[224:227], v[72:75]
	s_setprio 0
	s_setprio 1
	v_mfma_f32_16x16x32_bf16 v[116:119], v[144:147], v[174:177], v[116:119]
	v_mfma_f32_16x16x32_bf16 v[112:115], v[164:167], v[174:177], v[112:115]
	v_mfma_f32_16x16x32_bf16 v[100:103], v[144:147], v[204:207], v[100:103]
	v_mfma_f32_16x16x32_bf16 v[96:99], v[164:167], v[204:207], v[96:99]
	v_mfma_f32_16x16x32_bf16 v[84:87], v[144:147], v[212:215], v[84:87]
	v_mfma_f32_16x16x32_bf16 v[80:83], v[164:167], v[212:215], v[80:83]
	v_mfma_f32_16x16x32_bf16 v[68:71], v[144:147], v[220:223], v[68:71]
	v_mfma_f32_16x16x32_bf16 v[64:67], v[164:167], v[220:223], v[64:67]
	s_setprio 2
	s_barrier
	v_mfma_f32_16x16x32_bf16 v[116:119], v[148:151], v[178:181], v[116:119]
	v_mfma_f32_16x16x32_bf16 v[112:115], v[170:173], v[178:181], v[112:115]
	v_mfma_f32_16x16x32_bf16 v[100:103], v[148:151], v[208:211], v[100:103]
	v_mfma_f32_16x16x32_bf16 v[96:99], v[170:173], v[208:211], v[96:99]
	v_mfma_f32_16x16x32_bf16 v[84:87], v[148:151], v[216:219], v[84:87]
	v_mfma_f32_16x16x32_bf16 v[80:83], v[170:173], v[216:219], v[80:83]
	v_mfma_f32_16x16x32_bf16 v[68:71], v[148:151], v[224:227], v[68:71]
	v_mfma_f32_16x16x32_bf16 v[64:67], v[170:173], v[224:227], v[64:67]
	s_setprio 0
	s_add_i32 s6, s21, s30
	v_lshl_add_u64 v[228:229], s[44:45], 0, v[160:161]
	s_mov_b32 m0, s6
	ds_read_b128 v[174:177], v169 offset:16384
	ds_read_b128 v[178:181], v169 offset:17408
	ds_read_b128 v[204:207], v169 offset:18432
	ds_read_b128 v[208:211], v169 offset:19456
	ds_read_b128 v[212:215], v169 offset:20480
	ds_read_b128 v[216:219], v169 offset:21504
	ds_read_b128 v[220:223], v169 offset:22528
	ds_read_b128 v[224:227], v169 offset:23552
	global_load_lds_dwordx4 v[228:229], off
	s_add_i32 m0, s6, 0x2000
	s_add_u32 s6, s44, 0xb0000
	v_lshl_add_u64 v[230:231], s[44:45], 0, v[152:153]
	s_addc_u32 s7, s45, 0
	s_add_i32 s21, s26, s30
	global_load_lds_dwordx4 v[230:231], off
	v_lshl_add_u64 v[232:233], s[6:7], 0, v[160:161]
	s_mov_b32 m0, s21
	v_lshl_add_u64 v[234:235], s[48:49], 0, v[154:155]
	global_load_lds_dwordx4 v[232:233], off
	v_lshl_add_u64 v[232:233], s[6:7], 0, v[152:153]
	s_add_i32 m0, s21, 0x2000
	s_nop 0
	global_load_lds_dwordx4 v[232:233], off
	v_lshl_add_u64 v[232:233], s[48:49], 0, v[156:157]
	s_mov_b32 m0, s31
	s_nop 0
	global_load_lds_dwordx4 v[232:233], off
	s_mov_b32 m0, s50
	s_nop 0
	global_load_lds_dwordx4 v[234:235], off
	s_waitcnt vmcnt(8)
	s_waitcnt lgkmcnt(0)
	s_barrier
; #define PG8_STAGE(bufoff, gbase, voff) do { _Pragma("unroll") for (int _i = 0; _i < 2; ++_i) \
;         __builtin_amdgcn_global_load_lds((const unsigned*)((const char*)(gbase) + (voff)[_i]), (PG8_LAS unsigned*)(lds + (bufoff) + ldsw + _i * 8192), 16, 0, 0); } while (0)
; #define PG8_LDA(dst, b, h) do { _Pragma("unroll") for (int m = 0; m < 4; ++m) _Pragma("unroll") for (int k = 0; k < 2; ++k) dst[m][k] = *(const PG8_LAS bf16x8*)(lds + PG8_SA(b, h) + aoff + m * 2048 + k * 1024); } while (0)
; #define PG8_LDB(dst, b, h) do { _Pragma("unroll") for (int n = 0; n < 2; ++n) _Pragma("unroll") for (int k = 0; k < 2; ++k) dst[n][k] = *(const PG8_LAS bf16x8*)(lds + PG8_SB(b, h) + boff + n * 2048 + k * 1024); } while (0)
; #define PG8_MMA(ai, bj, At, Bt) do { __builtin_amdgcn_s_setprio(1); _Pragma("unroll") for (int m = 0; m < 4; ++m) _Pragma("unroll") for (int n = 0; n < 2; ++n) _Pragma("unroll") for (int k = 0; k < 2; ++k) \
;         acc[ai][bj][m][n] = __builtin_amdgcn_mfma_f32_16x16x32_bf16(Bt[n][k], At[m][k], acc[ai][bj][m][n], 0, 0, 0); __builtin_amdgcn_s_setprio(0); } while (0)
; #define PG8_WAIT_V(n) asm volatile("s_waitcnt vmcnt(" #n ")" ::: "memory")
; #define PG8_WAIT_L(n) asm volatile("s_waitcnt lgkmcnt(" #n ")" ::: "memory")
; #define PG8_BAR __builtin_amdgcn_s_barrier()
; #define PG8_SCHED __builtin_amdgcn_sched_barrier(0)
; template <class Epi, class Sched, bool ALIGN_EPI = false, bool SP2 = false>
; __device__ __forceinline__ void gemm_phase(PG8_LAS unsigned char* lds, const Gemm g, const Sched& S, const Epi& E, int wv) {
;     ...
;             PG8_WAIT_V(8); PG8_WAIT_L(0); PG8_BAR; PG8_MMA(1, 0, At, B0); PG8_MMA(1, 1, At, B1); PG8_BAR; PG8_SCHED;
;             PG8_LDB(B0, 1, 0); PG8_LDB(B1, 1, 1); PG8_SCHED; PG8_LDA(At, 1, 0); PG8_STAGE(PG8_SA(0, 1), a2 + hstep, voffA);
;             PG8_WAIT_V(8); PG8_WAIT_L(0); PG8_BAR; PG8_MMA(0, 0, At, B0); PG8_MMA(0, 1, At, B1); PG8_BAR; PG8_SCHED;
	s_setprio 1
	s_waitcnt lgkmcnt(0)
	v_mfma_f32_16x16x32_bf16 v[60:63], v[128:131], v[174:177], v[60:63]
	v_mfma_f32_16x16x32_bf16 v[56:59], v[136:139], v[174:177], v[56:59]
	v_mfma_f32_16x16x32_bf16 v[44:47], v[128:131], v[204:207], v[44:47]
	v_mfma_f32_16x16x32_bf16 v[40:43], v[136:139], v[204:207], v[40:43]
	v_mfma_f32_16x16x32_bf16 v[28:31], v[128:131], v[212:215], v[28:31]
	v_mfma_f32_16x16x32_bf16 v[24:27], v[136:139], v[212:215], v[24:27]
	v_mfma_f32_16x16x32_bf16 v[12:15], v[128:131], v[220:223], v[12:15]
	v_mfma_f32_16x16x32_bf16 v[8:11], v[136:139], v[220:223], v[8:11]
	v_mfma_f32_16x16x32_bf16 v[60:63], v[132:135], v[178:181], v[60:63]
	v_mfma_f32_16x16x32_bf16 v[56:59], v[140:143], v[178:181], v[56:59]
	v_mfma_f32_16x16x32_bf16 v[44:47], v[132:135], v[208:211], v[44:47]
	v_mfma_f32_16x16x32_bf16 v[40:43], v[140:143], v[208:211], v[40:43]
	v_mfma_f32_16x16x32_bf16 v[28:31], v[132:135], v[216:219], v[28:31]
	v_mfma_f32_16x16x32_bf16 v[24:27], v[140:143], v[216:219], v[24:27]
	v_mfma_f32_16x16x32_bf16 v[12:15], v[132:135], v[224:227], v[12:15]
	v_mfma_f32_16x16x32_bf16 v[8:11], v[140:143], v[224:227], v[8:11]
	s_setprio 0
	s_setprio 1
	v_mfma_f32_16x16x32_bf16 v[52:55], v[144:147], v[174:177], v[52:55]
	v_mfma_f32_16x16x32_bf16 v[48:51], v[164:167], v[174:177], v[48:51]
	v_mfma_f32_16x16x32_bf16 v[36:39], v[144:147], v[204:207], v[36:39]
	v_mfma_f32_16x16x32_bf16 v[32:35], v[164:167], v[204:207], v[32:35]
	v_mfma_f32_16x16x32_bf16 v[20:23], v[144:147], v[212:215], v[20:23]
	v_mfma_f32_16x16x32_bf16 v[16:19], v[164:167], v[212:215], v[16:19]
	v_mfma_f32_16x16x32_bf16 v[4:7], v[144:147], v[220:223], v[4:7]
	v_mfma_f32_16x16x32_bf16 v[0:3], v[164:167], v[220:223], v[0:3]
	s_setprio 2
	s_barrier
	v_mfma_f32_16x16x32_bf16 v[52:55], v[148:151], v[178:181], v[52:55]
	v_mfma_f32_16x16x32_bf16 v[48:51], v[170:173], v[178:181], v[48:51]
	v_mfma_f32_16x16x32_bf16 v[36:39], v[148:151], v[208:211], v[36:39]
	v_mfma_f32_16x16x32_bf16 v[32:35], v[170:173], v[208:211], v[32:35]
	v_mfma_f32_16x16x32_bf16 v[20:23], v[148:151], v[216:219], v[20:23]
	v_mfma_f32_16x16x32_bf16 v[16:19], v[170:173], v[216:219], v[16:19]
	v_mfma_f32_16x16x32_bf16 v[4:7], v[148:151], v[224:227], v[4:7]
	v_mfma_f32_16x16x32_bf16 v[0:3], v[170:173], v[224:227], v[0:3]
	s_setprio 0
	s_add_i32 s21, 0, 0x18000
	s_add_i32 s26, 0, 0x1c000
	v_add_u32_e32 v140, s21, v168
	v_add_u32_e32 v170, s26, v168
	ds_read_b128 v[128:131], v140
	ds_read_b128 v[132:135], v140 offset:1024
	ds_read_b128 v[136:139], v140 offset:2048
	ds_read_b128 v[140:143], v140 offset:3072
	ds_read_b128 v[144:147], v170
	ds_read_b128 v[148:151], v170 offset:1024
	ds_read_b128 v[164:167], v170 offset:2048
	ds_read_b128 v[170:173], v170 offset:3072
	s_add_u32 s6, s48, 0xb0000
	s_addc_u32 s7, s49, 0
	s_mov_b32 m0, s51
	v_lshl_add_u64 v[236:237], s[6:7], 0, v[156:157]
	ds_read_b128 v[174:177], v169 offset:32768
	ds_read_b128 v[178:181], v169 offset:33792
	ds_read_b128 v[204:207], v169 offset:34816
	ds_read_b128 v[208:211], v169 offset:35840
	ds_read_b128 v[212:215], v169 offset:36864
	ds_read_b128 v[216:219], v169 offset:37888
	ds_read_b128 v[220:223], v169 offset:38912
	ds_read_b128 v[224:227], v169 offset:39936
	global_load_lds_dwordx4 v[236:237], off
	v_lshl_add_u64 v[236:237], s[6:7], 0, v[154:155]
	s_mov_b32 m0, s52
	s_nop 0
	global_load_lds_dwordx4 v[236:237], off
	s_waitcnt vmcnt(8)
	s_waitcnt lgkmcnt(0)
	s_barrier
	s_setprio 1
	s_waitcnt lgkmcnt(0)
	v_mfma_f32_16x16x32_bf16 v[124:127], v[128:131], v[174:177], v[124:127]
	v_mfma_f32_16x16x32_bf16 v[120:123], v[136:139], v[174:177], v[120:123]
	v_mfma_f32_16x16x32_bf16 v[108:111], v[128:131], v[204:207], v[108:111]
	v_mfma_f32_16x16x32_bf16 v[104:107], v[136:139], v[204:207], v[104:107]
	v_mfma_f32_16x16x32_bf16 v[92:95], v[128:131], v[212:215], v[92:95]
	v_mfma_f32_16x16x32_bf16 v[88:91], v[136:139], v[212:215], v[88:91]
	v_mfma_f32_16x16x32_bf16 v[76:79], v[128:131], v[220:223], v[76:79]
	v_mfma_f32_16x16x32_bf16 v[72:75], v[136:139], v[220:223], v[72:75]
	v_mfma_f32_16x16x32_bf16 v[124:127], v[132:135], v[178:181], v[124:127]
	v_mfma_f32_16x16x32_bf16 v[120:123], v[140:143], v[178:181], v[120:123]
	v_mfma_f32_16x16x32_bf16 v[108:111], v[132:135], v[208:211], v[108:111]
	v_mfma_f32_16x16x32_bf16 v[104:107], v[140:143], v[208:211], v[104:107]
	v_mfma_f32_16x16x32_bf16 v[92:95], v[132:135], v[216:219], v[92:95]
	v_mfma_f32_16x16x32_bf16 v[88:91], v[140:143], v[216:219], v[88:91]
	v_mfma_f32_16x16x32_bf16 v[76:79], v[132:135], v[224:227], v[76:79]
	v_mfma_f32_16x16x32_bf16 v[72:75], v[140:143], v[224:227], v[72:75]
	s_setprio 0
	s_setprio 1
	v_mfma_f32_16x16x32_bf16 v[116:119], v[144:147], v[174:177], v[116:119]
	v_mfma_f32_16x16x32_bf16 v[112:115], v[164:167], v[174:177], v[112:115]
	v_mfma_f32_16x16x32_bf16 v[100:103], v[144:147], v[204:207], v[100:103]
	v_mfma_f32_16x16x32_bf16 v[96:99], v[164:167], v[204:207], v[96:99]
	v_mfma_f32_16x16x32_bf16 v[84:87], v[144:147], v[212:215], v[84:87]
	v_mfma_f32_16x16x32_bf16 v[80:83], v[164:167], v[212:215], v[80:83]
	v_mfma_f32_16x16x32_bf16 v[68:71], v[144:147], v[220:223], v[68:71]
	v_mfma_f32_16x16x32_bf16 v[64:67], v[164:167], v[220:223], v[64:67]
	s_setprio 2
	s_barrier
; #define PG8_STAGE(bufoff, gbase, voff) do { _Pragma("unroll") for (int _i = 0; _i < 2; ++_i) \
;         __builtin_amdgcn_global_load_lds((const unsigned*)((const char*)(gbase) + (voff)[_i]), (PG8_LAS unsigned*)(lds + (bufoff) + ldsw + _i * 8192), 16, 0, 0); } while (0)
; #define PG8_LDA(dst, b, h) do { _Pragma("unroll") for (int m = 0; m < 4; ++m) _Pragma("unroll") for (int k = 0; k < 2; ++k) dst[m][k] = *(const PG8_LAS bf16x8*)(lds + PG8_SA(b, h) + aoff + m * 2048 + k * 1024); } while (0)
; #define PG8_MMA(ai, bj, At, Bt) do { __builtin_amdgcn_s_setprio(1); _Pragma("unroll") for (int m = 0; m < 4; ++m) _Pragma("unroll") for (int n = 0; n < 2; ++n) _Pragma("unroll") for (int k = 0; k < 2; ++k) \
;         acc[ai][bj][m][n] = __builtin_amdgcn_mfma_f32_16x16x32_bf16(Bt[n][k], At[m][k], acc[ai][bj][m][n], 0, 0, 0); __builtin_amdgcn_s_setprio(0); } while (0)
; #define PG8_WAIT_V(n) asm volatile("s_waitcnt vmcnt(" #n ")" ::: "memory")
; #define PG8_WAIT_L(n) asm volatile("s_waitcnt lgkmcnt(" #n ")" ::: "memory")
; #define PG8_BAR __builtin_amdgcn_s_barrier()
; #define PG8_SCHED __builtin_amdgcn_sched_barrier(0)
; template <class Epi, class Sched, bool ALIGN_EPI = false, bool SP2 = false>
; __device__ __forceinline__ void gemm_phase(PG8_LAS unsigned char* lds, const Gemm g, const Sched& S, const Epi& E, int wv) {
;     ...
;         for (int t = 0; t < nt; t += 2) {
;     ...
;             PG8_WAIT_V(8); PG8_WAIT_L(0); PG8_BAR; PG8_MMA(0, 0, At, B0); PG8_MMA(0, 1, At, B1); PG8_BAR; PG8_SCHED;
;             PG8_LDA(At, 1, 1); PG8_STAGE(PG8_SB(1, 0), b3, voffB); PG8_STAGE(PG8_SB(1, 1), b3 + hstep, voffB); PG8_STAGE(PG8_SA(1, 0), a3, voffA);
;             PG8_WAIT_V(8); PG8_WAIT_L(0); PG8_BAR; PG8_MMA(1, 0, At, B0); PG8_MMA(1, 1, At, B1); PG8_BAR; PG8_SCHED;
	v_mfma_f32_16x16x32_bf16 v[116:119], v[148:151], v[178:181], v[116:119]
	v_mfma_f32_16x16x32_bf16 v[112:115], v[170:173], v[178:181], v[112:115]
	v_mfma_f32_16x16x32_bf16 v[100:103], v[148:151], v[208:211], v[100:103]
	v_mfma_f32_16x16x32_bf16 v[96:99], v[170:173], v[208:211], v[96:99]
	v_mfma_f32_16x16x32_bf16 v[84:87], v[148:151], v[216:219], v[84:87]
	v_mfma_f32_16x16x32_bf16 v[80:83], v[170:173], v[216:219], v[80:83]
	v_mfma_f32_16x16x32_bf16 v[68:71], v[148:151], v[224:227], v[68:71]
	v_mfma_f32_16x16x32_bf16 v[64:67], v[170:173], v[224:227], v[64:67]
	s_setprio 0
	s_add_i32 s6, s21, s30
	v_lshl_add_u64 v[228:229], v[228:229], 0, s[74:75]
	s_mov_b32 m0, s6
	ds_read_b128 v[174:177], v169 offset:49152
	ds_read_b128 v[178:181], v169 offset:50176
	ds_read_b128 v[204:207], v169 offset:51200
	ds_read_b128 v[208:211], v169 offset:52224
	ds_read_b128 v[212:215], v169 offset:53248
	ds_read_b128 v[216:219], v169 offset:54272
	ds_read_b128 v[220:223], v169 offset:55296
	ds_read_b128 v[224:227], v169 offset:56320
	global_load_lds_dwordx4 v[228:229], off
	s_add_i32 m0, s6, 0x2000
	s_add_u32 s6, s44, 0xb0080
	v_lshl_add_u64 v[228:229], v[230:231], 0, s[74:75]
	s_addc_u32 s7, s45, 0
	s_add_i32 s21, s26, s30
	global_load_lds_dwordx4 v[228:229], off
	v_lshl_add_u64 v[228:229], s[6:7], 0, v[160:161]
	s_mov_b32 m0, s21
	s_nop 0
	global_load_lds_dwordx4 v[228:229], off
	v_lshl_add_u64 v[228:229], s[6:7], 0, v[152:153]
	s_add_i32 m0, s21, 0x2000
	s_nop 0
	global_load_lds_dwordx4 v[228:229], off
	v_lshl_add_u64 v[228:229], v[232:233], 0, s[74:75]
	s_mov_b32 m0, s56
	s_nop 0
	global_load_lds_dwordx4 v[228:229], off
	v_lshl_add_u64 v[228:229], v[234:235], 0, s[74:75]
	s_mov_b32 m0, s57
	s_nop 0
	global_load_lds_dwordx4 v[228:229], off
	s_waitcnt vmcnt(8)
	s_waitcnt lgkmcnt(0)
	s_barrier
	s_setprio 1
	s_waitcnt lgkmcnt(0)
	v_mfma_f32_16x16x32_bf16 v[60:63], v[128:131], v[174:177], v[60:63]
	v_mfma_f32_16x16x32_bf16 v[56:59], v[136:139], v[174:177], v[56:59]
	v_mfma_f32_16x16x32_bf16 v[44:47], v[128:131], v[204:207], v[44:47]
	v_mfma_f32_16x16x32_bf16 v[40:43], v[136:139], v[204:207], v[40:43]
	v_mfma_f32_16x16x32_bf16 v[28:31], v[128:131], v[212:215], v[28:31]
	v_mfma_f32_16x16x32_bf16 v[24:27], v[136:139], v[212:215], v[24:27]
	v_mfma_f32_16x16x32_bf16 v[12:15], v[128:131], v[220:223], v[12:15]
	v_mfma_f32_16x16x32_bf16 v[8:11], v[136:139], v[220:223], v[8:11]
	v_mfma_f32_16x16x32_bf16 v[60:63], v[132:135], v[178:181], v[60:63]
	v_mfma_f32_16x16x32_bf16 v[56:59], v[140:143], v[178:181], v[56:59]
	v_mfma_f32_16x16x32_bf16 v[44:47], v[132:135], v[208:211], v[44:47]
	v_mfma_f32_16x16x32_bf16 v[40:43], v[140:143], v[208:211], v[40:43]
	v_mfma_f32_16x16x32_bf16 v[28:31], v[132:135], v[216:219], v[28:31]
	v_mfma_f32_16x16x32_bf16 v[24:27], v[140:143], v[216:219], v[24:27]
	v_mfma_f32_16x16x32_bf16 v[12:15], v[132:135], v[224:227], v[12:15]
	v_mfma_f32_16x16x32_bf16 v[8:11], v[140:143], v[224:227], v[8:11]
	s_setprio 0
	s_setprio 1
	v_mfma_f32_16x16x32_bf16 v[52:55], v[144:147], v[174:177], v[52:55]
	v_mfma_f32_16x16x32_bf16 v[48:51], v[164:167], v[174:177], v[48:51]
	v_mfma_f32_16x16x32_bf16 v[36:39], v[144:147], v[204:207], v[36:39]
	v_mfma_f32_16x16x32_bf16 v[32:35], v[164:167], v[204:207], v[32:35]
	v_mfma_f32_16x16x32_bf16 v[20:23], v[144:147], v[212:215], v[20:23]
	v_mfma_f32_16x16x32_bf16 v[16:19], v[164:167], v[212:215], v[16:19]
	v_mfma_f32_16x16x32_bf16 v[4:7], v[144:147], v[220:223], v[4:7]
	v_mfma_f32_16x16x32_bf16 v[0:3], v[164:167], v[220:223], v[0:3]
	s_setprio 2
	s_barrier
	v_mfma_f32_16x16x32_bf16 v[52:55], v[148:151], v[178:181], v[52:55]
	v_mfma_f32_16x16x32_bf16 v[48:51], v[170:173], v[178:181], v[48:51]
	v_mfma_f32_16x16x32_bf16 v[36:39], v[148:151], v[208:211], v[36:39]
	v_mfma_f32_16x16x32_bf16 v[32:35], v[170:173], v[208:211], v[32:35]
	v_mfma_f32_16x16x32_bf16 v[20:23], v[148:151], v[216:219], v[20:23]
	v_mfma_f32_16x16x32_bf16 v[16:19], v[170:173], v[216:219], v[16:19]
	v_mfma_f32_16x16x32_bf16 v[4:7], v[148:151], v[224:227], v[4:7]
	v_mfma_f32_16x16x32_bf16 v[0:3], v[170:173], v[224:227], v[0:3]
	s_setprio 0
	s_add_i32 s65, s65, 2
	s_add_u32 s24, s24, 0x100
	s_addc_u32 s25, s25, 0
	s_cmp_gt_u32 s65, 41
	s_mov_b64 s[6:7], s[42:43]
	s_cbranch_scc0 .LBB0_2180
	s_and_b64 vcc, exec, s[18:19]
	s_cbranch_vccz .LBB0_2183
	s_barrier

; #define PG8_STAGE(bufoff, gbase, voff) do { _Pragma("unroll") for (int _i = 0; _i < 2; ++_i) \
;         __builtin_amdgcn_global_load_lds((const unsigned*)((const char*)(gbase) + (voff)[_i]), (PG8_LAS unsigned*)(lds + (bufoff) + ldsw + _i * 8192), 16, 0, 0); } while (0)
; #define PG8_LDA(dst, b, h) do { _Pragma("unroll") for (int m = 0; m < 4; ++m) _Pragma("unroll") for (int k = 0; k < 2; ++k) dst[m][k] = *(const PG8_LAS bf16x8*)(lds + PG8_SA(b, h) + aoff + m * 2048 + k * 1024); } while (0)
; #define PG8_LDB(dst, b, h) do { _Pragma("unroll") for (int n = 0; n < 2; ++n) _Pragma("unroll") for (int k = 0; k < 2; ++k) dst[n][k] = *(const PG8_LAS bf16x8*)(lds + PG8_SB(b, h) + boff + n * 2048 + k * 1024); } while (0)
; #define PG8_MMA(ai, bj, At, Bt) do { __builtin_amdgcn_s_setprio(1); _Pragma("unroll") for (int m = 0; m < 4; ++m) _Pragma("unroll") for (int n = 0; n < 2; ++n) _Pragma("unroll") for (int k = 0; k < 2; ++k) \
;         acc[ai][bj][m][n] = __builtin_amdgcn_mfma_f32_16x16x32_bf16(Bt[n][k], At[m][k], acc[ai][bj][m][n], 0, 0, 0); __builtin_amdgcn_s_setprio(0); } while (0)
; #define PG8_WAIT_V(n) asm volatile("s_waitcnt vmcnt(" #n ")" ::: "memory")
; #define PG8_WAIT_L(n) asm volatile("s_waitcnt lgkmcnt(" #n ")" ::: "memory")
; #define PG8_BAR __builtin_amdgcn_s_barrier()
; #define PG8_SCHED __builtin_amdgcn_sched_barrier(0)
; template <class Epi, class Sched, bool ALIGN_EPI = false, bool SP2 = false>
; __device__ __forceinline__ void gemm_phase(PG8_LAS unsigned char* lds, const Gemm g, const Sched& S, const Epi& E, int wv) {
;     ...
;             const bool last = (t == nt - 2);
;             const char* a1 = cA + (size_t)(t + 1) * kstep;
;             const char* a2 = last ? nA : cA + (size_t)(t + 2) * kstep; const char* b2 = last ? nB : cB + (size_t)(t + 2) * kstep;
;             const char* a3 = a2 + kstep; const char* b3 = b2 + kstep;
;             if (last && has_next) S.a_ready(nxt);
;             if constexpr (SP2) {
;             PG8_LDB(B0, 0, 0); PG8_LDB(B1, 0, 1); PG8_SCHED; PG8_LDA(At, 0, 0); PG8_STAGE(PG8_SA(1, 1), a1 + hstep, voffA);
;             PG8_WAIT_V(8); PG8_WAIT_L(0); PG8_BAR; PG8_MMA(0, 0, At, B0); PG8_MMA(0, 1, At, B1); PG8_BAR; PG8_SCHED;
;             PG8_LDA(At, 0, 1); PG8_STAGE(PG8_SB(0, 0), b2, voffB); PG8_STAGE(PG8_SB(0, 1), b2 + hstep, voffB); PG8_STAGE(PG8_SA(0, 0), a2, voffA);
.LBB0_2213:
	s_add_u32 s21, s44, s56
	s_addc_u32 s26, s45, 0
	s_add_u32 s28, s21, 0x100
	s_addc_u32 s36, s26, 0
	s_and_b64 s[60:61], s[52:53], exec
	s_cselect_b32 s61, s13, s36
	s_cselect_b32 s60, s83, s28
	s_add_u32 s28, s34, s56
	s_addc_u32 s36, s35, 0
	s_add_u32 s28, s28, 0x100
	s_addc_u32 s36, s36, 0
	s_add_i32 s58, 0, 0x10000
	s_and_b64 s[52:53], s[52:53], exec
	s_cselect_b32 s63, s19, s36
	s_cselect_b32 s62, s91, s28
	s_add_i32 s53, 0, 0x14000
	s_add_u32 vcc_lo, s21, 0x10080
	s_addc_u32 vcc_hi, s26, 0
	s_add_i32 s28, s58, s29
	s_add_i32 m0, s80, 0xc000
	s_add_i32 s30, s80, 0xe000
	s_add_i32 s55, s28, 0x2000
	s_add_u32 s64, s62, 0x10000
	v_add_u32_e32 v148, s58, v134
	v_add_u32_e32 v166, s53, v134
	s_addc_u32 s65, s63, 0
	s_add_i32 s36, s53, s29
	ds_read_b128 v[136:139], v148
	ds_read_b128 v[140:143], v148 offset:1024
	ds_read_b128 v[144:147], v148 offset:2048
	ds_read_b128 v[148:151], v148 offset:3072
	ds_read_b128 v[152:155], v166
	ds_read_b128 v[156:159], v166 offset:1024
	ds_read_b128 v[162:165], v166 offset:2048
	ds_read_b128 v[166:169], v166 offset:3072
	s_add_i32 s21, s36, 0x2000
	s_add_i32 s92, 0, 0x18000
	s_add_i32 s94, 0, 0x1c000
	s_add_u32 s56, s60, 0x10000
	s_addc_u32 s57, s61, 0
	s_add_i32 s93, s92, s29
	s_add_i32 s88, s93, 0x2000
	s_add_u32 s52, s62, 0x10080
	s_addc_u32 s53, s63, 0
	s_add_i32 s58, s94, s29
	s_add_i32 s26, s58, 0x2000
	v_lshl_add_u64 v[224:225], vcc, 0, v[132:133]
	ds_read_b128 v[170:173], v135
	ds_read_b128 v[174:177], v135 offset:1024
	ds_read_b128 v[178:181], v135 offset:2048
	ds_read_b128 v[204:207], v135 offset:3072
	ds_read_b128 v[208:211], v135 offset:4096
	ds_read_b128 v[212:215], v135 offset:5120
	ds_read_b128 v[216:219], v135 offset:6144
	ds_read_b128 v[220:223], v135 offset:7168
	global_load_lds_dwordx4 v[224:225], off
	v_lshl_add_u64 v[224:225], vcc, 0, v[130:131]
	s_mov_b32 m0, s30
	s_nop 0
	global_load_lds_dwordx4 v[224:225], off
	s_waitcnt vmcnt(8)
	s_waitcnt lgkmcnt(0)
	s_barrier
	s_setprio 1
	s_waitcnt lgkmcnt(0)
	v_mfma_f32_16x16x32_bf16 v[124:127], v[136:139], v[170:173], v[124:127]
	v_mfma_f32_16x16x32_bf16 v[120:123], v[144:147], v[170:173], v[120:123]
	v_mfma_f32_16x16x32_bf16 v[116:119], v[136:139], v[178:181], v[116:119]
	v_mfma_f32_16x16x32_bf16 v[112:115], v[144:147], v[178:181], v[112:115]
	v_mfma_f32_16x16x32_bf16 v[100:103], v[136:139], v[208:211], v[100:103]
	v_mfma_f32_16x16x32_bf16 v[96:99], v[144:147], v[208:211], v[96:99]
	v_mfma_f32_16x16x32_bf16 v[84:87], v[136:139], v[216:219], v[84:87]
	v_mfma_f32_16x16x32_bf16 v[80:83], v[144:147], v[216:219], v[80:83]
	v_mfma_f32_16x16x32_bf16 v[124:127], v[140:143], v[174:177], v[124:127]
	v_mfma_f32_16x16x32_bf16 v[120:123], v[148:151], v[174:177], v[120:123]
	v_mfma_f32_16x16x32_bf16 v[116:119], v[140:143], v[204:207], v[116:119]
	v_mfma_f32_16x16x32_bf16 v[112:115], v[148:151], v[204:207], v[112:115]
	v_mfma_f32_16x16x32_bf16 v[100:103], v[140:143], v[212:215], v[100:103]
	v_mfma_f32_16x16x32_bf16 v[96:99], v[148:151], v[212:215], v[96:99]
	v_mfma_f32_16x16x32_bf16 v[84:87], v[140:143], v[220:223], v[84:87]
	v_mfma_f32_16x16x32_bf16 v[80:83], v[148:151], v[220:223], v[80:83]
	s_setprio 0
	s_setprio 1
	v_mfma_f32_16x16x32_bf16 v[108:111], v[152:155], v[170:173], v[108:111]
	v_mfma_f32_16x16x32_bf16 v[104:107], v[162:165], v[170:173], v[104:107]
	v_mfma_f32_16x16x32_bf16 v[92:95], v[152:155], v[178:181], v[92:95]
	v_mfma_f32_16x16x32_bf16 v[88:91], v[162:165], v[178:181], v[88:91]
	v_mfma_f32_16x16x32_bf16 v[76:79], v[152:155], v[208:211], v[76:79]
	v_mfma_f32_16x16x32_bf16 v[72:75], v[162:165], v[208:211], v[72:75]
	v_mfma_f32_16x16x32_bf16 v[68:71], v[152:155], v[216:219], v[68:71]
	v_mfma_f32_16x16x32_bf16 v[64:67], v[162:165], v[216:219], v[64:67]
	s_setprio 2
	s_barrier
	v_mfma_f32_16x16x32_bf16 v[108:111], v[156:159], v[174:177], v[108:111]
	v_mfma_f32_16x16x32_bf16 v[104:107], v[166:169], v[174:177], v[104:107]
	v_mfma_f32_16x16x32_bf16 v[92:95], v[156:159], v[204:207], v[92:95]
	v_mfma_f32_16x16x32_bf16 v[88:91], v[166:169], v[204:207], v[88:91]
	v_mfma_f32_16x16x32_bf16 v[76:79], v[156:159], v[212:215], v[76:79]
	v_mfma_f32_16x16x32_bf16 v[72:75], v[166:169], v[212:215], v[72:75]
	v_mfma_f32_16x16x32_bf16 v[68:71], v[156:159], v[220:223], v[68:71]
	v_mfma_f32_16x16x32_bf16 v[64:67], v[166:169], v[220:223], v[64:67]
	s_setprio 0
	s_mov_b32 m0, s28
	v_lshl_add_u64 v[224:225], s[62:63], 0, v[160:161]
	ds_read_b128 v[170:173], v135 offset:16384
	ds_read_b128 v[174:177], v135 offset:17408
	ds_read_b128 v[178:181], v135 offset:18432
	ds_read_b128 v[204:207], v135 offset:19456
	ds_read_b128 v[208:211], v135 offset:20480
	ds_read_b128 v[212:215], v135 offset:21504
	ds_read_b128 v[216:219], v135 offset:22528
	ds_read_b128 v[220:223], v135 offset:23552
	global_load_lds_dwordx4 v[224:225], off
	v_lshl_add_u64 v[226:227], s[62:63], 0, v[128:129]
	s_mov_b32 m0, s55
	v_lshl_add_u64 v[228:229], s[64:65], 0, v[160:161]
	global_load_lds_dwordx4 v[226:227], off
	s_mov_b32 m0, s36
	v_lshl_add_u64 v[230:231], s[60:61], 0, v[130:131]
	global_load_lds_dwordx4 v[228:229], off
	v_lshl_add_u64 v[228:229], s[64:65], 0, v[128:129]
	s_mov_b32 m0, s21
	s_nop 0
	global_load_lds_dwordx4 v[228:229], off
	v_lshl_add_u64 v[228:229], s[60:61], 0, v[132:133]
	s_mov_b32 m0, s80
	s_nop 0
	global_load_lds_dwordx4 v[228:229], off
	s_mov_b32 m0, s31
	s_nop 0
	global_load_lds_dwordx4 v[230:231], off
	s_waitcnt vmcnt(8)
	s_waitcnt lgkmcnt(0)
	s_barrier
; #define PG8_STAGE(bufoff, gbase, voff) do { _Pragma("unroll") for (int _i = 0; _i < 2; ++_i) \
;         __builtin_amdgcn_global_load_lds((const unsigned*)((const char*)(gbase) + (voff)[_i]), (PG8_LAS unsigned*)(lds + (bufoff) + ldsw + _i * 8192), 16, 0, 0); } while (0)
; #define PG8_LDA(dst, b, h) do { _Pragma("unroll") for (int m = 0; m < 4; ++m) _Pragma("unroll") for (int k = 0; k < 2; ++k) dst[m][k] = *(const PG8_LAS bf16x8*)(lds + PG8_SA(b, h) + aoff + m * 2048 + k * 1024); } while (0)
; #define PG8_LDB(dst, b, h) do { _Pragma("unroll") for (int n = 0; n < 2; ++n) _Pragma("unroll") for (int k = 0; k < 2; ++k) dst[n][k] = *(const PG8_LAS bf16x8*)(lds + PG8_SB(b, h) + boff + n * 2048 + k * 1024); } while (0)
; #define PG8_MMA(ai, bj, At, Bt) do { __builtin_amdgcn_s_setprio(1); _Pragma("unroll") for (int m = 0; m < 4; ++m) _Pragma("unroll") for (int n = 0; n < 2; ++n) _Pragma("unroll") for (int k = 0; k < 2; ++k) \
;         acc[ai][bj][m][n] = __builtin_amdgcn_mfma_f32_16x16x32_bf16(Bt[n][k], At[m][k], acc[ai][bj][m][n], 0, 0, 0); __builtin_amdgcn_s_setprio(0); } while (0)
; #define PG8_WAIT_V(n) asm volatile("s_waitcnt vmcnt(" #n ")" ::: "memory")
; #define PG8_WAIT_L(n) asm volatile("s_waitcnt lgkmcnt(" #n ")" ::: "memory")
; #define PG8_BAR __builtin_amdgcn_s_barrier()
; #define PG8_SCHED __builtin_amdgcn_sched_barrier(0)
; template <class Epi, class Sched, bool ALIGN_EPI = false, bool SP2 = false>
; __device__ __forceinline__ void gemm_phase(PG8_LAS unsigned char* lds, const Gemm g, const Sched& S, const Epi& E, int wv) {
;     ...
;             PG8_WAIT_V(8); PG8_WAIT_L(0); PG8_BAR; PG8_MMA(1, 0, At, B0); PG8_MMA(1, 1, At, B1); PG8_BAR; PG8_SCHED;
;             PG8_LDB(B0, 1, 0); PG8_LDB(B1, 1, 1); PG8_SCHED; PG8_LDA(At, 1, 0); PG8_STAGE(PG8_SA(0, 1), a2 + hstep, voffA);
;             PG8_WAIT_V(8); PG8_WAIT_L(0); PG8_BAR; PG8_MMA(0, 0, At, B0); PG8_MMA(0, 1, At, B1); PG8_BAR; PG8_SCHED;
	s_setprio 1
	s_waitcnt lgkmcnt(0)
	v_mfma_f32_16x16x32_bf16 v[60:63], v[136:139], v[170:173], v[60:63]
	v_mfma_f32_16x16x32_bf16 v[56:59], v[144:147], v[170:173], v[56:59]
	v_mfma_f32_16x16x32_bf16 v[52:55], v[136:139], v[178:181], v[52:55]
	v_mfma_f32_16x16x32_bf16 v[48:51], v[144:147], v[178:181], v[48:51]
	v_mfma_f32_16x16x32_bf16 v[36:39], v[136:139], v[208:211], v[36:39]
	v_mfma_f32_16x16x32_bf16 v[32:35], v[144:147], v[208:211], v[32:35]
	v_mfma_f32_16x16x32_bf16 v[20:23], v[136:139], v[216:219], v[20:23]
	v_mfma_f32_16x16x32_bf16 v[16:19], v[144:147], v[216:219], v[16:19]
	v_mfma_f32_16x16x32_bf16 v[60:63], v[140:143], v[174:177], v[60:63]
	v_mfma_f32_16x16x32_bf16 v[56:59], v[148:151], v[174:177], v[56:59]
	v_mfma_f32_16x16x32_bf16 v[52:55], v[140:143], v[204:207], v[52:55]
	v_mfma_f32_16x16x32_bf16 v[48:51], v[148:151], v[204:207], v[48:51]
	v_mfma_f32_16x16x32_bf16 v[36:39], v[140:143], v[212:215], v[36:39]
	v_mfma_f32_16x16x32_bf16 v[32:35], v[148:151], v[212:215], v[32:35]
	v_mfma_f32_16x16x32_bf16 v[20:23], v[140:143], v[220:223], v[20:23]
	v_mfma_f32_16x16x32_bf16 v[16:19], v[148:151], v[220:223], v[16:19]
	s_setprio 0
	s_setprio 1
	v_mfma_f32_16x16x32_bf16 v[44:47], v[152:155], v[170:173], v[44:47]
	v_mfma_f32_16x16x32_bf16 v[40:43], v[162:165], v[170:173], v[40:43]
	v_mfma_f32_16x16x32_bf16 v[28:31], v[152:155], v[178:181], v[28:31]
	v_mfma_f32_16x16x32_bf16 v[24:27], v[162:165], v[178:181], v[24:27]
	v_mfma_f32_16x16x32_bf16 v[12:15], v[152:155], v[208:211], v[12:15]
	v_mfma_f32_16x16x32_bf16 v[8:11], v[162:165], v[208:211], v[8:11]
	v_mfma_f32_16x16x32_bf16 v[4:7], v[152:155], v[216:219], v[4:7]
	v_mfma_f32_16x16x32_bf16 v[0:3], v[162:165], v[216:219], v[0:3]
	s_setprio 2
	s_barrier
	v_mfma_f32_16x16x32_bf16 v[44:47], v[156:159], v[174:177], v[44:47]
	v_mfma_f32_16x16x32_bf16 v[40:43], v[166:169], v[174:177], v[40:43]
	v_mfma_f32_16x16x32_bf16 v[28:31], v[156:159], v[204:207], v[28:31]
	v_mfma_f32_16x16x32_bf16 v[24:27], v[166:169], v[204:207], v[24:27]
	v_mfma_f32_16x16x32_bf16 v[12:15], v[156:159], v[212:215], v[12:15]
	v_mfma_f32_16x16x32_bf16 v[8:11], v[166:169], v[212:215], v[8:11]
	v_mfma_f32_16x16x32_bf16 v[4:7], v[156:159], v[220:223], v[4:7]
	v_mfma_f32_16x16x32_bf16 v[0:3], v[166:169], v[220:223], v[0:3]
	s_setprio 0
	v_add_u32_e32 v148, s92, v134
	v_add_u32_e32 v166, s94, v134
	ds_read_b128 v[136:139], v148
	ds_read_b128 v[140:143], v148 offset:1024
	ds_read_b128 v[144:147], v148 offset:2048
	ds_read_b128 v[148:151], v148 offset:3072
	ds_read_b128 v[152:155], v166
	ds_read_b128 v[156:159], v166 offset:1024
	ds_read_b128 v[162:165], v166 offset:2048
	ds_read_b128 v[166:169], v166 offset:3072
	s_mov_b32 m0, s54
	v_lshl_add_u64 v[232:233], s[56:57], 0, v[132:133]
	ds_read_b128 v[170:173], v135 offset:32768
	ds_read_b128 v[174:177], v135 offset:33792
	ds_read_b128 v[178:181], v135 offset:34816
	ds_read_b128 v[204:207], v135 offset:35840
	ds_read_b128 v[208:211], v135 offset:36864
	ds_read_b128 v[212:215], v135 offset:37888
	ds_read_b128 v[216:219], v135 offset:38912
	ds_read_b128 v[220:223], v135 offset:39936
	global_load_lds_dwordx4 v[232:233], off
	v_lshl_add_u64 v[232:233], s[56:57], 0, v[130:131]
	s_mov_b32 m0, s66
	s_nop 0
	global_load_lds_dwordx4 v[232:233], off
	s_waitcnt vmcnt(8)
	s_waitcnt lgkmcnt(0)
	s_barrier
	s_setprio 1
	s_waitcnt lgkmcnt(0)
	v_mfma_f32_16x16x32_bf16 v[124:127], v[136:139], v[170:173], v[124:127]
	v_mfma_f32_16x16x32_bf16 v[120:123], v[144:147], v[170:173], v[120:123]
	v_mfma_f32_16x16x32_bf16 v[116:119], v[136:139], v[178:181], v[116:119]
	v_mfma_f32_16x16x32_bf16 v[112:115], v[144:147], v[178:181], v[112:115]
	v_mfma_f32_16x16x32_bf16 v[100:103], v[136:139], v[208:211], v[100:103]
	v_mfma_f32_16x16x32_bf16 v[96:99], v[144:147], v[208:211], v[96:99]
	v_mfma_f32_16x16x32_bf16 v[84:87], v[136:139], v[216:219], v[84:87]
	v_mfma_f32_16x16x32_bf16 v[80:83], v[144:147], v[216:219], v[80:83]
	v_mfma_f32_16x16x32_bf16 v[124:127], v[140:143], v[174:177], v[124:127]
	v_mfma_f32_16x16x32_bf16 v[120:123], v[148:151], v[174:177], v[120:123]
	v_mfma_f32_16x16x32_bf16 v[116:119], v[140:143], v[204:207], v[116:119]
	v_mfma_f32_16x16x32_bf16 v[112:115], v[148:151], v[204:207], v[112:115]
	v_mfma_f32_16x16x32_bf16 v[100:103], v[140:143], v[212:215], v[100:103]
	v_mfma_f32_16x16x32_bf16 v[96:99], v[148:151], v[212:215], v[96:99]
	v_mfma_f32_16x16x32_bf16 v[84:87], v[140:143], v[220:223], v[84:87]
	v_mfma_f32_16x16x32_bf16 v[80:83], v[148:151], v[220:223], v[80:83]
	s_setprio 0
	s_setprio 1
	v_mfma_f32_16x16x32_bf16 v[108:111], v[152:155], v[170:173], v[108:111]
	v_mfma_f32_16x16x32_bf16 v[104:107], v[162:165], v[170:173], v[104:107]
	v_mfma_f32_16x16x32_bf16 v[92:95], v[152:155], v[178:181], v[92:95]
	v_mfma_f32_16x16x32_bf16 v[88:91], v[162:165], v[178:181], v[88:91]
	v_mfma_f32_16x16x32_bf16 v[76:79], v[152:155], v[208:211], v[76:79]
	v_mfma_f32_16x16x32_bf16 v[72:75], v[162:165], v[208:211], v[72:75]
	v_mfma_f32_16x16x32_bf16 v[68:71], v[152:155], v[216:219], v[68:71]
	v_mfma_f32_16x16x32_bf16 v[64:67], v[162:165], v[216:219], v[64:67]
	s_setprio 2
	s_barrier
; #define PG8_STAGE(bufoff, gbase, voff) do { _Pragma("unroll") for (int _i = 0; _i < 2; ++_i) \
;         __builtin_amdgcn_global_load_lds((const unsigned*)((const char*)(gbase) + (voff)[_i]), (PG8_LAS unsigned*)(lds + (bufoff) + ldsw + _i * 8192), 16, 0, 0); } while (0)
; #define PG8_LDA(dst, b, h) do { _Pragma("unroll") for (int m = 0; m < 4; ++m) _Pragma("unroll") for (int k = 0; k < 2; ++k) dst[m][k] = *(const PG8_LAS bf16x8*)(lds + PG8_SA(b, h) + aoff + m * 2048 + k * 1024); } while (0)
; #define PG8_MMA(ai, bj, At, Bt) do { __builtin_amdgcn_s_setprio(1); _Pragma("unroll") for (int m = 0; m < 4; ++m) _Pragma("unroll") for (int n = 0; n < 2; ++n) _Pragma("unroll") for (int k = 0; k < 2; ++k) \
;         acc[ai][bj][m][n] = __builtin_amdgcn_mfma_f32_16x16x32_bf16(Bt[n][k], At[m][k], acc[ai][bj][m][n], 0, 0, 0); __builtin_amdgcn_s_setprio(0); } while (0)
; #define PG8_WAIT_V(n) asm volatile("s_waitcnt vmcnt(" #n ")" ::: "memory")
; #define PG8_WAIT_L(n) asm volatile("s_waitcnt lgkmcnt(" #n ")" ::: "memory")
; #define PG8_BAR __builtin_amdgcn_s_barrier()
; #define PG8_SCHED __builtin_amdgcn_sched_barrier(0)
; template <class Epi, class Sched, bool ALIGN_EPI = false, bool SP2 = false>
; __device__ __forceinline__ void gemm_phase(PG8_LAS unsigned char* lds, const Gemm g, const Sched& S, const Epi& E, int wv) {
;     ...
;         for (int t = 0; t < nt; t += 2) {
;     ...
;             PG8_WAIT_V(8); PG8_WAIT_L(0); PG8_BAR; PG8_MMA(0, 0, At, B0); PG8_MMA(0, 1, At, B1); PG8_BAR; PG8_SCHED;
;             PG8_LDA(At, 1, 1); PG8_STAGE(PG8_SB(1, 0), b3, voffB); PG8_STAGE(PG8_SB(1, 1), b3 + hstep, voffB); PG8_STAGE(PG8_SA(1, 0), a3, voffA);
;             PG8_WAIT_V(8); PG8_WAIT_L(0); PG8_BAR; PG8_MMA(1, 0, At, B0); PG8_MMA(1, 1, At, B1); PG8_BAR; PG8_SCHED;
	v_mfma_f32_16x16x32_bf16 v[108:111], v[156:159], v[174:177], v[108:111]
	v_mfma_f32_16x16x32_bf16 v[104:107], v[166:169], v[174:177], v[104:107]
	v_mfma_f32_16x16x32_bf16 v[92:95], v[156:159], v[204:207], v[92:95]
	v_mfma_f32_16x16x32_bf16 v[88:91], v[166:169], v[204:207], v[88:91]
	v_mfma_f32_16x16x32_bf16 v[76:79], v[156:159], v[212:215], v[76:79]
	v_mfma_f32_16x16x32_bf16 v[72:75], v[166:169], v[212:215], v[72:75]
	v_mfma_f32_16x16x32_bf16 v[68:71], v[156:159], v[220:223], v[68:71]
	v_mfma_f32_16x16x32_bf16 v[64:67], v[166:169], v[220:223], v[64:67]
	s_setprio 0
	s_mov_b32 m0, s93
	v_lshl_add_u64 v[224:225], v[224:225], 0, s[74:75]
	ds_read_b128 v[170:173], v135 offset:49152
	ds_read_b128 v[174:177], v135 offset:50176
	ds_read_b128 v[178:181], v135 offset:51200
	ds_read_b128 v[204:207], v135 offset:52224
	ds_read_b128 v[208:211], v135 offset:53248
	ds_read_b128 v[212:215], v135 offset:54272
	ds_read_b128 v[216:219], v135 offset:55296
	ds_read_b128 v[220:223], v135 offset:56320
	global_load_lds_dwordx4 v[224:225], off
	v_lshl_add_u64 v[224:225], v[226:227], 0, s[74:75]
	s_mov_b32 m0, s88
	s_nop 0
	global_load_lds_dwordx4 v[224:225], off
	v_lshl_add_u64 v[224:225], s[52:53], 0, v[160:161]
	s_mov_b32 m0, s58
	s_nop 0
	global_load_lds_dwordx4 v[224:225], off
	v_lshl_add_u64 v[224:225], s[52:53], 0, v[128:129]
	s_mov_b32 m0, s26
	s_nop 0
	global_load_lds_dwordx4 v[224:225], off
	v_lshl_add_u64 v[224:225], v[228:229], 0, s[74:75]
	s_mov_b32 m0, s81
	s_nop 0
	global_load_lds_dwordx4 v[224:225], off
	v_lshl_add_u64 v[224:225], v[230:231], 0, s[74:75]
	s_mov_b32 m0, s89
	s_nop 0
	global_load_lds_dwordx4 v[224:225], off
	s_waitcnt vmcnt(8)
	s_waitcnt lgkmcnt(0)
	s_barrier
	s_setprio 1
	s_waitcnt lgkmcnt(0)
	v_mfma_f32_16x16x32_bf16 v[60:63], v[136:139], v[170:173], v[60:63]
	v_mfma_f32_16x16x32_bf16 v[56:59], v[144:147], v[170:173], v[56:59]
	v_mfma_f32_16x16x32_bf16 v[52:55], v[136:139], v[178:181], v[52:55]
	v_mfma_f32_16x16x32_bf16 v[48:51], v[144:147], v[178:181], v[48:51]
	v_mfma_f32_16x16x32_bf16 v[36:39], v[136:139], v[208:211], v[36:39]
	v_mfma_f32_16x16x32_bf16 v[32:35], v[144:147], v[208:211], v[32:35]
	v_mfma_f32_16x16x32_bf16 v[20:23], v[136:139], v[216:219], v[20:23]
	v_mfma_f32_16x16x32_bf16 v[16:19], v[144:147], v[216:219], v[16:19]
	v_mfma_f32_16x16x32_bf16 v[60:63], v[140:143], v[174:177], v[60:63]
	v_mfma_f32_16x16x32_bf16 v[56:59], v[148:151], v[174:177], v[56:59]
	v_mfma_f32_16x16x32_bf16 v[52:55], v[140:143], v[204:207], v[52:55]
	v_mfma_f32_16x16x32_bf16 v[48:51], v[148:151], v[204:207], v[48:51]
	v_mfma_f32_16x16x32_bf16 v[36:39], v[140:143], v[212:215], v[36:39]
	v_mfma_f32_16x16x32_bf16 v[32:35], v[148:151], v[212:215], v[32:35]
	v_mfma_f32_16x16x32_bf16 v[20:23], v[140:143], v[220:223], v[20:23]
	v_mfma_f32_16x16x32_bf16 v[16:19], v[148:151], v[220:223], v[16:19]
	s_setprio 0
	s_setprio 1
	v_mfma_f32_16x16x32_bf16 v[44:47], v[152:155], v[170:173], v[44:47]
	v_mfma_f32_16x16x32_bf16 v[40:43], v[162:165], v[170:173], v[40:43]
	v_mfma_f32_16x16x32_bf16 v[28:31], v[152:155], v[178:181], v[28:31]
	v_mfma_f32_16x16x32_bf16 v[24:27], v[162:165], v[178:181], v[24:27]
	v_mfma_f32_16x16x32_bf16 v[12:15], v[152:155], v[208:211], v[12:15]
	v_mfma_f32_16x16x32_bf16 v[8:11], v[162:165], v[208:211], v[8:11]
	v_mfma_f32_16x16x32_bf16 v[4:7], v[152:155], v[216:219], v[4:7]
	v_mfma_f32_16x16x32_bf16 v[0:3], v[162:165], v[216:219], v[0:3]
	s_setprio 2
	s_barrier
	v_mfma_f32_16x16x32_bf16 v[44:47], v[156:159], v[174:177], v[44:47]
	v_mfma_f32_16x16x32_bf16 v[40:43], v[166:169], v[174:177], v[40:43]
	v_mfma_f32_16x16x32_bf16 v[28:31], v[156:159], v[204:207], v[28:31]
	v_mfma_f32_16x16x32_bf16 v[24:27], v[166:169], v[204:207], v[24:27]
	v_mfma_f32_16x16x32_bf16 v[12:15], v[156:159], v[212:215], v[12:15]
	v_mfma_f32_16x16x32_bf16 v[8:11], v[166:169], v[212:215], v[8:11]
	v_mfma_f32_16x16x32_bf16 v[4:7], v[156:159], v[220:223], v[4:7]
	v_mfma_f32_16x16x32_bf16 v[0:3], v[166:169], v[220:223], v[0:3]
	s_setprio 0
	s_movk_i32 s56, 0x100
	s_andn2_b64 vcc, exec, s[50:51]
	s_mov_b64 s[52:53], -1
	s_mov_b64 s[50:51], 0
	s_cbranch_vccz .LBB0_2213
	s_and_b64 vcc, exec, s[8:9]
	s_cbranch_vccz .LBB0_2216
	s_barrier

; #define PG8_STAGE(bufoff, gbase, voff) do { _Pragma("unroll") for (int _i = 0; _i < 2; ++_i) \
;         __builtin_amdgcn_global_load_lds((const unsigned*)((const char*)(gbase) + (voff)[_i]), (PG8_LAS unsigned*)(lds + (bufoff) + ldsw + _i * 8192), 16, 0, 0); } while (0)
; #define PG8_LDA(dst, b, h) do { _Pragma("unroll") for (int m = 0; m < 4; ++m) _Pragma("unroll") for (int k = 0; k < 2; ++k) dst[m][k] = *(const PG8_LAS bf16x8*)(lds + PG8_SA(b, h) + aoff + m * 2048 + k * 1024); } while (0)
; #define PG8_LDB(dst, b, h) do { _Pragma("unroll") for (int n = 0; n < 2; ++n) _Pragma("unroll") for (int k = 0; k < 2; ++k) dst[n][k] = *(const PG8_LAS bf16x8*)(lds + PG8_SB(b, h) + boff + n * 2048 + k * 1024); } while (0)
; #define PG8_MMA(ai, bj, At, Bt) do { __builtin_amdgcn_s_setprio(1); _Pragma("unroll") for (int m = 0; m < 4; ++m) _Pragma("unroll") for (int n = 0; n < 2; ++n) _Pragma("unroll") for (int k = 0; k < 2; ++k) \
;         acc[ai][bj][m][n] = __builtin_amdgcn_mfma_f32_16x16x32_bf16(Bt[n][k], At[m][k], acc[ai][bj][m][n], 0, 0, 0); __builtin_amdgcn_s_setprio(0); } while (0)
; #define PG8_WAIT_V(n) asm volatile("s_waitcnt vmcnt(" #n ")" ::: "memory")
; #define PG8_WAIT_L(n) asm volatile("s_waitcnt lgkmcnt(" #n ")" ::: "memory")
; #define PG8_BAR __builtin_amdgcn_s_barrier()
; #define PG8_SCHED __builtin_amdgcn_sched_barrier(0)
; template <class Epi, class Sched, bool ALIGN_EPI = false, bool SP2 = false>
; __device__ __forceinline__ void gemm_phase(PG8_LAS unsigned char* lds, const Gemm g, const Sched& S, const Epi& E, int wv) {
;     ...
;             const bool last = (t == nt - 2);
;             const char* a1 = cA + (size_t)(t + 1) * kstep;
;             const char* a2 = last ? nA : cA + (size_t)(t + 2) * kstep; const char* b2 = last ? nB : cB + (size_t)(t + 2) * kstep;
;             const char* a3 = a2 + kstep; const char* b3 = b2 + kstep;
;             if (last && has_next) S.a_ready(nxt);
;             if constexpr (SP2) {
;             PG8_LDB(B0, 0, 0); PG8_LDB(B1, 0, 1); PG8_SCHED; PG8_LDA(At, 0, 0); PG8_STAGE(PG8_SA(1, 1), a1 + hstep, voffA);
;             PG8_WAIT_V(8); PG8_WAIT_L(0); PG8_BAR; PG8_MMA(0, 0, At, B0); PG8_MMA(0, 1, At, B1); PG8_BAR; PG8_SCHED;
;             PG8_LDA(At, 0, 1); PG8_STAGE(PG8_SB(0, 0), b2, voffB); PG8_STAGE(PG8_SB(0, 1), b2 + hstep, voffB); PG8_STAGE(PG8_SA(0, 0), a2, voffA);
.LBB0_2281:
	s_add_u32 s6, s4, 0xfffc0080
	s_addc_u32 s7, s5, -1
	s_add_i32 s21, 0, 0x10000
	s_cmp_eq_u32 vcc_hi, 12
	s_cselect_b32 s9, s53, s7
	s_cselect_b32 s8, s81, s6
	s_cselect_b32 s7, s57, vcc_lo
	s_cselect_b32 s6, s83, s91
	s_add_i32 s26, 0, 0x14000
	v_add_u32_e32 v140, s21, v203
	v_add_u32_e32 v156, s26, v203
	ds_read_b128 v[124:127], v140
	ds_read_b128 v[128:131], v140 offset:1024
	ds_read_b128 v[136:139], v140 offset:2048
	ds_read_b128 v[140:143], v140 offset:3072
	ds_read_b128 v[144:147], v156
	ds_read_b128 v[148:151], v156 offset:1024
	ds_read_b128 v[152:155], v156 offset:2048
	ds_read_b128 v[156:159], v156 offset:3072
	v_lshl_add_u64 v[180:181], s[4:5], 0, v[168:169]
	s_add_i32 m0, s66, 0xc000
	ds_read_b128 v[172:175], v204
	ds_read_b128 v[176:179], v204 offset:1024
	ds_read_b128 v[206:209], v204 offset:2048
	ds_read_b128 v[210:213], v204 offset:3072
	ds_read_b128 v[214:217], v204 offset:4096
	ds_read_b128 v[218:221], v204 offset:5120
	ds_read_b128 v[222:225], v204 offset:6144
	ds_read_b128 v[226:229], v204 offset:7168
	global_load_lds_dwordx4 v[180:181], off
	v_lshl_add_u64 v[180:181], s[4:5], 0, v[170:171]
	s_add_i32 m0, s66, 0xe000
	s_nop 0
	global_load_lds_dwordx4 v[180:181], off
	s_waitcnt vmcnt(8)
	s_waitcnt lgkmcnt(0)
	s_barrier
	s_setprio 1
	s_waitcnt lgkmcnt(0)
	v_mfma_f32_16x16x32_bf16 v[132:135], v[124:127], v[172:175], v[132:135]
	v_mfma_f32_16x16x32_bf16 v[120:123], v[136:139], v[172:175], v[120:123]
	v_mfma_f32_16x16x32_bf16 v[108:111], v[124:127], v[206:209], v[108:111]
	v_mfma_f32_16x16x32_bf16 v[104:107], v[136:139], v[206:209], v[104:107]
	v_mfma_f32_16x16x32_bf16 v[92:95], v[124:127], v[214:217], v[92:95]
	v_mfma_f32_16x16x32_bf16 v[88:91], v[136:139], v[214:217], v[88:91]
	v_mfma_f32_16x16x32_bf16 v[76:79], v[124:127], v[222:225], v[76:79]
	v_mfma_f32_16x16x32_bf16 v[72:75], v[136:139], v[222:225], v[72:75]
	v_mfma_f32_16x16x32_bf16 v[132:135], v[128:131], v[176:179], v[132:135]
	v_mfma_f32_16x16x32_bf16 v[120:123], v[140:143], v[176:179], v[120:123]
	v_mfma_f32_16x16x32_bf16 v[108:111], v[128:131], v[210:213], v[108:111]
	v_mfma_f32_16x16x32_bf16 v[104:107], v[140:143], v[210:213], v[104:107]
	v_mfma_f32_16x16x32_bf16 v[92:95], v[128:131], v[218:221], v[92:95]
	v_mfma_f32_16x16x32_bf16 v[88:91], v[140:143], v[218:221], v[88:91]
	v_mfma_f32_16x16x32_bf16 v[76:79], v[128:131], v[226:229], v[76:79]
	v_mfma_f32_16x16x32_bf16 v[72:75], v[140:143], v[226:229], v[72:75]
	s_setprio 0
	s_setprio 1
	v_mfma_f32_16x16x32_bf16 v[116:119], v[144:147], v[172:175], v[116:119]
	v_mfma_f32_16x16x32_bf16 v[112:115], v[152:155], v[172:175], v[112:115]
	v_mfma_f32_16x16x32_bf16 v[100:103], v[144:147], v[206:209], v[100:103]
	v_mfma_f32_16x16x32_bf16 v[96:99], v[152:155], v[206:209], v[96:99]
	v_mfma_f32_16x16x32_bf16 v[84:87], v[144:147], v[214:217], v[84:87]
	v_mfma_f32_16x16x32_bf16 v[80:83], v[152:155], v[214:217], v[80:83]
	v_mfma_f32_16x16x32_bf16 v[68:71], v[144:147], v[222:225], v[68:71]
	v_mfma_f32_16x16x32_bf16 v[64:67], v[152:155], v[222:225], v[64:67]
	s_setprio 2
	s_barrier
	v_mfma_f32_16x16x32_bf16 v[116:119], v[148:151], v[176:179], v[116:119]
	v_mfma_f32_16x16x32_bf16 v[112:115], v[156:159], v[176:179], v[112:115]
	v_mfma_f32_16x16x32_bf16 v[100:103], v[148:151], v[210:213], v[100:103]
	v_mfma_f32_16x16x32_bf16 v[96:99], v[156:159], v[210:213], v[96:99]
	v_mfma_f32_16x16x32_bf16 v[84:87], v[148:151], v[218:221], v[84:87]
	v_mfma_f32_16x16x32_bf16 v[80:83], v[156:159], v[218:221], v[80:83]
	v_mfma_f32_16x16x32_bf16 v[68:71], v[148:151], v[226:229], v[68:71]
	v_mfma_f32_16x16x32_bf16 v[64:67], v[156:159], v[226:229], v[64:67]
	s_setprio 0
	s_add_i32 s21, s21, s31
	v_lshl_add_u64 v[180:181], s[6:7], 0, v[160:161]
	s_mov_b32 m0, s21
	ds_read_b128 v[172:175], v204 offset:16384
	ds_read_b128 v[176:179], v204 offset:17408
	ds_read_b128 v[206:209], v204 offset:18432
	ds_read_b128 v[210:213], v204 offset:19456
	ds_read_b128 v[214:217], v204 offset:20480
	ds_read_b128 v[218:221], v204 offset:21504
	ds_read_b128 v[222:225], v204 offset:22528
	ds_read_b128 v[226:229], v204 offset:23552
	global_load_lds_dwordx4 v[180:181], off
	s_add_i32 m0, s21, 0x2000
	s_add_u32 s92, s6, 0x40000
	v_lshl_add_u64 v[230:231], s[6:7], 0, v[162:163]
	s_addc_u32 s93, s7, 0
	s_add_i32 s21, s26, s31
	global_load_lds_dwordx4 v[230:231], off
	v_lshl_add_u64 v[232:233], s[92:93], 0, v[160:161]
	s_mov_b32 m0, s21
	v_lshl_add_u64 v[234:235], s[8:9], 0, v[164:165]
	global_load_lds_dwordx4 v[232:233], off
	v_lshl_add_u64 v[232:233], s[92:93], 0, v[162:163]
	s_add_i32 m0, s21, 0x2000
	s_nop 0
	global_load_lds_dwordx4 v[232:233], off
	v_lshl_add_u64 v[232:233], s[8:9], 0, v[166:167]
	s_mov_b32 m0, s66
	s_nop 0
	global_load_lds_dwordx4 v[232:233], off
	s_mov_b32 m0, s67
	s_nop 0
	global_load_lds_dwordx4 v[234:235], off
	s_waitcnt vmcnt(8)
	s_waitcnt lgkmcnt(0)
	s_barrier
; #define PG8_STAGE(bufoff, gbase, voff) do { _Pragma("unroll") for (int _i = 0; _i < 2; ++_i) \
;         __builtin_amdgcn_global_load_lds((const unsigned*)((const char*)(gbase) + (voff)[_i]), (PG8_LAS unsigned*)(lds + (bufoff) + ldsw + _i * 8192), 16, 0, 0); } while (0)
; #define PG8_LDA(dst, b, h) do { _Pragma("unroll") for (int m = 0; m < 4; ++m) _Pragma("unroll") for (int k = 0; k < 2; ++k) dst[m][k] = *(const PG8_LAS bf16x8*)(lds + PG8_SA(b, h) + aoff + m * 2048 + k * 1024); } while (0)
; #define PG8_LDB(dst, b, h) do { _Pragma("unroll") for (int n = 0; n < 2; ++n) _Pragma("unroll") for (int k = 0; k < 2; ++k) dst[n][k] = *(const PG8_LAS bf16x8*)(lds + PG8_SB(b, h) + boff + n * 2048 + k * 1024); } while (0)
; #define PG8_MMA(ai, bj, At, Bt) do { __builtin_amdgcn_s_setprio(1); _Pragma("unroll") for (int m = 0; m < 4; ++m) _Pragma("unroll") for (int n = 0; n < 2; ++n) _Pragma("unroll") for (int k = 0; k < 2; ++k) \
;         acc[ai][bj][m][n] = __builtin_amdgcn_mfma_f32_16x16x32_bf16(Bt[n][k], At[m][k], acc[ai][bj][m][n], 0, 0, 0); __builtin_amdgcn_s_setprio(0); } while (0)
; #define PG8_WAIT_V(n) asm volatile("s_waitcnt vmcnt(" #n ")" ::: "memory")
; #define PG8_WAIT_L(n) asm volatile("s_waitcnt lgkmcnt(" #n ")" ::: "memory")
; #define PG8_BAR __builtin_amdgcn_s_barrier()
; #define PG8_SCHED __builtin_amdgcn_sched_barrier(0)
; template <class Epi, class Sched, bool ALIGN_EPI = false, bool SP2 = false>
; __device__ __forceinline__ void gemm_phase(PG8_LAS unsigned char* lds, const Gemm g, const Sched& S, const Epi& E, int wv) {
;     ...
;             PG8_WAIT_V(8); PG8_WAIT_L(0); PG8_BAR; PG8_MMA(1, 0, At, B0); PG8_MMA(1, 1, At, B1); PG8_BAR; PG8_SCHED;
;             PG8_LDB(B0, 1, 0); PG8_LDB(B1, 1, 1); PG8_SCHED; PG8_LDA(At, 1, 0); PG8_STAGE(PG8_SA(0, 1), a2 + hstep, voffA);
;             PG8_WAIT_V(8); PG8_WAIT_L(0); PG8_BAR; PG8_MMA(0, 0, At, B0); PG8_MMA(0, 1, At, B1); PG8_BAR; PG8_SCHED;
	s_setprio 1
	s_waitcnt lgkmcnt(0)
	v_mfma_f32_16x16x32_bf16 v[60:63], v[124:127], v[172:175], v[60:63]
	v_mfma_f32_16x16x32_bf16 v[56:59], v[136:139], v[172:175], v[56:59]
	v_mfma_f32_16x16x32_bf16 v[44:47], v[124:127], v[206:209], v[44:47]
	v_mfma_f32_16x16x32_bf16 v[40:43], v[136:139], v[206:209], v[40:43]
	v_mfma_f32_16x16x32_bf16 v[28:31], v[124:127], v[214:217], v[28:31]
	v_mfma_f32_16x16x32_bf16 v[24:27], v[136:139], v[214:217], v[24:27]
	v_mfma_f32_16x16x32_bf16 v[12:15], v[124:127], v[222:225], v[12:15]
	v_mfma_f32_16x16x32_bf16 v[8:11], v[136:139], v[222:225], v[8:11]
	v_mfma_f32_16x16x32_bf16 v[60:63], v[128:131], v[176:179], v[60:63]
	v_mfma_f32_16x16x32_bf16 v[56:59], v[140:143], v[176:179], v[56:59]
	v_mfma_f32_16x16x32_bf16 v[44:47], v[128:131], v[210:213], v[44:47]
	v_mfma_f32_16x16x32_bf16 v[40:43], v[140:143], v[210:213], v[40:43]
	v_mfma_f32_16x16x32_bf16 v[28:31], v[128:131], v[218:221], v[28:31]
	v_mfma_f32_16x16x32_bf16 v[24:27], v[140:143], v[218:221], v[24:27]
	v_mfma_f32_16x16x32_bf16 v[12:15], v[128:131], v[226:229], v[12:15]
	v_mfma_f32_16x16x32_bf16 v[8:11], v[140:143], v[226:229], v[8:11]
	s_setprio 0
	s_setprio 1
	v_mfma_f32_16x16x32_bf16 v[52:55], v[144:147], v[172:175], v[52:55]
	v_mfma_f32_16x16x32_bf16 v[48:51], v[152:155], v[172:175], v[48:51]
	v_mfma_f32_16x16x32_bf16 v[36:39], v[144:147], v[206:209], v[36:39]
	v_mfma_f32_16x16x32_bf16 v[32:35], v[152:155], v[206:209], v[32:35]
	v_mfma_f32_16x16x32_bf16 v[20:23], v[144:147], v[214:217], v[20:23]
	v_mfma_f32_16x16x32_bf16 v[16:19], v[152:155], v[214:217], v[16:19]
	v_mfma_f32_16x16x32_bf16 v[4:7], v[144:147], v[222:225], v[4:7]
	v_mfma_f32_16x16x32_bf16 v[0:3], v[152:155], v[222:225], v[0:3]
	s_setprio 2
	s_barrier
	v_mfma_f32_16x16x32_bf16 v[52:55], v[148:151], v[176:179], v[52:55]
	v_mfma_f32_16x16x32_bf16 v[48:51], v[156:159], v[176:179], v[48:51]
	v_mfma_f32_16x16x32_bf16 v[36:39], v[148:151], v[210:213], v[36:39]
	v_mfma_f32_16x16x32_bf16 v[32:35], v[156:159], v[210:213], v[32:35]
	v_mfma_f32_16x16x32_bf16 v[20:23], v[148:151], v[218:221], v[20:23]
	v_mfma_f32_16x16x32_bf16 v[16:19], v[156:159], v[218:221], v[16:19]
	v_mfma_f32_16x16x32_bf16 v[4:7], v[148:151], v[226:229], v[4:7]
	v_mfma_f32_16x16x32_bf16 v[0:3], v[156:159], v[226:229], v[0:3]
	s_setprio 0
	s_add_i32 s21, 0, 0x18000
	s_add_i32 s26, 0, 0x1c000
	v_add_u32_e32 v140, s21, v203
	v_add_u32_e32 v156, s26, v203
	ds_read_b128 v[124:127], v140
	ds_read_b128 v[128:131], v140 offset:1024
	ds_read_b128 v[136:139], v140 offset:2048
	ds_read_b128 v[140:143], v140 offset:3072
	ds_read_b128 v[144:147], v156
	ds_read_b128 v[148:151], v156 offset:1024
	ds_read_b128 v[152:155], v156 offset:2048
	ds_read_b128 v[156:159], v156 offset:3072
	s_add_u32 s8, s8, 0x40000
	s_addc_u32 s9, s9, 0
	s_mov_b32 m0, s76
	v_lshl_add_u64 v[236:237], s[8:9], 0, v[166:167]
	ds_read_b128 v[172:175], v204 offset:32768
	ds_read_b128 v[176:179], v204 offset:33792
	ds_read_b128 v[206:209], v204 offset:34816
	ds_read_b128 v[210:213], v204 offset:35840
	ds_read_b128 v[214:217], v204 offset:36864
	ds_read_b128 v[218:221], v204 offset:37888
	ds_read_b128 v[222:225], v204 offset:38912
	ds_read_b128 v[226:229], v204 offset:39936
	global_load_lds_dwordx4 v[236:237], off
	v_lshl_add_u64 v[236:237], s[8:9], 0, v[164:165]
	s_mov_b32 m0, s77
	s_nop 0
	global_load_lds_dwordx4 v[236:237], off
	s_waitcnt vmcnt(8)
	s_waitcnt lgkmcnt(0)
	s_barrier
	s_setprio 1
	s_waitcnt lgkmcnt(0)
	v_mfma_f32_16x16x32_bf16 v[132:135], v[124:127], v[172:175], v[132:135]
	v_mfma_f32_16x16x32_bf16 v[120:123], v[136:139], v[172:175], v[120:123]
	v_mfma_f32_16x16x32_bf16 v[108:111], v[124:127], v[206:209], v[108:111]
	v_mfma_f32_16x16x32_bf16 v[104:107], v[136:139], v[206:209], v[104:107]
	v_mfma_f32_16x16x32_bf16 v[92:95], v[124:127], v[214:217], v[92:95]
	v_mfma_f32_16x16x32_bf16 v[88:91], v[136:139], v[214:217], v[88:91]
	v_mfma_f32_16x16x32_bf16 v[76:79], v[124:127], v[222:225], v[76:79]
	v_mfma_f32_16x16x32_bf16 v[72:75], v[136:139], v[222:225], v[72:75]
	v_mfma_f32_16x16x32_bf16 v[132:135], v[128:131], v[176:179], v[132:135]
	v_mfma_f32_16x16x32_bf16 v[120:123], v[140:143], v[176:179], v[120:123]
	v_mfma_f32_16x16x32_bf16 v[108:111], v[128:131], v[210:213], v[108:111]
	v_mfma_f32_16x16x32_bf16 v[104:107], v[140:143], v[210:213], v[104:107]
	v_mfma_f32_16x16x32_bf16 v[92:95], v[128:131], v[218:221], v[92:95]
	v_mfma_f32_16x16x32_bf16 v[88:91], v[140:143], v[218:221], v[88:91]
	v_mfma_f32_16x16x32_bf16 v[76:79], v[128:131], v[226:229], v[76:79]
	v_mfma_f32_16x16x32_bf16 v[72:75], v[140:143], v[226:229], v[72:75]
	s_setprio 0
	s_setprio 1
	v_mfma_f32_16x16x32_bf16 v[116:119], v[144:147], v[172:175], v[116:119]
	v_mfma_f32_16x16x32_bf16 v[112:115], v[152:155], v[172:175], v[112:115]
	v_mfma_f32_16x16x32_bf16 v[100:103], v[144:147], v[206:209], v[100:103]
	v_mfma_f32_16x16x32_bf16 v[96:99], v[152:155], v[206:209], v[96:99]
	v_mfma_f32_16x16x32_bf16 v[84:87], v[144:147], v[214:217], v[84:87]
	v_mfma_f32_16x16x32_bf16 v[80:83], v[152:155], v[214:217], v[80:83]
	v_mfma_f32_16x16x32_bf16 v[68:71], v[144:147], v[222:225], v[68:71]
	v_mfma_f32_16x16x32_bf16 v[64:67], v[152:155], v[222:225], v[64:67]
	s_setprio 2
	s_barrier
; #define PG8_STAGE(bufoff, gbase, voff) do { _Pragma("unroll") for (int _i = 0; _i < 2; ++_i) \
;         __builtin_amdgcn_global_load_lds((const unsigned*)((const char*)(gbase) + (voff)[_i]), (PG8_LAS unsigned*)(lds + (bufoff) + ldsw + _i * 8192), 16, 0, 0); } while (0)
; #define PG8_LDA(dst, b, h) do { _Pragma("unroll") for (int m = 0; m < 4; ++m) _Pragma("unroll") for (int k = 0; k < 2; ++k) dst[m][k] = *(const PG8_LAS bf16x8*)(lds + PG8_SA(b, h) + aoff + m * 2048 + k * 1024); } while (0)
; #define PG8_MMA(ai, bj, At, Bt) do { __builtin_amdgcn_s_setprio(1); _Pragma("unroll") for (int m = 0; m < 4; ++m) _Pragma("unroll") for (int n = 0; n < 2; ++n) _Pragma("unroll") for (int k = 0; k < 2; ++k) \
;         acc[ai][bj][m][n] = __builtin_amdgcn_mfma_f32_16x16x32_bf16(Bt[n][k], At[m][k], acc[ai][bj][m][n], 0, 0, 0); __builtin_amdgcn_s_setprio(0); } while (0)
; #define PG8_WAIT_V(n) asm volatile("s_waitcnt vmcnt(" #n ")" ::: "memory")
; #define PG8_WAIT_L(n) asm volatile("s_waitcnt lgkmcnt(" #n ")" ::: "memory")
; #define PG8_BAR __builtin_amdgcn_s_barrier()
; #define PG8_SCHED __builtin_amdgcn_sched_barrier(0)
; template <class Epi, class Sched, bool ALIGN_EPI = false, bool SP2 = false>
; __device__ __forceinline__ void gemm_phase(PG8_LAS unsigned char* lds, const Gemm g, const Sched& S, const Epi& E, int wv) {
;     ...
;         for (int t = 0; t < nt; t += 2) {
;     ...
;             PG8_WAIT_V(8); PG8_WAIT_L(0); PG8_BAR; PG8_MMA(0, 0, At, B0); PG8_MMA(0, 1, At, B1); PG8_BAR; PG8_SCHED;
;             PG8_LDA(At, 1, 1); PG8_STAGE(PG8_SB(1, 0), b3, voffB); PG8_STAGE(PG8_SB(1, 1), b3 + hstep, voffB); PG8_STAGE(PG8_SA(1, 0), a3, voffA);
;             PG8_WAIT_V(8); PG8_WAIT_L(0); PG8_BAR; PG8_MMA(1, 0, At, B0); PG8_MMA(1, 1, At, B1); PG8_BAR; PG8_SCHED;
	v_mfma_f32_16x16x32_bf16 v[116:119], v[148:151], v[176:179], v[116:119]
	v_mfma_f32_16x16x32_bf16 v[112:115], v[156:159], v[176:179], v[112:115]
	v_mfma_f32_16x16x32_bf16 v[100:103], v[148:151], v[210:213], v[100:103]
	v_mfma_f32_16x16x32_bf16 v[96:99], v[156:159], v[210:213], v[96:99]
	v_mfma_f32_16x16x32_bf16 v[84:87], v[148:151], v[218:221], v[84:87]
	v_mfma_f32_16x16x32_bf16 v[80:83], v[156:159], v[218:221], v[80:83]
	v_mfma_f32_16x16x32_bf16 v[68:71], v[148:151], v[226:229], v[68:71]
	v_mfma_f32_16x16x32_bf16 v[64:67], v[156:159], v[226:229], v[64:67]
	s_setprio 0
	s_add_i32 s8, s21, s31
	v_lshl_add_u64 v[180:181], v[180:181], 0, s[74:75]
	s_mov_b32 m0, s8
	ds_read_b128 v[172:175], v204 offset:49152
	ds_read_b128 v[176:179], v204 offset:50176
	ds_read_b128 v[206:209], v204 offset:51200
	ds_read_b128 v[210:213], v204 offset:52224
	ds_read_b128 v[214:217], v204 offset:53248
	ds_read_b128 v[218:221], v204 offset:54272
	ds_read_b128 v[222:225], v204 offset:55296
	ds_read_b128 v[226:229], v204 offset:56320
	global_load_lds_dwordx4 v[180:181], off
	s_add_i32 m0, s8, 0x2000
	s_add_u32 s6, s6, 0x40080
	v_lshl_add_u64 v[180:181], v[230:231], 0, s[74:75]
	s_addc_u32 s7, s7, 0
	s_add_i32 s8, s26, s31
	global_load_lds_dwordx4 v[180:181], off
	v_lshl_add_u64 v[180:181], s[6:7], 0, v[160:161]
	s_mov_b32 m0, s8
	s_nop 0
	global_load_lds_dwordx4 v[180:181], off
	v_lshl_add_u64 v[180:181], s[6:7], 0, v[162:163]
	s_add_i32 m0, s8, 0x2000
	s_nop 0
	global_load_lds_dwordx4 v[180:181], off
	v_lshl_add_u64 v[180:181], v[232:233], 0, s[74:75]
	s_mov_b32 m0, s95
	s_nop 0
	global_load_lds_dwordx4 v[180:181], off
	v_lshl_add_u64 v[180:181], v[234:235], 0, s[74:75]
	s_mov_b32 m0, s54
	s_nop 0
	global_load_lds_dwordx4 v[180:181], off
	s_waitcnt vmcnt(8)
	s_waitcnt lgkmcnt(0)
	s_barrier
	s_setprio 1
	s_waitcnt lgkmcnt(0)
	v_mfma_f32_16x16x32_bf16 v[60:63], v[124:127], v[172:175], v[60:63]
	v_mfma_f32_16x16x32_bf16 v[56:59], v[136:139], v[172:175], v[56:59]
	v_mfma_f32_16x16x32_bf16 v[44:47], v[124:127], v[206:209], v[44:47]
	v_mfma_f32_16x16x32_bf16 v[40:43], v[136:139], v[206:209], v[40:43]
	v_mfma_f32_16x16x32_bf16 v[28:31], v[124:127], v[214:217], v[28:31]
	v_mfma_f32_16x16x32_bf16 v[24:27], v[136:139], v[214:217], v[24:27]
	v_mfma_f32_16x16x32_bf16 v[12:15], v[124:127], v[222:225], v[12:15]
	v_mfma_f32_16x16x32_bf16 v[8:11], v[136:139], v[222:225], v[8:11]
	v_mfma_f32_16x16x32_bf16 v[60:63], v[128:131], v[176:179], v[60:63]
	v_mfma_f32_16x16x32_bf16 v[56:59], v[140:143], v[176:179], v[56:59]
	v_mfma_f32_16x16x32_bf16 v[44:47], v[128:131], v[210:213], v[44:47]
	v_mfma_f32_16x16x32_bf16 v[40:43], v[140:143], v[210:213], v[40:43]
	v_mfma_f32_16x16x32_bf16 v[28:31], v[128:131], v[218:221], v[28:31]
	v_mfma_f32_16x16x32_bf16 v[24:27], v[140:143], v[218:221], v[24:27]
	v_mfma_f32_16x16x32_bf16 v[12:15], v[128:131], v[226:229], v[12:15]
	v_mfma_f32_16x16x32_bf16 v[8:11], v[140:143], v[226:229], v[8:11]
	s_setprio 0
	s_setprio 1
	v_mfma_f32_16x16x32_bf16 v[52:55], v[144:147], v[172:175], v[52:55]
	v_mfma_f32_16x16x32_bf16 v[48:51], v[152:155], v[172:175], v[48:51]
	v_mfma_f32_16x16x32_bf16 v[36:39], v[144:147], v[206:209], v[36:39]
	v_mfma_f32_16x16x32_bf16 v[32:35], v[152:155], v[206:209], v[32:35]
	v_mfma_f32_16x16x32_bf16 v[20:23], v[144:147], v[214:217], v[20:23]
	v_mfma_f32_16x16x32_bf16 v[16:19], v[152:155], v[214:217], v[16:19]
	v_mfma_f32_16x16x32_bf16 v[4:7], v[144:147], v[222:225], v[4:7]
	v_mfma_f32_16x16x32_bf16 v[0:3], v[152:155], v[222:225], v[0:3]
	s_setprio 2
	s_barrier
	v_mfma_f32_16x16x32_bf16 v[52:55], v[148:151], v[176:179], v[52:55]
	v_mfma_f32_16x16x32_bf16 v[48:51], v[156:159], v[176:179], v[48:51]
	v_mfma_f32_16x16x32_bf16 v[36:39], v[148:151], v[210:213], v[36:39]
	v_mfma_f32_16x16x32_bf16 v[32:35], v[156:159], v[210:213], v[32:35]
	v_mfma_f32_16x16x32_bf16 v[20:23], v[148:151], v[218:221], v[20:23]
	v_mfma_f32_16x16x32_bf16 v[16:19], v[156:159], v[218:221], v[16:19]
	v_mfma_f32_16x16x32_bf16 v[4:7], v[148:151], v[226:229], v[4:7]
	v_mfma_f32_16x16x32_bf16 v[0:3], v[156:159], v[226:229], v[0:3]
	s_setprio 0
	s_add_i32 vcc_hi, vcc_hi, 2
	s_add_u32 s4, s4, 0x100
	s_addc_u32 s5, s5, 0
	s_add_u32 s91, s91, 0x100
	s_addc_u32 vcc_lo, vcc_lo, 0
	s_cmp_gt_u32 vcc_hi, 13
	s_cbranch_scc0 .LBB0_2281
	s_and_b64 vcc, exec, s[44:45]
	s_cbranch_vccz .LBB0_2284
	s_barrier
